# v6: remaining in-place bf16 bit-trick packs (phase2, mixer, GLA) -> v_cvt_pk_bf16_f32 via scratch reg
# baseline (speedup 1.0000x reference)
; __device__ __forceinline__ unsigned pk2(float lo, float hi) { return f2bf(lo) | (f2bf(hi) << 16); }
; __device__ __forceinline__ void phase_prologue(const Params& P, LAS unsigned char* lds) {
;     ...
;     for (int i = blockIdx.x * 512 + tid; i < 8 * 128 * 128 / 4; i += G * 512) {
;         const int e = 4 * i, t = (e >> 7) & 127, s = e & 127; const f32x4 v = *(const f32x4*)(P.w_spatial + e);
;         u32x2 o; o.x = pk2(s <= t ? v[0] : 0.f, s + 1 <= t ? v[1] : 0.f); o.y = pk2(s + 2 <= t ? v[2] : 0.f, s + 3 <= t ? v[3] : 0.f);
;         *(u32x2*)(WsT + e) = o;
;     }
.LBB0_96:
	v_ashrrev_i32_e32 v1, 31, v0
	v_lshl_add_u64 v[4:5], v[0:1], 2, s[50:51]
	global_load_dwordx4 v[4:7], v[4:5], off
	v_bfe_u32 v3, v2, 5, 7
	s_waitcnt vmcnt(36)
	v_and_b32_e32 v10, 0x7c, v0
	v_add_u32_e32 v2, s3, v2
	s_waitcnt vmcnt(35)
	v_or_b32_e32 v11, 2, v10
	v_cmp_lt_i32_e32 vcc, s17, v2
	v_or_b32_e32 v12, 3, v10
	v_cmp_le_u32_e64 s[6:7], v11, v3
	s_or_b64 s[14:15], vcc, s[14:15]
	v_cmp_le_u32_e32 vcc, v10, v3
	v_lshl_add_u64 v[8:9], v[0:1], 1, s[12:13]
	v_cmp_lt_u32_e64 s[4:5], v10, v3
	v_cmp_le_u32_e64 s[8:9], v12, v3
	v_add_u32_e32 v0, s16, v0
	s_waitcnt vmcnt(0)
	v_cndmask_b32_e32 v1, 0, v4, vcc
	v_cndmask_b32_e64 v4, 0, v6, s[6:7]
	v_cndmask_b32_e64 v3, 0, v5, s[4:5]
	v_cndmask_b32_e64 v5, 0, v7, s[8:9]
	v_bfe_u32 v7, v3, 16, 1
	v_cvt_pk_bf16_f32 v210, v1, v3
	v_cvt_pk_bf16_f32 v212, v4, v5
	v_add3_u32 v3, v3, v7, s17
	v_mov_b32_e32 v4, v210
	v_mov_b32_e32 v5, v212
	global_store_dwordx2 v[8:9], v[4:5], off
	s_andn2_b64 exec, exec, s[14:15]
	s_cbranch_execnz .LBB0_96

; __device__ __forceinline__ unsigned pk2(float lo, float hi) { return f2bf(lo) | (f2bf(hi) << 16); }
; __device__ __forceinline__ void phase_gla_pre(const Params& P, LAS unsigned char* lds, bool dry) {
;     ...
;             const int t = 16 * tt + fr, sb = 16 * st + 4 * g;
;             u32x2 o; o.x = pk2(sb <= t ? acc[0] : 0.f, sb + 1 <= t ? acc[1] : 0.f); o.y = pk2(sb + 2 <= t ? acc[2] : 0.f, sb + 3 <= t ? acc[3] : 0.f);
;             if (!dry) *(u32x2*)(PB + (size_t)item * 4096 + t * 64 + sb) = o;
;         }
;         __syncthreads();
.LBB0_479:
	s_or_b64 exec, exec, s[42:43]
	s_nop 5
	v_cndmask_b32_e64 v20, v20, 0, s[26:27]
	v_cndmask_b32_e64 v21, 0, v21, s[28:29]
	v_cvt_pk_bf16_f32 v136, v20, v21
	v_mov_b32_e32 v20, v136
	v_cndmask_b32_e64 v21, v22, 0, s[30:31]
	v_bfe_u32 v22, v21, 16, 1
	v_add3_u32 v21, v21, v22, s86
	v_cndmask_b32_e64 v22, v23, 0, s[34:35]
	v_bfe_u32 v23, v22, 16, 1
	v_lshrrev_b32_e32 v21, 16, v21
	v_add3_u32 v22, v22, v23, s86
	v_and_or_b32 v21, v22, s87, v21
	s_add_i32 s1, s1, s3
	s_add_i32 s84, s84, s85
	s_andn2_b64 vcc, exec, s[36:37]
	s_mov_b32 s80, s82
	global_store_dwordx2 v[24:25], v[20:21], off offset:32
	s_barrier
	s_cbranch_vccz .LBB0_502

; __device__ __forceinline__ float bf2f(unsigned b) { return __uint_as_float(b << 16); }
; __device__ __forceinline__ unsigned f2bf(float f) { unsigned u = __float_as_uint(f); return (u + 0x7fffu + ((u >> 16) & 1u)) >> 16; }
; __device__ __forceinline__ void split8(const f32x4 x0, const f32x4 x1, bf16x8& hi, bf16x8& lo) {
; #pragma unroll
;     for (int j = 0; j < 8; ++j) { const float x = j < 4 ? x0[j & 3] : x1[j & 3]; const unsigned h = f2bf(x); const unsigned l = f2bf(x - bf2f(h)); hi[j] = (short)h; lo[j] = (short)l; }
; }
; __device__ __forceinline__ void phase_gla_pre(const Params& P, LAS unsigned char* lds, bool dry) {
;     ...
;         if (g < 2) { f32x4 w0, w1;
; #pragma unroll
;             for (int j = 0; j < 4; ++j) { w0[j] = P.w_gate_up[(8 * g + j) * 512 + h * 128 + 16 * w + fr]; w1[j] = P.w_gate_up[(8 * g + 4 + j) * 512 + h * 128 + 16 * w + fr]; }
;             split8(w0, w1, bhi, blo); }
.Lp2_nopf:
	s_ashr_i32 s82, s80, 6
	s_lshl_b32 s36, s82, 7
	s_and_b32 s42, s36, 0x180
	v_mov_b32_e32 v32, 0
	v_mov_b32_e32 v24, 0
	v_mov_b32_e32 v25, 0
	v_mov_b32_e32 v26, 0
	v_mov_b32_e32 v27, 0
	v_mov_b32_e32 v20, 0
	v_mov_b32_e32 v21, 0
	v_mov_b32_e32 v22, 0
	v_mov_b32_e32 v23, 0
	s_cmp_lg_u32 s98, 0
	s_cbranch_scc1 .Lp2_hoisted
	s_and_saveexec_b64 s[36:37], s[6:7]
	s_cbranch_execz .LBB0_484
	v_or_b32_e32 v28, s42, v80
	v_or_b32_e32 v26, 0x400, v28
	v_add_u32_e32 v20, v28, v81
	v_add_u32_e32 v24, v26, v81
	v_add_u32_e32 v26, v26, v82
	v_or_b32_e32 v30, 0x600, v28
	v_ashrrev_i32_e32 v21, 31, v20
	v_add_u32_e32 v22, v28, v82
	v_ashrrev_i32_e32 v25, 31, v24
	v_ashrrev_i32_e32 v27, 31, v26
	v_add_u32_e32 v28, v30, v81
	v_add_u32_e32 v30, v30, v82
	v_lshl_add_u64 v[20:21], v[20:21], 2, s[54:55]
	v_ashrrev_i32_e32 v23, 31, v22
	v_lshl_add_u64 v[24:25], v[24:25], 2, s[54:55]
	v_lshl_add_u64 v[26:27], v[26:27], 2, s[54:55]
	v_ashrrev_i32_e32 v29, 31, v28
	v_ashrrev_i32_e32 v31, 31, v30
	v_lshl_add_u64 v[22:23], v[22:23], 2, s[54:55]
	v_lshl_add_u64 v[28:29], v[28:29], 2, s[54:55]
	v_lshl_add_u64 v[30:31], v[30:31], 2, s[54:55]
	global_load_dword v34, v[20:21], off
	global_load_dword v36, v[22:23], off
	global_load_dword v37, v[22:23], off offset:2048
	s_nop 0
	global_load_dword v24, v[24:25], off
	s_nop 0
	global_load_dword v26, v[26:27], off
	s_nop 0
	global_load_dword v25, v[28:29], off
	global_load_dword v27, v[30:31], off
	global_load_dword v35, v[20:21], off offset:2048
	s_waitcnt vmcnt(7)
	v_and_b32_sdwa v20, v34, v95 dst_sel:DWORD dst_unused:UNUSED_PAD src0_sel:WORD_1 src1_sel:DWORD
	s_waitcnt vmcnt(6)
	v_and_b32_sdwa v22, v36, v95 dst_sel:DWORD dst_unused:UNUSED_PAD src0_sel:WORD_1 src1_sel:DWORD
	s_waitcnt vmcnt(5)
	v_and_b32_sdwa v21, v37, v95 dst_sel:DWORD dst_unused:UNUSED_PAD src0_sel:WORD_1 src1_sel:DWORD
	v_add3_u32 v33, v34, v20, s86
	s_waitcnt vmcnt(4)
	v_and_b32_sdwa v29, v24, v95 dst_sel:DWORD dst_unused:UNUSED_PAD src0_sel:WORD_1 src1_sel:DWORD
	s_waitcnt vmcnt(2)
	v_and_b32_sdwa v20, v25, v95 dst_sel:DWORD dst_unused:UNUSED_PAD src0_sel:WORD_1 src1_sel:DWORD
	s_waitcnt vmcnt(1)
	v_and_b32_sdwa v31, v27, v95 dst_sel:DWORD dst_unused:UNUSED_PAD src0_sel:WORD_1 src1_sel:DWORD
	s_waitcnt vmcnt(0)
	v_and_b32_sdwa v23, v35, v95 dst_sel:DWORD dst_unused:UNUSED_PAD src0_sel:WORD_1 src1_sel:DWORD
	v_and_b32_sdwa v38, v26, v95 dst_sel:DWORD dst_unused:UNUSED_PAD src0_sel:WORD_1 src1_sel:DWORD
	v_add3_u32 v30, v37, v21, s86
	v_add3_u32 v22, v36, v22, s86
	v_add3_u32 v23, v35, v23, s86
	v_add3_u32 v40, v25, v20, s86
	v_add3_u32 v41, v24, v29, s86
	v_add3_u32 v42, v27, v31, s86
	v_add3_u32 v43, v26, v38, s86
	v_and_b32_e32 v28, 0xffff0000, v33
	v_and_b32_e32 v21, 0xffff0000, v30
	v_and_b32_e32 v20, 0xffff0000, v22
	v_cvt_pk_bf16_f32 v22, v36, v37
	v_and_b32_e32 v29, 0xffff0000, v23
	v_and_b32_e32 v31, 0xffff0000, v40
	v_and_b32_e32 v30, 0xffff0000, v41
	v_and_b32_e32 v39, 0xffff0000, v42
	v_and_b32_e32 v38, 0xffff0000, v43
	v_pk_add_f32 v[36:37], v[36:37], v[20:21] neg_lo:[0,1] neg_hi:[0,1]
	v_pk_add_f32 v[28:29], v[34:35], v[28:29] neg_lo:[0,1] neg_hi:[0,1]
	v_cvt_pk_bf16_f32 v137, v24, v25
	v_pk_add_f32 v[24:25], v[24:25], v[30:31] neg_lo:[0,1] neg_hi:[0,1]
	v_cvt_pk_bf16_f32 v181, v26, v27
	v_pk_add_f32 v[26:27], v[26:27], v[38:39] neg_lo:[0,1] neg_hi:[0,1]
	v_cvt_pk_bf16_f32 v20, v34, v35
	v_cvt_pk_bf16_f32 v138, v36, v37
	v_cvt_pk_bf16_f32 v180, v26, v27
	v_cvt_pk_bf16_f32 v149, v24, v25
	v_cvt_pk_bf16_f32 v139, v28, v29
	v_mov_b32_e32 v21, v137
	v_mov_b32_e32 v26, v138
	v_mov_b32_e32 v24, v139
	v_mov_b32_e32 v25, v149
	v_mov_b32_e32 v27, v180
	v_mov_b32_e32 v23, v181

; #define LAS __attribute__((address_space(3)))
; __device__ __forceinline__ float bf2f(unsigned b) { return __uint_as_float(b << 16); }
; __device__ __forceinline__ unsigned f2bf(float f) { unsigned u = __float_as_uint(f); return (u + 0x7fffu + ((u >> 16) & 1u)) >> 16; }
; __device__ __forceinline__ void split8(const f32x4 x0, const f32x4 x1, bf16x8& hi, bf16x8& lo) {
; #pragma unroll
;     for (int j = 0; j < 8; ++j) { const float x = j < 4 ? x0[j & 3] : x1[j & 3]; const unsigned h = f2bf(x); const unsigned l = f2bf(x - bf2f(h)); hi[j] = (short)h; lo[j] = (short)l; }
; }
; __device__ __forceinline__ void phase_gla_pre(const Params& P, LAS unsigned char* lds, bool dry) {
;     ...
;         for (int tt = 0; tt < 4; ++tt) {
;             bf16x8 ahi = (bf16x8){0, 0, 0, 0, 0, 0, 0, 0}, alo = ahi;
;             if (g < 2) { const f32x4 l0 = *(const LAS f32x4*)(Llr + (16 * tt + fr) * 16 + 8 * g), l1 = *(const LAS f32x4*)(Llr + (16 * tt + fr) * 16 + 8 * g + 4); split8(l0, l1, ahi, alo); }
.Lp2_join:
	v_mov_b32_e32 v33, 0
	v_mov_b32_e32 v34, 0
	v_mov_b32_e32 v35, 0
	v_mov_b32_e32 v36, 0
	v_mov_b32_e32 v37, 0
	v_mov_b32_e32 v38, 0
	v_mov_b32_e32 v39, 0
	s_waitcnt lgkmcnt(0)
	s_barrier
	s_and_saveexec_b64 s[36:37], s[6:7]
	s_cbranch_execz .LBB0_486
	ds_read_b128 v[30:33], v96
	ds_read_b128 v[34:37], v96 offset:16
	s_waitcnt lgkmcnt(1)
	v_and_b32_sdwa v29, v31, v95 dst_sel:DWORD dst_unused:UNUSED_PAD src0_sel:WORD_1 src1_sel:DWORD
	v_and_b32_sdwa v38, v30, v95 dst_sel:DWORD dst_unused:UNUSED_PAD src0_sel:WORD_1 src1_sel:DWORD
	v_add3_u32 v29, v31, v29, s86
	v_add3_u32 v40, v30, v38, s86
	v_and_b32_e32 v39, 0xffff0000, v29
	v_and_b32_e32 v38, 0xffff0000, v40
	v_cvt_pk_bf16_f32 v186, v30, v31
	v_pk_add_f32 v[30:31], v[30:31], v[38:39] neg_lo:[0,1] neg_hi:[0,1]
	v_and_b32_sdwa v38, v33, v95 dst_sel:DWORD dst_unused:UNUSED_PAD src0_sel:WORD_1 src1_sel:DWORD
	v_and_b32_sdwa v39, v32, v95 dst_sel:DWORD dst_unused:UNUSED_PAD src0_sel:WORD_1 src1_sel:DWORD
	v_add3_u32 v41, v33, v38, s86
	v_add3_u32 v42, v32, v39, s86
	v_and_b32_e32 v39, 0xffff0000, v41
	v_and_b32_e32 v38, 0xffff0000, v42
	v_cvt_pk_bf16_f32 v187, v32, v33
	v_pk_add_f32 v[32:33], v[32:33], v[38:39] neg_lo:[0,1] neg_hi:[0,1]
	s_waitcnt lgkmcnt(0)
	v_and_b32_sdwa v38, v35, v95 dst_sel:DWORD dst_unused:UNUSED_PAD src0_sel:WORD_1 src1_sel:DWORD
	v_and_b32_sdwa v39, v34, v95 dst_sel:DWORD dst_unused:UNUSED_PAD src0_sel:WORD_1 src1_sel:DWORD
	v_add3_u32 v43, v35, v38, s86
	v_add3_u32 v44, v34, v39, s86
	v_and_b32_e32 v39, 0xffff0000, v43
	v_and_b32_e32 v38, 0xffff0000, v44
	v_cvt_pk_bf16_f32 v188, v34, v35
	v_pk_add_f32 v[34:35], v[34:35], v[38:39] neg_lo:[0,1] neg_hi:[0,1]
	v_and_b32_sdwa v38, v37, v95 dst_sel:DWORD dst_unused:UNUSED_PAD src0_sel:WORD_1 src1_sel:DWORD
	v_and_b32_sdwa v39, v36, v95 dst_sel:DWORD dst_unused:UNUSED_PAD src0_sel:WORD_1 src1_sel:DWORD
	v_add3_u32 v45, v37, v38, s86
	v_add3_u32 v46, v36, v39, s86
	v_and_b32_e32 v39, 0xffff0000, v45
	v_and_b32_e32 v38, 0xffff0000, v46
	v_cvt_pk_bf16_f32 v189, v36, v37
	v_pk_add_f32 v[36:37], v[36:37], v[38:39] neg_lo:[0,1] neg_hi:[0,1]
	v_cvt_pk_bf16_f32 v185, v36, v37
	v_cvt_pk_bf16_f32 v184, v34, v35
	v_cvt_pk_bf16_f32 v183, v32, v33
	v_cvt_pk_bf16_f32 v182, v30, v31
	v_mov_b32_e32 v32, v182
	v_mov_b32_e32 v33, v183
	v_mov_b32_e32 v34, v184
	v_mov_b32_e32 v35, v185
	v_mov_b32_e32 v36, v186
	v_mov_b32_e32 v37, v187
	v_mov_b32_e32 v38, v188
	v_mov_b32_e32 v39, v189

; #define LAS __attribute__((address_space(3)))
; __device__ __forceinline__ float bf2f(unsigned b) { return __uint_as_float(b << 16); }
; __device__ __forceinline__ unsigned f2bf(float f) { unsigned u = __float_as_uint(f); return (u + 0x7fffu + ((u >> 16) & 1u)) >> 16; }
; __device__ __forceinline__ void split8(const f32x4 x0, const f32x4 x1, bf16x8& hi, bf16x8& lo) {
; #pragma unroll
;     for (int j = 0; j < 8; ++j) { const float x = j < 4 ? x0[j & 3] : x1[j & 3]; const unsigned h = f2bf(x); const unsigned l = f2bf(x - bf2f(h)); hi[j] = (short)h; lo[j] = (short)l; }
; }
; __device__ __forceinline__ void phase_gla_pre(const Params& P, LAS unsigned char* lds, bool dry) {
;     ...
;         for (int tt = 0; tt < 4; ++tt) {
;             bf16x8 ahi = (bf16x8){0, 0, 0, 0, 0, 0, 0, 0}, alo = ahi;
;             if (g < 2) { const f32x4 l0 = *(const LAS f32x4*)(Llr + (16 * tt + fr) * 16 + 8 * g), l1 = *(const LAS f32x4*)(Llr + (16 * tt + fr) * 16 + 8 * g + 4); split8(l0, l1, ahi, alo); }
;             f32x4 acc = (f32x4){bg, bg, bg, bg};
;             acc = __builtin_amdgcn_mfma_f32_16x16x32_bf16(alo, bhi, acc, 0, 0, 0); acc = __builtin_amdgcn_mfma_f32_16x16x32_bf16(ahi, blo, acc, 0, 0, 0); acc = __builtin_amdgcn_mfma_f32_16x16x32_bf16(ahi, bhi, acc, 0, 0, 0);
;             float pr[4];
; #pragma unroll
;             for (int r = 0; r < 4; ++r) { const float lg = acc[r]; const float ls = fminf(lg, 0.f) - __logf(1.0f + __expf(-fabsf(lg))); pr[r] = ls * (1.0f / 16.0f) + (r ? pr[r - 1] : 0.f); }
;             const float T = pr[3];
;             const float u1 = __shfl_up(T, 16), s1 = T + (g >= 1 ? u1 : 0.f);
;             const float u2 = __shfl_up(s1, 32), s2 = s1 + (g >= 2 ? u2 : 0.f);
;             const float base = run + (s2 - T); run += __shfl(s2, 48 + fr);
; #pragma unroll
;             for (int r = 0; r < 4; ++r) *(LAS float*)(Lb + (16 * tt + 4 * g + r) * BP + (16 * w + fr) * 4) = base + pr[r];
.Lp2_nowait1:
	v_mov_b32_e32 v140, v20
	v_mov_b32_e32 v141, v21
	v_mov_b32_e32 v142, v22
	v_mov_b32_e32 v143, v23
	v_mov_b32_e32 v144, v24
	v_mov_b32_e32 v145, v25
	v_mov_b32_e32 v146, v26
	v_mov_b32_e32 v147, v27
	v_mov_b32_e32 v148, v28
	s_and_b32 s98, s38, 0xff
	s_cselect_b32 s98, 0, 1
	v_mov_b32_e32 v29, v28
	v_mov_b32_e32 v30, v28
	v_mov_b32_e32 v31, v28
	v_mov_b32_e32 v40, 0
	v_mov_b32_e32 v41, 0
	v_mfma_f32_16x16x32_bf16 v[32:35], v[32:35], v[20:23], v[28:31]
	v_mfma_f32_16x16x32_bf16 v[32:35], v[36:39], v[24:27], v[32:35]
	v_mfma_f32_16x16x32_bf16 v[32:35], v[36:39], v[20:23], v[32:35]
	s_nop 7
	v_max_f32_e32 v36, v32, v32
	v_mul_f32_e64 v32, |v32|, s89
	v_exp_f32_e32 v32, v32
	v_mul_f32_e64 v37, |v33|, s89
	v_exp_f32_e32 v37, v37
	v_min_f32_e32 v36, 0, v36
	v_add_f32_e32 v32, 1.0, v32
	v_cmp_gt_f32_e32 vcc, s90, v32
	v_add_f32_e32 v37, 1.0, v37
	v_cmp_gt_f32_e64 s[36:37], s90, v37
	v_cndmask_b32_e64 v38, 0, 32, vcc
	v_ldexp_f32 v32, v32, v38
	v_log_f32_e32 v32, v32
	v_cndmask_b32_e64 v39, 0, 32, s[36:37]
	v_ldexp_f32 v37, v37, v39
	v_log_f32_e32 v37, v37
	v_mul_f32_e32 v39, 0x3f317217, v32
	v_fma_f32 v39, v32, s91, -v39
	v_fmac_f32_e32 v39, 0x3377d1cf, v32
	v_cndmask_b32_e32 v38, 0, v97, vcc
	v_fmac_f32_e32 v39, 0x3f317217, v32
	v_cmp_lt_f32_e64 vcc, |v32|, s92
	v_max_f32_e32 v33, v33, v33
	v_min_f32_e32 v33, 0, v33
	v_cndmask_b32_e32 v32, v32, v39, vcc
	v_sub_f32_e32 v32, v32, v38
	v_sub_f32_e32 v32, v36, v32
	v_mul_f32_e32 v36, 0x3f317217, v37
	v_fma_f32 v36, v37, s91, -v36
	v_fmac_f32_e32 v36, 0x3377d1cf, v37
	v_fmac_f32_e32 v36, 0x3f317217, v37
	v_cmp_lt_f32_e64 vcc, |v37|, s92
	v_cndmask_b32_e64 v38, 0, v97, s[36:37]
	v_fma_f32 v32, v32, s93, 0
	v_cndmask_b32_e32 v36, v37, v36, vcc
	v_mul_f32_e64 v37, |v34|, s89
	v_exp_f32_e32 v37, v37
	v_sub_f32_e32 v36, v36, v38
	v_sub_f32_e32 v33, v33, v36
	v_mov_b32_e32 v39, 0
	v_add_f32_e32 v36, 1.0, v37
	v_cmp_gt_f32_e32 vcc, s90, v36
	s_nop 1
	v_cndmask_b32_e64 v37, 0, 32, vcc
	v_ldexp_f32 v36, v36, v37
	v_log_f32_e32 v36, v36
	v_fmamk_f32 v37, v33, 0x3d800000, v32
	v_max_f32_e32 v33, v34, v34
	v_cndmask_b32_e32 v38, 0, v97, vcc
	v_mul_f32_e32 v34, 0x3f317217, v36
	v_fma_f32 v34, v36, s91, -v34
	v_fmac_f32_e32 v34, 0x3377d1cf, v36
	v_fmac_f32_e32 v34, 0x3f317217, v36
	v_cmp_lt_f32_e64 s[36:37], |v36|, s92
	v_min_f32_e32 v33, 0, v33
	s_nop 0
	v_cndmask_b32_e64 v34, v36, v34, s[36:37]
	v_mul_f32_e64 v36, |v35|, s89
	v_exp_f32_e32 v36, v36
	v_sub_f32_e32 v34, v34, v38
	v_sub_f32_e32 v33, v33, v34
	v_add_u32_e32 v38, 0x8800, v98
	v_add_f32_e32 v34, 1.0, v36
	v_cmp_gt_f32_e32 vcc, s90, v34
	s_nop 1
	v_cndmask_b32_e64 v36, 0, 32, vcc
	v_ldexp_f32 v34, v34, v36
	v_log_f32_e32 v34, v34
	v_fmamk_f32 v36, v33, 0x3d800000, v37
	v_max_f32_e32 v33, v35, v35
	v_min_f32_e32 v33, 0, v33
	v_mul_f32_e32 v35, 0x3f317217, v34
	v_fma_f32 v35, v34, s91, -v35
	v_fmac_f32_e32 v35, 0x3377d1cf, v34
	v_fmac_f32_e32 v35, 0x3f317217, v34
	v_cmp_lt_f32_e64 s[36:37], |v34|, s92
	s_nop 1
	v_cndmask_b32_e64 v34, v34, v35, s[36:37]
	v_cndmask_b32_e32 v35, 0, v97, vcc
	v_sub_f32_e32 v34, v34, v35
	v_sub_f32_e32 v33, v33, v34
	v_fmamk_f32 v34, v33, 0x3d800000, v36
	ds_bpermute_b32 v33, v83, v34
	s_waitcnt lgkmcnt(0)
	v_cndmask_b32_e64 v33, v33, 0, s[8:9]
	v_add_f32_e32 v33, v33, v34
	ds_bpermute_b32 v35, v84, v33
	s_waitcnt lgkmcnt(0)
	v_cndmask_b32_e64 v35, 0, v35, s[10:11]
	v_add_f32_e32 v33, v35, v33
	v_sub_f32_e32 v35, v33, v34
	ds_bpermute_b32 v33, v85, v33
	v_add_f32_e32 v35, 0, v35
	v_add_f32_e32 v32, v32, v35
	v_add_f32_e32 v37, v37, v35
	ds_write2_b32 v38, v32, v37 offset1:132
	v_add_f32_e32 v32, v36, v35
	v_add_f32_e32 v34, v34, v35
	v_add_u32_e32 v35, 0x8c00, v98
	ds_write2_b32 v35, v32, v34 offset0:8 offset1:140
	v_mov_b32_e32 v32, 0
	v_mov_b32_e32 v34, 0
	v_mov_b32_e32 v35, 0
	v_mov_b32_e32 v36, 0
	v_mov_b32_e32 v37, 0
	v_mov_b32_e32 v38, 0
	s_and_saveexec_b64 s[36:37], s[6:7]
	s_cbranch_execz .LBB0_488
	ds_read_b128 v[34:37], v96 offset:1024
	ds_read_b128 v[38:41], v96 offset:1040
	s_waitcnt lgkmcnt(1)
	v_and_b32_sdwa v42, v35, v95 dst_sel:DWORD dst_unused:UNUSED_PAD src0_sel:WORD_1 src1_sel:DWORD
	v_and_b32_sdwa v43, v34, v95 dst_sel:DWORD dst_unused:UNUSED_PAD src0_sel:WORD_1 src1_sel:DWORD
	v_add3_u32 v44, v35, v42, s86
	v_add3_u32 v45, v34, v43, s86
	v_and_b32_e32 v43, 0xffff0000, v44
	v_and_b32_e32 v42, 0xffff0000, v45
	v_cvt_pk_bf16_f32 v196, v34, v35
	v_pk_add_f32 v[34:35], v[34:35], v[42:43] neg_lo:[0,1] neg_hi:[0,1]
	v_and_b32_sdwa v42, v37, v95 dst_sel:DWORD dst_unused:UNUSED_PAD src0_sel:WORD_1 src1_sel:DWORD
	v_and_b32_sdwa v43, v36, v95 dst_sel:DWORD dst_unused:UNUSED_PAD src0_sel:WORD_1 src1_sel:DWORD
	v_add3_u32 v46, v37, v42, s86
	v_add3_u32 v47, v36, v43, s86
	v_and_b32_e32 v43, 0xffff0000, v46
	v_and_b32_e32 v42, 0xffff0000, v47
	v_cvt_pk_bf16_f32 v197, v36, v37
	v_pk_add_f32 v[36:37], v[36:37], v[42:43] neg_lo:[0,1] neg_hi:[0,1]
	s_waitcnt lgkmcnt(0)
	v_and_b32_sdwa v42, v39, v95 dst_sel:DWORD dst_unused:UNUSED_PAD src0_sel:WORD_1 src1_sel:DWORD
	v_and_b32_sdwa v43, v38, v95 dst_sel:DWORD dst_unused:UNUSED_PAD src0_sel:WORD_1 src1_sel:DWORD
	v_add3_u32 v60, v39, v42, s86
	v_add3_u32 v61, v38, v43, s86
	v_and_b32_e32 v43, 0xffff0000, v60
	v_and_b32_e32 v42, 0xffff0000, v61
	v_cvt_pk_bf16_f32 v198, v38, v39
	v_pk_add_f32 v[38:39], v[38:39], v[42:43] neg_lo:[0,1] neg_hi:[0,1]
	v_and_b32_sdwa v42, v41, v95 dst_sel:DWORD dst_unused:UNUSED_PAD src0_sel:WORD_1 src1_sel:DWORD
	v_and_b32_sdwa v43, v40, v95 dst_sel:DWORD dst_unused:UNUSED_PAD src0_sel:WORD_1 src1_sel:DWORD
	v_add3_u32 v62, v41, v42, s86
	v_add3_u32 v63, v40, v43, s86
	v_and_b32_e32 v43, 0xffff0000, v62
	v_and_b32_e32 v42, 0xffff0000, v63
	v_cvt_pk_bf16_f32 v199, v40, v41
	v_pk_add_f32 v[40:41], v[40:41], v[42:43] neg_lo:[0,1] neg_hi:[0,1]
	v_cvt_pk_bf16_f32 v193, v40, v41
	v_cvt_pk_bf16_f32 v192, v38, v39
	v_cvt_pk_bf16_f32 v191, v36, v37
	v_cvt_pk_bf16_f32 v190, v34, v35
	v_mov_b32_e32 v34, v190
	v_mov_b32_e32 v35, v191
	v_mov_b32_e32 v36, v192
	v_mov_b32_e32 v37, v193
	v_mov_b32_e32 v38, v196
	v_mov_b32_e32 v39, v197
	v_mov_b32_e32 v40, v198
	v_mov_b32_e32 v41, v199
; #define LAS __attribute__((address_space(3)))
; __device__ __forceinline__ float bf2f(unsigned b) { return __uint_as_float(b << 16); }
; __device__ __forceinline__ unsigned f2bf(float f) { unsigned u = __float_as_uint(f); return (u + 0x7fffu + ((u >> 16) & 1u)) >> 16; }
; __device__ __forceinline__ void split8(const f32x4 x0, const f32x4 x1, bf16x8& hi, bf16x8& lo) {
; #pragma unroll
;     for (int j = 0; j < 8; ++j) { const float x = j < 4 ? x0[j & 3] : x1[j & 3]; const unsigned h = f2bf(x); const unsigned l = f2bf(x - bf2f(h)); hi[j] = (short)h; lo[j] = (short)l; }
; }
; __device__ __forceinline__ void phase_gla_pre(const Params& P, LAS unsigned char* lds, bool dry) {
;     ...
;         for (int tt = 0; tt < 4; ++tt) {
;             bf16x8 ahi = (bf16x8){0, 0, 0, 0, 0, 0, 0, 0}, alo = ahi;
;             if (g < 2) { const f32x4 l0 = *(const LAS f32x4*)(Llr + (16 * tt + fr) * 16 + 8 * g), l1 = *(const LAS f32x4*)(Llr + (16 * tt + fr) * 16 + 8 * g + 4); split8(l0, l1, ahi, alo); }
;             f32x4 acc = (f32x4){bg, bg, bg, bg};
;             acc = __builtin_amdgcn_mfma_f32_16x16x32_bf16(alo, bhi, acc, 0, 0, 0); acc = __builtin_amdgcn_mfma_f32_16x16x32_bf16(ahi, blo, acc, 0, 0, 0); acc = __builtin_amdgcn_mfma_f32_16x16x32_bf16(ahi, bhi, acc, 0, 0, 0);
;             float pr[4];
; #pragma unroll
;             for (int r = 0; r < 4; ++r) { const float lg = acc[r]; const float ls = fminf(lg, 0.f) - __logf(1.0f + __expf(-fabsf(lg))); pr[r] = ls * (1.0f / 16.0f) + (r ? pr[r - 1] : 0.f); }
;             const float T = pr[3];
;             const float u1 = __shfl_up(T, 16), s1 = T + (g >= 1 ? u1 : 0.f);
;             const float u2 = __shfl_up(s1, 32), s2 = s1 + (g >= 2 ? u2 : 0.f);
;             const float base = run + (s2 - T); run += __shfl(s2, 48 + fr);
; #pragma unroll
;             for (int r = 0; r < 4; ++r) *(LAS float*)(Lb + (16 * tt + 4 * g + r) * BP + (16 * w + fr) * 4) = base + pr[r];
.LBB0_488:
	s_or_b64 exec, exec, s[36:37]
	v_mfma_f32_16x16x32_bf16 v[34:37], v[34:37], v[20:23], v[28:31]
	v_mfma_f32_16x16x32_bf16 v[34:37], v[38:41], v[24:27], v[34:37]
	v_mfma_f32_16x16x32_bf16 v[34:37], v[38:41], v[20:23], v[34:37]
	s_nop 7
	v_max_f32_e32 v38, v34, v34
	v_mul_f32_e64 v34, |v34|, s89
	v_exp_f32_e32 v34, v34
	v_mul_f32_e64 v39, |v35|, s89
	v_exp_f32_e32 v39, v39
	v_min_f32_e32 v38, 0, v38
	v_add_f32_e32 v34, 1.0, v34
	v_cmp_gt_f32_e32 vcc, s90, v34
	v_add_f32_e32 v39, 1.0, v39
	v_cmp_gt_f32_e64 s[36:37], s90, v39
	v_cndmask_b32_e64 v40, 0, 32, vcc
	v_ldexp_f32 v34, v34, v40
	v_log_f32_e32 v34, v34
	v_cndmask_b32_e64 v41, 0, 32, s[36:37]
	v_ldexp_f32 v39, v39, v41
	v_log_f32_e32 v39, v39
	v_mul_f32_e32 v41, 0x3f317217, v34
	v_fma_f32 v41, v34, s91, -v41
	v_fmac_f32_e32 v41, 0x3377d1cf, v34
	v_cndmask_b32_e32 v40, 0, v97, vcc
	v_fmac_f32_e32 v41, 0x3f317217, v34
	v_cmp_lt_f32_e64 vcc, |v34|, s92
	v_mul_f32_e32 v42, 0x3f317217, v39
	v_max_f32_e32 v35, v35, v35
	v_cndmask_b32_e32 v34, v34, v41, vcc
	v_sub_f32_e32 v34, v34, v40
	v_sub_f32_e32 v34, v38, v34
	v_fma_f32 v38, v39, s91, -v42
	v_fmac_f32_e32 v38, 0x3377d1cf, v39
	v_fmac_f32_e32 v38, 0x3f317217, v39
	v_cmp_lt_f32_e64 vcc, |v39|, s92
	v_cndmask_b32_e64 v40, 0, v97, s[36:37]
	v_min_f32_e32 v35, 0, v35
	v_cndmask_b32_e32 v38, v39, v38, vcc
	v_mul_f32_e64 v39, |v36|, s89
	v_exp_f32_e32 v39, v39
	v_sub_f32_e32 v38, v38, v40
	v_sub_f32_e32 v35, v35, v38
	v_max_f32_e32 v36, v36, v36
	v_add_f32_e32 v38, 1.0, v39
	v_cmp_gt_f32_e32 vcc, s90, v38
	v_min_f32_e32 v36, 0, v36
	v_fma_f32 v34, v34, s93, 0
	v_cndmask_b32_e64 v39, 0, 32, vcc
	v_ldexp_f32 v38, v38, v39
	v_log_f32_e32 v38, v38
	v_cndmask_b32_e32 v40, 0, v97, vcc
	v_fmamk_f32 v35, v35, 0x3d800000, v34
	v_mul_f32_e32 v39, 0x3f317217, v38
	v_fma_f32 v39, v38, s91, -v39
	v_fmac_f32_e32 v39, 0x3377d1cf, v38
	v_fmac_f32_e32 v39, 0x3f317217, v38
	v_cmp_lt_f32_e64 s[36:37], |v38|, s92
	s_nop 1
	v_cndmask_b32_e64 v38, v38, v39, s[36:37]
	v_mul_f32_e64 v39, |v37|, s89
	v_exp_f32_e32 v39, v39
	v_sub_f32_e32 v38, v38, v40
	v_sub_f32_e32 v36, v36, v38
	v_max_f32_e32 v37, v37, v37
	v_add_f32_e32 v38, 1.0, v39
	v_cmp_gt_f32_e32 vcc, s90, v38
	v_min_f32_e32 v37, 0, v37
	v_fmamk_f32 v36, v36, 0x3d800000, v35
	v_cndmask_b32_e64 v39, 0, 32, vcc
	v_ldexp_f32 v38, v38, v39
	v_log_f32_e32 v38, v38
	s_waitcnt lgkmcnt(2)
	v_add_f32_e32 v40, 0, v33
	v_mul_f32_e32 v39, 0x3f317217, v38
	v_fma_f32 v39, v38, s91, -v39
	v_fmac_f32_e32 v39, 0x3377d1cf, v38
	v_fmac_f32_e32 v39, 0x3f317217, v38
	v_cmp_lt_f32_e64 s[36:37], |v38|, s92
	s_nop 1
	v_cndmask_b32_e64 v38, v38, v39, s[36:37]
	v_cndmask_b32_e32 v39, 0, v97, vcc
	v_sub_f32_e32 v38, v38, v39
	v_sub_f32_e32 v37, v37, v38
	v_fmamk_f32 v37, v37, 0x3d800000, v36
	ds_bpermute_b32 v38, v83, v37
	s_waitcnt lgkmcnt(0)
	v_cndmask_b32_e64 v38, v38, 0, s[8:9]
	v_add_f32_e32 v38, v38, v37
	ds_bpermute_b32 v39, v84, v38
	s_waitcnt lgkmcnt(0)
	v_cndmask_b32_e64 v33, 0, v39, s[10:11]
	v_add_f32_e32 v33, v33, v38
	v_sub_f32_e32 v38, v33, v37
	ds_bpermute_b32 v41, v85, v33
	v_add_f32_e32 v38, v40, v38
	v_add_f32_e32 v33, v34, v38
	v_add_f32_e32 v34, v35, v38
	v_add_u32_e32 v35, 0xa800, v98
	ds_write2_b32 v35, v33, v34 offset0:64 offset1:196
	v_add_f32_e32 v33, v36, v38
	v_add_f32_e32 v34, v37, v38
	v_add_u32_e32 v35, 0xac00, v98
	ds_write2_b32 v35, v33, v34 offset0:72 offset1:204
	v_mov_b32_e32 v33, 0
	v_mov_b32_e32 v34, 0
	v_mov_b32_e32 v35, 0
	v_mov_b32_e32 v36, 0
	v_mov_b32_e32 v37, 0
	v_mov_b32_e32 v38, 0
	v_mov_b32_e32 v39, 0
	s_and_saveexec_b64 s[36:37], s[6:7]
	s_cbranch_execz .LBB0_490
	ds_read_b128 v[32:35], v96 offset:2048
	ds_read_b128 v[36:39], v96 offset:2064
	s_waitcnt lgkmcnt(1)
	v_and_b32_sdwa v42, v33, v95 dst_sel:DWORD dst_unused:UNUSED_PAD src0_sel:WORD_1 src1_sel:DWORD
	v_and_b32_sdwa v43, v32, v95 dst_sel:DWORD dst_unused:UNUSED_PAD src0_sel:WORD_1 src1_sel:DWORD
	v_add3_u32 v44, v33, v42, s86
	v_add3_u32 v45, v32, v43, s86
	v_and_b32_e32 v43, 0xffff0000, v44
	v_and_b32_e32 v42, 0xffff0000, v45
	v_cvt_pk_bf16_f32 v204, v32, v33
	v_pk_add_f32 v[32:33], v[32:33], v[42:43] neg_lo:[0,1] neg_hi:[0,1]
	v_and_b32_sdwa v42, v35, v95 dst_sel:DWORD dst_unused:UNUSED_PAD src0_sel:WORD_1 src1_sel:DWORD
	v_and_b32_sdwa v43, v34, v95 dst_sel:DWORD dst_unused:UNUSED_PAD src0_sel:WORD_1 src1_sel:DWORD
	v_add3_u32 v46, v35, v42, s86
	v_add3_u32 v47, v34, v43, s86
	v_and_b32_e32 v43, 0xffff0000, v46
	v_and_b32_e32 v42, 0xffff0000, v47
	v_cvt_pk_bf16_f32 v205, v34, v35
	v_pk_add_f32 v[34:35], v[34:35], v[42:43] neg_lo:[0,1] neg_hi:[0,1]
	s_waitcnt lgkmcnt(0)
	v_and_b32_sdwa v42, v37, v95 dst_sel:DWORD dst_unused:UNUSED_PAD src0_sel:WORD_1 src1_sel:DWORD
	v_and_b32_sdwa v43, v36, v95 dst_sel:DWORD dst_unused:UNUSED_PAD src0_sel:WORD_1 src1_sel:DWORD
	v_add3_u32 v60, v37, v42, s86
	v_add3_u32 v61, v36, v43, s86
	v_and_b32_e32 v43, 0xffff0000, v60
	v_and_b32_e32 v42, 0xffff0000, v61
	v_cvt_pk_bf16_f32 v206, v36, v37
	v_pk_add_f32 v[36:37], v[36:37], v[42:43] neg_lo:[0,1] neg_hi:[0,1]
	v_and_b32_sdwa v42, v39, v95 dst_sel:DWORD dst_unused:UNUSED_PAD src0_sel:WORD_1 src1_sel:DWORD
	v_and_b32_sdwa v43, v38, v95 dst_sel:DWORD dst_unused:UNUSED_PAD src0_sel:WORD_1 src1_sel:DWORD
	v_add3_u32 v62, v39, v42, s86
	v_add3_u32 v63, v38, v43, s86
	v_and_b32_e32 v43, 0xffff0000, v62
	v_and_b32_e32 v42, 0xffff0000, v63
	v_cvt_pk_bf16_f32 v208, v38, v39
	v_pk_add_f32 v[38:39], v[38:39], v[42:43] neg_lo:[0,1] neg_hi:[0,1]
	v_cvt_pk_bf16_f32 v203, v38, v39
	v_cvt_pk_bf16_f32 v202, v36, v37
	v_cvt_pk_bf16_f32 v201, v34, v35
	v_cvt_pk_bf16_f32 v200, v32, v33
	v_mov_b32_e32 v32, v200
	v_mov_b32_e32 v33, v201
	v_mov_b32_e32 v34, v202
	v_mov_b32_e32 v35, v203
	v_mov_b32_e32 v36, v204
	v_mov_b32_e32 v37, v205
	v_mov_b32_e32 v38, v206
	v_mov_b32_e32 v39, v208
; #define LAS __attribute__((address_space(3)))
; __device__ __forceinline__ float bf2f(unsigned b) { return __uint_as_float(b << 16); }
; __device__ __forceinline__ unsigned f2bf(float f) { unsigned u = __float_as_uint(f); return (u + 0x7fffu + ((u >> 16) & 1u)) >> 16; }
; __device__ __forceinline__ void split8(const f32x4 x0, const f32x4 x1, bf16x8& hi, bf16x8& lo) {
; #pragma unroll
;     for (int j = 0; j < 8; ++j) { const float x = j < 4 ? x0[j & 3] : x1[j & 3]; const unsigned h = f2bf(x); const unsigned l = f2bf(x - bf2f(h)); hi[j] = (short)h; lo[j] = (short)l; }
; }
; __device__ __forceinline__ void phase_gla_pre(const Params& P, LAS unsigned char* lds, bool dry) {
;     ...
;         for (int tt = 0; tt < 4; ++tt) {
;             bf16x8 ahi = (bf16x8){0, 0, 0, 0, 0, 0, 0, 0}, alo = ahi;
;             if (g < 2) { const f32x4 l0 = *(const LAS f32x4*)(Llr + (16 * tt + fr) * 16 + 8 * g), l1 = *(const LAS f32x4*)(Llr + (16 * tt + fr) * 16 + 8 * g + 4); split8(l0, l1, ahi, alo); }
;             f32x4 acc = (f32x4){bg, bg, bg, bg};
;             acc = __builtin_amdgcn_mfma_f32_16x16x32_bf16(alo, bhi, acc, 0, 0, 0); acc = __builtin_amdgcn_mfma_f32_16x16x32_bf16(ahi, blo, acc, 0, 0, 0); acc = __builtin_amdgcn_mfma_f32_16x16x32_bf16(ahi, bhi, acc, 0, 0, 0);
;             float pr[4];
; #pragma unroll
;             for (int r = 0; r < 4; ++r) { const float lg = acc[r]; const float ls = fminf(lg, 0.f) - __logf(1.0f + __expf(-fabsf(lg))); pr[r] = ls * (1.0f / 16.0f) + (r ? pr[r - 1] : 0.f); }
;             const float T = pr[3];
;             const float u1 = __shfl_up(T, 16), s1 = T + (g >= 1 ? u1 : 0.f);
;             const float u2 = __shfl_up(s1, 32), s2 = s1 + (g >= 2 ? u2 : 0.f);
;             const float base = run + (s2 - T); run += __shfl(s2, 48 + fr);
; #pragma unroll
;             for (int r = 0; r < 4; ++r) *(LAS float*)(Lb + (16 * tt + 4 * g + r) * BP + (16 * w + fr) * 4) = base + pr[r];
.LBB0_490:
	s_or_b64 exec, exec, s[36:37]
	v_mfma_f32_16x16x32_bf16 v[32:35], v[32:35], v[20:23], v[28:31]
	s_waitcnt lgkmcnt(2)
	v_add_f32_e32 v40, v40, v41
	v_mfma_f32_16x16x32_bf16 v[32:35], v[36:39], v[24:27], v[32:35]
	v_mfma_f32_16x16x32_bf16 v[32:35], v[36:39], v[20:23], v[32:35]
	s_nop 7
	v_max_f32_e32 v36, v32, v32
	v_mul_f32_e64 v32, |v32|, s89
	v_exp_f32_e32 v32, v32
	v_mul_f32_e64 v37, |v33|, s89
	v_exp_f32_e32 v37, v37
	v_min_f32_e32 v36, 0, v36
	v_add_f32_e32 v32, 1.0, v32
	v_cmp_gt_f32_e32 vcc, s90, v32
	v_add_f32_e32 v37, 1.0, v37
	v_cmp_gt_f32_e64 s[36:37], s90, v37
	v_cndmask_b32_e64 v38, 0, 32, vcc
	v_ldexp_f32 v32, v32, v38
	v_log_f32_e32 v32, v32
	v_cndmask_b32_e64 v39, 0, 32, s[36:37]
	v_ldexp_f32 v37, v37, v39
	v_log_f32_e32 v37, v37
	v_mul_f32_e32 v39, 0x3f317217, v32
	v_fma_f32 v39, v32, s91, -v39
	v_fmac_f32_e32 v39, 0x3377d1cf, v32
	v_cndmask_b32_e32 v38, 0, v97, vcc
	v_fmac_f32_e32 v39, 0x3f317217, v32
	v_cmp_lt_f32_e64 vcc, |v32|, s92
	v_mul_f32_e32 v42, 0x3f317217, v37
	v_max_f32_e32 v33, v33, v33
	v_cndmask_b32_e32 v32, v32, v39, vcc
	v_sub_f32_e32 v32, v32, v38
	v_sub_f32_e32 v32, v36, v32
	v_fma_f32 v36, v37, s91, -v42
	v_fmac_f32_e32 v36, 0x3377d1cf, v37
	v_fmac_f32_e32 v36, 0x3f317217, v37
	v_cmp_lt_f32_e64 vcc, |v37|, s92
	v_cndmask_b32_e64 v38, 0, v97, s[36:37]
	v_min_f32_e32 v33, 0, v33
	v_cndmask_b32_e32 v36, v37, v36, vcc
	v_mul_f32_e64 v37, |v34|, s89
	v_exp_f32_e32 v37, v37
	v_sub_f32_e32 v36, v36, v38
	v_sub_f32_e32 v33, v33, v36
	v_max_f32_e32 v34, v34, v34
	v_add_f32_e32 v36, 1.0, v37
	v_cmp_gt_f32_e32 vcc, s90, v36
	v_min_f32_e32 v34, 0, v34
	v_fma_f32 v32, v32, s93, 0
	v_cndmask_b32_e64 v37, 0, 32, vcc
	v_ldexp_f32 v36, v36, v37
	v_log_f32_e32 v36, v36
	v_cndmask_b32_e32 v38, 0, v97, vcc
	v_fmamk_f32 v33, v33, 0x3d800000, v32
	v_mov_b32_e32 v39, 0
	v_mul_f32_e32 v37, 0x3f317217, v36
	v_fma_f32 v37, v36, s91, -v37
	v_fmac_f32_e32 v37, 0x3377d1cf, v36
	v_fmac_f32_e32 v37, 0x3f317217, v36
	v_cmp_lt_f32_e64 s[36:37], |v36|, s92
	s_nop 1
	v_cndmask_b32_e64 v36, v36, v37, s[36:37]
	v_mul_f32_e64 v37, |v35|, s89
	v_exp_f32_e32 v37, v37
	v_sub_f32_e32 v36, v36, v38
	v_sub_f32_e32 v34, v34, v36
	v_max_f32_e32 v35, v35, v35
	v_add_f32_e32 v36, 1.0, v37
	v_cmp_gt_f32_e32 vcc, s90, v36
	v_min_f32_e32 v35, 0, v35
	v_fmamk_f32 v34, v34, 0x3d800000, v33
	v_cndmask_b32_e64 v37, 0, 32, vcc
	v_ldexp_f32 v36, v36, v37
	v_log_f32_e32 v36, v36
	v_mov_b32_e32 v38, 0
	v_mul_f32_e32 v37, 0x3f317217, v36
	v_fma_f32 v37, v36, s91, -v37
	v_fmac_f32_e32 v37, 0x3377d1cf, v36
	v_fmac_f32_e32 v37, 0x3f317217, v36
	v_cmp_lt_f32_e64 s[36:37], |v36|, s92
	s_nop 1
	v_cndmask_b32_e64 v36, v36, v37, s[36:37]
	v_cndmask_b32_e32 v37, 0, v97, vcc
	v_sub_f32_e32 v36, v36, v37
	v_sub_f32_e32 v35, v35, v36
	v_fmamk_f32 v35, v35, 0x3d800000, v34
	ds_bpermute_b32 v36, v83, v35
	s_waitcnt lgkmcnt(0)
	v_cndmask_b32_e64 v36, v36, 0, s[8:9]
	v_add_f32_e32 v36, v36, v35
	ds_bpermute_b32 v37, v84, v36
	s_waitcnt lgkmcnt(0)
	v_cndmask_b32_e64 v37, 0, v37, s[10:11]
	v_add_f32_e32 v36, v37, v36
	v_sub_f32_e32 v37, v36, v35
	ds_bpermute_b32 v41, v85, v36
	v_add_f32_e32 v37, v40, v37
	v_add_f32_e32 v32, v32, v37
	v_add_f32_e32 v33, v33, v37
	v_add_u32_e32 v36, 0xca00, v98
	ds_write2_b32 v36, v32, v33 offset1:132
	v_add_f32_e32 v32, v34, v37
	v_add_f32_e32 v33, v35, v37
	v_add_u32_e32 v34, 0xce00, v98
	ds_write2_b32 v34, v32, v33 offset0:8 offset1:140
	v_mov_b32_e32 v32, 0
	v_mov_b32_e32 v33, 0
	v_mov_b32_e32 v34, 0
	v_mov_b32_e32 v35, 0
	v_mov_b32_e32 v36, 0
	v_mov_b32_e32 v37, 0
	s_and_saveexec_b64 s[36:37], s[6:7]
	s_cbranch_execz .LBB0_492
	ds_read_b128 v[32:35], v96 offset:3072
	ds_read_b128 v[36:39], v96 offset:3088
	s_waitcnt lgkmcnt(1)
	v_and_b32_sdwa v42, v33, v95 dst_sel:DWORD dst_unused:UNUSED_PAD src0_sel:WORD_1 src1_sel:DWORD
	v_and_b32_sdwa v43, v32, v95 dst_sel:DWORD dst_unused:UNUSED_PAD src0_sel:WORD_1 src1_sel:DWORD
	v_add3_u32 v44, v33, v42, s86
	v_add3_u32 v45, v32, v43, s86
	v_and_b32_e32 v43, 0xffff0000, v44
	v_and_b32_e32 v42, 0xffff0000, v45
	v_cvt_pk_bf16_f32 v214, v32, v33
	v_pk_add_f32 v[32:33], v[32:33], v[42:43] neg_lo:[0,1] neg_hi:[0,1]
	v_and_b32_sdwa v42, v35, v95 dst_sel:DWORD dst_unused:UNUSED_PAD src0_sel:WORD_1 src1_sel:DWORD
	v_and_b32_sdwa v43, v34, v95 dst_sel:DWORD dst_unused:UNUSED_PAD src0_sel:WORD_1 src1_sel:DWORD
	v_add3_u32 v46, v35, v42, s86
	v_add3_u32 v47, v34, v43, s86
	v_and_b32_e32 v43, 0xffff0000, v46
	v_and_b32_e32 v42, 0xffff0000, v47
	v_cvt_pk_bf16_f32 v216, v34, v35
	v_pk_add_f32 v[34:35], v[34:35], v[42:43] neg_lo:[0,1] neg_hi:[0,1]
	s_waitcnt lgkmcnt(0)
	v_and_b32_sdwa v42, v37, v95 dst_sel:DWORD dst_unused:UNUSED_PAD src0_sel:WORD_1 src1_sel:DWORD
	v_and_b32_sdwa v43, v36, v95 dst_sel:DWORD dst_unused:UNUSED_PAD src0_sel:WORD_1 src1_sel:DWORD
	v_add3_u32 v60, v37, v42, s86
	v_add3_u32 v61, v36, v43, s86
	v_and_b32_e32 v43, 0xffff0000, v60
	v_and_b32_e32 v42, 0xffff0000, v61
	v_cvt_pk_bf16_f32 v217, v36, v37
	v_pk_add_f32 v[36:37], v[36:37], v[42:43] neg_lo:[0,1] neg_hi:[0,1]
	v_and_b32_sdwa v42, v39, v95 dst_sel:DWORD dst_unused:UNUSED_PAD src0_sel:WORD_1 src1_sel:DWORD
	v_and_b32_sdwa v43, v38, v95 dst_sel:DWORD dst_unused:UNUSED_PAD src0_sel:WORD_1 src1_sel:DWORD
	v_add3_u32 v62, v39, v42, s86
	v_add3_u32 v63, v38, v43, s86
	v_and_b32_e32 v43, 0xffff0000, v62
	v_and_b32_e32 v42, 0xffff0000, v63
	v_cvt_pk_bf16_f32 v218, v38, v39
	v_pk_add_f32 v[38:39], v[38:39], v[42:43] neg_lo:[0,1] neg_hi:[0,1]
	v_cvt_pk_bf16_f32 v213, v38, v39
	v_cvt_pk_bf16_f32 v212, v36, v37
	v_cvt_pk_bf16_f32 v210, v34, v35
	v_cvt_pk_bf16_f32 v209, v32, v33
	v_mov_b32_e32 v32, v209
	v_mov_b32_e32 v33, v210
	v_mov_b32_e32 v34, v212
	v_mov_b32_e32 v35, v213
	v_mov_b32_e32 v36, v214
	v_mov_b32_e32 v37, v216
	v_mov_b32_e32 v38, v217
	v_mov_b32_e32 v39, v218
; #define LAS __attribute__((address_space(3)))
; __device__ __forceinline__ void phase_gla_pre(const Params& P, LAS unsigned char* lds, bool dry) {
;     ...
;         for (int tt = 0; tt < 4; ++tt) {
;             bf16x8 ahi = (bf16x8){0, 0, 0, 0, 0, 0, 0, 0}, alo = ahi;
;             if (g < 2) { const f32x4 l0 = *(const LAS f32x4*)(Llr + (16 * tt + fr) * 16 + 8 * g), l1 = *(const LAS f32x4*)(Llr + (16 * tt + fr) * 16 + 8 * g + 4); split8(l0, l1, ahi, alo); }
;             f32x4 acc = (f32x4){bg, bg, bg, bg};
;             acc = __builtin_amdgcn_mfma_f32_16x16x32_bf16(alo, bhi, acc, 0, 0, 0); acc = __builtin_amdgcn_mfma_f32_16x16x32_bf16(ahi, blo, acc, 0, 0, 0); acc = __builtin_amdgcn_mfma_f32_16x16x32_bf16(ahi, bhi, acc, 0, 0, 0);
;             float pr[4];
; #pragma unroll
;             for (int r = 0; r < 4; ++r) { const float lg = acc[r]; const float ls = fminf(lg, 0.f) - __logf(1.0f + __expf(-fabsf(lg))); pr[r] = ls * (1.0f / 16.0f) + (r ? pr[r - 1] : 0.f); }
;             const float T = pr[3];
;             const float u1 = __shfl_up(T, 16), s1 = T + (g >= 1 ? u1 : 0.f);
;             const float u2 = __shfl_up(s1, 32), s2 = s1 + (g >= 2 ? u2 : 0.f);
;             const float base = run + (s2 - T); run += __shfl(s2, 48 + fr);
; #pragma unroll
;             for (int r = 0; r < 4; ++r) *(LAS float*)(Lb + (16 * tt + 4 * g + r) * BP + (16 * w + fr) * 4) = base + pr[r];
;         }
;         __syncthreads();
;         {
;             f32x4 bb[4], bm[4], bl[4];
; #pragma unroll
;             for (int i = 0; i < 4; ++i) { bb[i] = *(const LAS f32x4*)(Lb + te * BP + (16 * kc + 4 * i) * 4); bm[i] = *(const LAS f32x4*)(Lb + 31 * BP + (16 * kc + 4 * i) * 4); bl[i] = *(const LAS f32x4*)(Lb + 63 * BP + (16 * kc + 4 * i) * 4); }
;             unsigned oqi[8], oki[8], oqd[8], oks[8];
; #pragma unroll
;             for (int e2 = 0; e2 < 8; ++e2) {
;                 const unsigned qw = e2 < 4 ? rq[0][e2] : rq[1][e2 - 4], kw = e2 < 4 ? rk[0][e2] : rk[1][e2 - 4];
;                 float vqi[2], vki[2], vqd[2], vks[2];
; #pragma unroll
;                 for (int hh = 0; hh < 2; ++hh) {
;                     const int e = 2 * e2 + hh; const float bv = bb[e >> 2][e & 3], bmv = bm[e >> 2][e & 3], blv = bl[e >> 2][e & 3];
;                     const float qv = hh ? bfhi(qw) : bflo(qw), kv = hh ? bfhi(kw) : bflo(kw);
;                     const float e1 = __expf(bv - bmv);
.LBB0_492:
	s_or_b64 exec, exec, s[36:37]
	v_mfma_f32_16x16x32_bf16 v[28:31], v[32:35], v[20:23], v[28:31]
	v_and_b32_e32 v111, 0xffff0000, v5
	v_and_b32_e32 v110, 0xffff0000, v4
	v_and_b32_e32 v117, 0xffff0000, v13
	v_mfma_f32_16x16x32_bf16 v[24:27], v[36:39], v[24:27], v[28:31]
	v_and_b32_e32 v116, 0xffff0000, v12
	v_and_b32_e32 v121, 0xffff0000, v7
	v_and_b32_e32 v120, 0xffff0000, v6
	v_mfma_f32_16x16x32_bf16 v[20:23], v[36:39], v[20:23], v[24:27]
	v_and_b32_e32 v127, 0xffff0000, v17
	v_and_b32_e32 v126, 0xffff0000, v16
	v_lshlrev_b32_e32 v125, 16, v17
	v_lshlrev_b32_e32 v124, 16, v16
	v_lshlrev_b32_e32 v133, 16, v11
	s_nop 2
	v_max_f32_e32 v24, v20, v20
	v_mul_f32_e64 v20, |v20|, s89
	v_exp_f32_e32 v20, v20
	v_mul_f32_e64 v25, |v21|, s89
	v_exp_f32_e32 v25, v25
	v_min_f32_e32 v24, 0, v24
	v_add_f32_e32 v20, 1.0, v20
	v_cmp_gt_f32_e32 vcc, s90, v20
	v_add_f32_e32 v25, 1.0, v25
	v_cmp_gt_f32_e64 s[36:37], s90, v25
	v_cndmask_b32_e64 v26, 0, 32, vcc
	v_ldexp_f32 v20, v20, v26
	v_log_f32_e32 v20, v20
	v_cndmask_b32_e64 v27, 0, 32, s[36:37]
	v_ldexp_f32 v25, v25, v27
	v_log_f32_e32 v25, v25
	v_mul_f32_e32 v27, 0x3f317217, v20
	v_fma_f32 v27, v20, s91, -v27
	v_fmac_f32_e32 v27, 0x3377d1cf, v20
	v_cndmask_b32_e32 v26, 0, v97, vcc
	v_fmac_f32_e32 v27, 0x3f317217, v20
	v_cmp_lt_f32_e64 vcc, |v20|, s92
	v_mul_f32_e32 v28, 0x3f317217, v25
	v_max_f32_e32 v21, v21, v21
	v_cndmask_b32_e32 v20, v20, v27, vcc
	v_sub_f32_e32 v20, v20, v26
	v_sub_f32_e32 v20, v24, v20
	v_fma_f32 v24, v25, s91, -v28
	v_fmac_f32_e32 v24, 0x3377d1cf, v25
	v_fmac_f32_e32 v24, 0x3f317217, v25
	v_cmp_lt_f32_e64 vcc, |v25|, s92
	v_cndmask_b32_e64 v26, 0, v97, s[36:37]
	v_min_f32_e32 v21, 0, v21
	v_cndmask_b32_e32 v24, v25, v24, vcc
	v_mul_f32_e64 v25, |v22|, s89
	v_exp_f32_e32 v25, v25
	v_sub_f32_e32 v24, v24, v26
	v_sub_f32_e32 v21, v21, v24
	v_max_f32_e32 v22, v22, v22
	v_add_f32_e32 v24, 1.0, v25
	v_cmp_gt_f32_e32 vcc, s90, v24
	v_min_f32_e32 v22, 0, v22
	v_fma_f32 v20, v20, s93, 0
	v_cndmask_b32_e64 v25, 0, 32, vcc
	v_ldexp_f32 v24, v24, v25
	v_log_f32_e32 v24, v24
	v_cndmask_b32_e32 v26, 0, v97, vcc
	v_fmamk_f32 v21, v21, 0x3d800000, v20
	v_lshlrev_b32_e32 v132, 16, v10
	v_mul_f32_e32 v25, 0x3f317217, v24
	v_fma_f32 v25, v24, s91, -v25
	v_fmac_f32_e32 v25, 0x3377d1cf, v24
	v_fmac_f32_e32 v25, 0x3f317217, v24
	v_cmp_lt_f32_e64 s[36:37], |v24|, s92
	v_and_b32_e32 v135, 0xffff0000, v11
	v_and_b32_e32 v134, 0xffff0000, v10
	v_cndmask_b32_e64 v24, v24, v25, s[36:37]
	v_mul_f32_e64 v25, |v23|, s89
	v_exp_f32_e32 v25, v25
	v_sub_f32_e32 v24, v24, v26
	v_sub_f32_e32 v22, v22, v24
	v_max_f32_e32 v23, v23, v23
	v_add_f32_e32 v24, 1.0, v25
	v_cmp_gt_f32_e32 vcc, s90, v24
	v_min_f32_e32 v23, 0, v23
	v_fmamk_f32 v22, v22, 0x3d800000, v21
	v_cndmask_b32_e64 v25, 0, 32, vcc
	v_ldexp_f32 v24, v24, v25
	v_log_f32_e32 v24, v24
	s_waitcnt lgkmcnt(2)
	v_add_f32_e32 v26, v40, v41
	s_and_b32 s74, s1, 0xfc0
	s_ashr_i32 s83, s82, 31
	v_mul_f32_e32 v25, 0x3f317217, v24
	v_fma_f32 v25, v24, s91, -v25
	v_fmac_f32_e32 v25, 0x3377d1cf, v24
	v_fmac_f32_e32 v25, 0x3f317217, v24
	v_cmp_lt_f32_e64 s[36:37], |v24|, s92
	s_nop 1
	v_cndmask_b32_e64 v24, v24, v25, s[36:37]
	v_cndmask_b32_e32 v25, 0, v97, vcc
	v_sub_f32_e32 v24, v24, v25
	v_sub_f32_e32 v23, v23, v24
	v_fmamk_f32 v23, v23, 0x3d800000, v22
	ds_bpermute_b32 v24, v83, v23
	s_lshl_b64 s[36:37], s[82:83], 20
	s_waitcnt lgkmcnt(0)
	v_cndmask_b32_e64 v24, v24, 0, s[8:9]
	v_add_f32_e32 v24, v24, v23
	ds_bpermute_b32 v25, v84, v24
	s_waitcnt lgkmcnt(0)
	v_cndmask_b32_e64 v25, 0, v25, s[10:11]
	v_add_f32_e32 v24, v25, v24
	v_sub_f32_e32 v24, v24, v23
	v_add_f32_e32 v24, v26, v24
	v_add_f32_e32 v20, v20, v24
	v_add_f32_e32 v21, v21, v24
	v_add_u32_e32 v25, 0xea00, v98
	ds_write2_b32 v25, v20, v21 offset0:64 offset1:196
	v_add_f32_e32 v20, v22, v24
	v_add_f32_e32 v21, v23, v24
	v_add_u32_e32 v22, 0xee00, v98
	ds_write2_b32 v22, v20, v21 offset0:72 offset1:204
	v_add_u32_e32 v22, s94, v87
	s_waitcnt lgkmcnt(0)
	s_barrier
	v_add_u32_e32 v20, v86, v87
	v_add_u32_e32 v21, 0, v87
	ds_read_b128 v[32:35], v22
	ds_read_b128 v[24:27], v89
	ds_read_b128 v[60:63], v21 offset:51184
	ds_read_b128 v[64:67], v20 offset:34816
	ds_read_b128 v[74:77], v20 offset:34832
	ds_read_b128 v[44:47], v20 offset:34848
	ds_read_b128 v[36:39], v20 offset:34864
	ds_read_b128 v[100:103], v21 offset:51200
	s_waitcnt lgkmcnt(4)
	v_sub_f32_e32 v61, v65, v61
	v_mul_f32_e32 v61, 0x3fb8aa3b, v61
	v_sub_f32_e32 v63, v67, v63
	v_exp_f32_e32 v72, v61
	v_sub_f32_e32 v61, v32, v64
	v_mul_f32_e32 v63, 0x3fb8aa3b, v63
	v_mul_f32_e32 v61, 0x3fb8aa3b, v61
	v_exp_f32_e32 v73, v63
	v_exp_f32_e32 v78, v61
	v_mul_f32_e32 v61, 0x3fb8aa3b, v65
	v_sub_f32_e32 v20, v64, v60
	v_exp_f32_e32 v108, v61
	v_sub_f32_e32 v61, v66, v62
	v_mul_f32_e32 v20, 0x3fb8aa3b, v20
	v_mul_f32_e32 v69, 0x3fb8aa3b, v64
	v_mul_f32_e32 v61, 0x3fb8aa3b, v61
	v_sub_f32_e32 v62, v33, v65
	v_mul_f32_e32 v65, 0x3fb8aa3b, v66
	v_sub_f32_e32 v63, v34, v66
	v_exp_f32_e32 v60, v20
	v_exp_f32_e32 v70, v69
	v_rcp_f32_e32 v64, v72
	v_exp_f32_e32 v61, v61
	v_exp_f32_e32 v71, v65
	v_mul_f32_e32 v63, 0x3fb8aa3b, v63
	v_rcp_f32_e32 v65, v73
	v_exp_f32_e32 v79, v63
	v_mul_f32_e32 v63, 0x3fb8aa3b, v67
	v_exp_f32_e32 v109, v63
	v_sub_f32_e32 v63, v35, v67
	v_lshlrev_b32_e32 v67, 16, v5
	v_lshlrev_b32_e32 v66, 16, v4
	v_pk_mul_f32 v[112:113], v[60:61], v[66:67]
	v_pk_mul_f32 v[114:115], v[72:73], v[110:111]
	v_pk_mul_f32 v[72:73], v[64:65], v[116:117]
	v_pk_mul_f32 v[64:65], v[70:71], v[66:67]
	s_waitcnt lgkmcnt(0)
; #define LAS __attribute__((address_space(3)))
; __device__ __forceinline__ float bflo(unsigned w) { return __uint_as_float(w << 16); }
; __device__ __forceinline__ float bfhi(unsigned w) { return __uint_as_float(w & 0xffff0000u); }
; __device__ __forceinline__ unsigned pk2(float lo, float hi) { return f2bf(lo) | (f2bf(hi) << 16); }
; __device__ __forceinline__ void phase_gla_pre(const Params& P, LAS unsigned char* lds, bool dry) {
;     ...
;                     const int e = 2 * e2 + hh; const float bv = bb[e >> 2][e & 3], bmv = bm[e >> 2][e & 3], blv = bl[e >> 2][e & 3];
;                     const float qv = hh ? bfhi(qw) : bflo(qw), kv = hh ? bfhi(kw) : bflo(kw);
;                     const float e1 = __expf(bv - bmv);
;                     vqi[hh] = qv * e1; vki[hh] = kv * __builtin_amdgcn_rcpf(e1); vqd[hh] = qv * __expf(bv); vks[hh] = kv * __expf(blv - bv);
;                 }
;                 oqi[e2] = pk2(vqi[0], vqi[1]); oki[e2] = pk2(vki[0], vki[1]); oqd[e2] = pk2(vqd[0], vqd[1]); oks[e2] = pk2(vks[0], vks[1]);
;             }
;             *(LAS u32x4*)(Lqi + te * QP + 32 * kc) = (u32x4){oqi[0], oqi[1], oqi[2], oqi[3]}; *(LAS u32x4*)(Lqi + te * QP + 32 * kc + 16) = (u32x4){oqi[4], oqi[5], oqi[6], oqi[7]};
	v_sub_f32_e32 v66, v74, v100
	v_mul_f32_e32 v66, 0x3fb8aa3b, v66
	v_mul_f32_e32 v71, 0x3fb8aa3b, v74
	v_exp_f32_e32 v70, v66
	v_pk_mul_f32 v[66:67], v[108:109], v[110:111]
	v_exp_f32_e32 v108, v71
	v_sub_f32_e32 v71, v75, v101
	v_mul_f32_e32 v71, 0x3fb8aa3b, v71
	v_mul_f32_e32 v62, 0x3fb8aa3b, v62
	v_mul_f32_e32 v63, 0x3fb8aa3b, v63
	v_exp_f32_e32 v100, v71
	v_sub_f32_e32 v71, v24, v74
	v_exp_f32_e32 v62, v62
	v_exp_f32_e32 v63, v63
	v_mul_f32_e32 v71, 0x3fb8aa3b, v71
	v_exp_f32_e32 v74, v71
	v_mul_f32_e32 v71, 0x3fb8aa3b, v75
	v_sub_f32_e32 v75, v25, v75
	v_mul_f32_e32 v75, 0x3fb8aa3b, v75
	v_exp_f32_e32 v118, v75
	v_mul_f32_e32 v75, 0x3fb8aa3b, v76
	v_pk_mul_f32 v[62:63], v[62:63], v[116:117]
	v_exp_f32_e32 v116, v71
	v_sub_f32_e32 v71, v76, v102
	v_exp_f32_e32 v109, v75
	v_sub_f32_e32 v75, v77, v103
	v_mul_f32_e32 v71, 0x3fb8aa3b, v71
	v_mul_f32_e32 v75, 0x3fb8aa3b, v75
	v_rcp_f32_e32 v68, v60
	v_rcp_f32_e32 v69, v61
	v_exp_f32_e32 v71, v71
	v_exp_f32_e32 v101, v75
	v_sub_f32_e32 v75, v26, v76
	v_mul_f32_e32 v76, 0x3fb8aa3b, v77
	v_exp_f32_e32 v117, v76
	v_sub_f32_e32 v76, v27, v77
	v_mul_f32_e32 v76, 0x3fb8aa3b, v76
	v_lshlrev_b32_e32 v61, 16, v13
	v_lshlrev_b32_e32 v60, 16, v12
	v_exp_f32_e32 v119, v76
	v_lshlrev_b32_e32 v77, 16, v7
	v_lshlrev_b32_e32 v76, 16, v6
	v_pk_mul_f32 v[68:69], v[68:69], v[60:61]
	v_pk_mul_f32 v[60:61], v[78:79], v[60:61]
	v_rcp_f32_e32 v78, v70
	v_rcp_f32_e32 v110, v100
	v_rcp_f32_e32 v79, v71
	v_rcp_f32_e32 v111, v101
	v_pk_mul_f32 v[70:71], v[70:71], v[76:77]
	v_pk_mul_f32 v[100:101], v[100:101], v[120:121]
	v_cvt_pk_bf16_f32 v224, v112, v114
	v_cvt_pk_bf16_f32 v222, v113, v115
	v_cvt_pk_bf16_f32 v221, v70, v100
	v_cvt_pk_bf16_f32 v220, v71, v101
	ds_read_b128 v[104:107], v21 offset:51216
	ds_read_b128 v[40:43], v21 offset:51232
	ds_read_b128 v[28:31], v90
	ds_read_b128 v[20:23], v91
	v_mov_b32_e32 v103, v220
	v_mov_b32_e32 v102, v221
	v_lshlrev_b32_e32 v71, 16, v15
	v_lshlrev_b32_e32 v70, 16, v14
	v_mul_f32_e32 v75, 0x3fb8aa3b, v75
	v_mov_b32_e32 v101, v222
	v_mov_b32_e32 v100, v224
	v_pk_mul_f32 v[114:115], v[78:79], v[70:71]
	s_waitcnt lgkmcnt(3)
	v_sub_f32_e32 v78, v44, v104
	v_sub_f32_e32 v105, v45, v105
	v_exp_f32_e32 v75, v75
	v_mul_f32_e32 v78, 0x3fb8aa3b, v78
	v_mul_f32_e32 v105, 0x3fb8aa3b, v105
	v_exp_f32_e32 v104, v78
	v_pk_mul_f32 v[78:79], v[116:117], v[120:121]
	v_exp_f32_e32 v116, v105
	v_mul_f32_e32 v105, 0x3fb8aa3b, v45
	s_waitcnt lgkmcnt(1)
	v_sub_f32_e32 v45, v29, v45
	v_mul_f32_e32 v45, 0x3fb8aa3b, v45
	v_and_b32_e32 v113, 0xffff0000, v15
	v_and_b32_e32 v112, 0xffff0000, v14
	v_exp_f32_e32 v120, v105
	v_sub_f32_e32 v105, v46, v106
	v_exp_f32_e32 v106, v45
	v_mul_f32_e32 v45, 0x3fb8aa3b, v46
	v_pk_mul_f32 v[110:111], v[110:111], v[112:113]
	v_pk_mul_f32 v[70:71], v[74:75], v[70:71]
	v_pk_mul_f32 v[74:75], v[118:119], v[112:113]
	v_exp_f32_e32 v113, v45
	v_sub_f32_e32 v45, v47, v107
	v_mul_f32_e32 v45, 0x3fb8aa3b, v45
	v_exp_f32_e32 v117, v45
	v_sub_f32_e32 v45, v30, v46
	v_mul_f32_e32 v46, 0x3fb8aa3b, v47
	v_exp_f32_e32 v121, v46
	v_sub_f32_e32 v46, v31, v47
	v_pk_mul_f32 v[76:77], v[108:109], v[76:77]
	v_mul_f32_e32 v109, 0x3fb8aa3b, v44
	v_mul_f32_e32 v105, 0x3fb8aa3b, v105
	v_mul_f32_e32 v46, 0x3fb8aa3b, v46
	v_exp_f32_e32 v112, v109
	v_exp_f32_e32 v105, v105
	v_exp_f32_e32 v107, v46
	v_rcp_f32_e32 v118, v116
	v_rcp_f32_e32 v119, v117
	v_sub_f32_e32 v44, v28, v44
	v_lshlrev_b32_e32 v47, 16, v9
	v_lshlrev_b32_e32 v46, 16, v8
	v_rcp_f32_e32 v108, v104
	v_mul_f32_e32 v44, 0x3fb8aa3b, v44
	v_rcp_f32_e32 v109, v105
	v_mul_f32_e32 v45, 0x3fb8aa3b, v45
	v_pk_mul_f32 v[104:105], v[104:105], v[46:47]
	v_pk_mul_f32 v[112:113], v[112:113], v[46:47]
	v_sub_f32_e32 v40, v36, v40
	v_pk_mul_f32 v[46:47], v[106:107], v[126:127]
	v_mul_f32_e32 v107, 0x3fb8aa3b, v36
	s_waitcnt lgkmcnt(0)
; #define LAS __attribute__((address_space(3)))
; __device__ __forceinline__ float bflo(unsigned w) { return __uint_as_float(w << 16); }
; __device__ __forceinline__ float bfhi(unsigned w) { return __uint_as_float(w & 0xffff0000u); }
; __device__ __forceinline__ unsigned pk2(float lo, float hi) { return f2bf(lo) | (f2bf(hi) << 16); }
; __device__ __forceinline__ void phase_gla_pre(const Params& P, LAS unsigned char* lds, bool dry) {
;     ...
;             for (int e2 = 0; e2 < 8; ++e2) {
;                 const unsigned qw = e2 < 4 ? rq[0][e2] : rq[1][e2 - 4], kw = e2 < 4 ? rk[0][e2] : rk[1][e2 - 4];
;                 float vqi[2], vki[2], vqd[2], vks[2];
; #pragma unroll
;                 for (int hh = 0; hh < 2; ++hh) {
;                     const int e = 2 * e2 + hh; const float bv = bb[e >> 2][e & 3], bmv = bm[e >> 2][e & 3], blv = bl[e >> 2][e & 3];
;                     const float qv = hh ? bfhi(qw) : bflo(qw), kv = hh ? bfhi(kw) : bflo(kw);
;                     const float e1 = __expf(bv - bmv);
;                     vqi[hh] = qv * e1; vki[hh] = kv * __builtin_amdgcn_rcpf(e1); vqd[hh] = qv * __expf(bv); vks[hh] = kv * __expf(blv - bv);
;                 }
;                 oqi[e2] = pk2(vqi[0], vqi[1]); oki[e2] = pk2(vki[0], vki[1]); oqd[e2] = pk2(vqd[0], vqd[1]); oks[e2] = pk2(vks[0], vks[1]);
;             }
;             *(LAS u32x4*)(Lqi + te * QP + 32 * kc) = (u32x4){oqi[0], oqi[1], oqi[2], oqi[3]}; *(LAS u32x4*)(Lqi + te * QP + 32 * kc + 16) = (u32x4){oqi[4], oqi[5], oqi[6], oqi[7]};
;             *(LAS u32x4*)(Lki + te * QP + 32 * kc) = (u32x4){oki[0], oki[1], oki[2], oki[3]}; *(LAS u32x4*)(Lki + te * QP + 32 * kc + 16) = (u32x4){oki[4], oki[5], oki[6], oki[7]};
;             if (!dry) {
;                 bf16_t* p_ = PJ + ((size_t)bh * SEQ + c * 64 + te) * 128 + 16 * kc;
;                 *(u32x4*)(p_ + T_Q) = (u32x4){oqd[0], oqd[1], oqd[2], oqd[3]}; *(u32x4*)(p_ + T_Q + 8) = (u32x4){oqd[4], oqd[5], oqd[6], oqd[7]};
;                 *(u32x4*)(p_ + T_K) = (u32x4){oks[0], oks[1], oks[2], oks[3]}; *(u32x4*)(p_ + T_K + 8) = (u32x4){oks[4], oks[5], oks[6], oks[7]};
;                 if (te == 63) {
; #pragma unroll
;                     for (int i = 0; i < 4; ++i) *(f32x4*)(DEC + (size_t)item * 128 + 16 * kc + 4 * i) = (f32x4){__expf(bl[i][0]), __expf(bl[i][1]), __expf(bl[i][2]), __expf(bl[i][3])};
;                 }
	v_sub_f32_e32 v36, v20, v36
	v_exp_f32_e32 v44, v44
	v_exp_f32_e32 v45, v45
	v_mul_f32_e32 v36, 0x3fb8aa3b, v36
	v_pk_mul_f32 v[118:119], v[118:119], v[126:127]
	v_exp_f32_e32 v126, v36
	v_mul_f32_e32 v36, 0x3fb8aa3b, v37
	v_sub_f32_e32 v41, v37, v41
	v_exp_f32_e32 v130, v36
	v_sub_f32_e32 v36, v38, v42
	v_mul_f32_e32 v41, 0x3fb8aa3b, v41
	v_mul_f32_e32 v36, 0x3fb8aa3b, v36
	v_pk_mul_f32 v[108:109], v[108:109], v[124:125]
	v_pk_mul_f32 v[44:45], v[44:45], v[124:125]
	v_exp_f32_e32 v124, v41
	v_exp_f32_e32 v41, v36
	v_sub_f32_e32 v36, v21, v37
	v_mul_f32_e32 v36, 0x3fb8aa3b, v36
	v_and_b32_e32 v123, 0xffff0000, v9
	v_and_b32_e32 v122, 0xffff0000, v8
	v_exp_f32_e32 v42, v36
	v_mul_f32_e32 v36, 0x3fb8aa3b, v38
	v_pk_mul_f32 v[116:117], v[116:117], v[122:123]
	v_pk_mul_f32 v[120:121], v[120:121], v[122:123]
	v_exp_f32_e32 v123, v36
	v_sub_f32_e32 v36, v39, v43
	v_mul_f32_e32 v36, 0x3fb8aa3b, v36
	v_mul_f32_e32 v40, 0x3fb8aa3b, v40
	v_exp_f32_e32 v125, v36
	v_sub_f32_e32 v36, v22, v38
	v_exp_f32_e32 v40, v40
	v_mul_f32_e32 v36, 0x3fb8aa3b, v36
	v_exp_f32_e32 v127, v36
	v_mul_f32_e32 v36, 0x3fb8aa3b, v39
	v_exp_f32_e32 v131, v36
	v_sub_f32_e32 v36, v23, v39
	v_mul_f32_e32 v36, 0x3fb8aa3b, v36
	v_rcp_f32_e32 v128, v124
	v_rcp_f32_e32 v129, v125
	v_exp_f32_e32 v43, v36
	v_pk_mul_f32 v[36:37], v[40:41], v[132:133]
	v_pk_mul_f32 v[38:39], v[124:125], v[134:135]
	v_rcp_f32_e32 v106, v40
	v_exp_f32_e32 v122, v107
	v_rcp_f32_e32 v107, v41
	v_cvt_pk_bf16_f32 v228, v104, v116
	v_cvt_pk_bf16_f32 v227, v105, v117
	v_cvt_pk_bf16_f32 v226, v36, v38
	v_cvt_pk_bf16_f32 v225, v37, v39
	v_mov_b32_e32 v39, v225
	v_mov_b32_e32 v38, v226
	v_mov_b32_e32 v37, v227
	v_mov_b32_e32 v36, v228
	ds_write_b128 v92, v[100:103]
	ds_write_b128 v92, v[36:39] offset:16
	v_cvt_pk_bf16_f32 v230, v68, v72
	v_cvt_pk_bf16_f32 v229, v69, v73
	v_lshlrev_b32_e32 v41, 16, v19
	v_lshlrev_b32_e32 v40, 16, v18
	v_cvt_pk_bf16_f32 v39, v115, v111
	v_cvt_pk_bf16_f32 v38, v114, v110
	v_mov_b32_e32 v37, v229
	v_mov_b32_e32 v36, v230
	v_and_b32_e32 v105, 0xffff0000, v19
	v_and_b32_e32 v104, 0xffff0000, v18
	v_pk_mul_f32 v[106:107], v[106:107], v[40:41]
	ds_write_b128 v92, v[36:39] offset:17408
	v_pk_mul_f32 v[116:117], v[128:129], v[104:105]
	v_cvt_pk_bf16_f32 v39, v107, v117
	v_cvt_pk_bf16_f32 v38, v106, v116
	v_cvt_pk_bf16_f32 v37, v109, v119
	v_cvt_pk_bf16_f32 v36, v108, v118
	ds_write_b128 v92, v[36:39] offset:17424
	v_lshl_add_u64 v[36:37], s[74:75], 0, v[48:49]
	v_lshlrev_b64 v[36:37], 8, v[36:37]
	v_lshl_add_u64 v[38:39], v[52:53], 0, s[36:37]
	v_lshl_add_u64 v[68:69], v[38:39], 0, v[36:37]
	v_cvt_pk_bf16_f32 v232, v64, v66
	v_cvt_pk_bf16_f32 v233, v65, v67
	s_brev_b32 s36, 16
	v_cvt_pk_bf16_f32 v39, v77, v79
	v_mov_b32_e32 v36, v232
	v_add_co_u32_e32 v64, vcc, s36, v68
	v_cvt_pk_bf16_f32 v38, v76, v78
	v_mov_b32_e32 v37, v233
	v_addc_co_u32_e32 v65, vcc, 0, v69, vcc
	v_pk_mul_f32 v[122:123], v[122:123], v[132:133]
	global_store_dwordx4 v[64:65], v[36:39], off
	v_pk_mul_f32 v[124:125], v[130:131], v[134:135]
	s_nop 0
	v_cvt_pk_bf16_f32 v39, v123, v125
	v_cvt_pk_bf16_f32 v38, v122, v124
	v_cvt_pk_bf16_f32 v37, v113, v121
	v_cvt_pk_bf16_f32 v36, v112, v120
	global_store_dwordx4 v[64:65], v[36:39], off offset:16
	s_nop 1
	s_nop 0
	v_cvt_pk_bf16_f32 v234, v60, v62
	v_cvt_pk_bf16_f32 v235, v61, v63
	v_cvt_pk_bf16_f32 v39, v71, v75
	v_mov_b32_e32 v36, v234
	v_add_co_u32_e32 v60, vcc, s95, v68
	v_pk_mul_f32 v[42:43], v[42:43], v[104:105]
	v_cvt_pk_bf16_f32 v38, v70, v74
	v_mov_b32_e32 v37, v235
	v_addc_co_u32_e32 v61, vcc, 0, v69, vcc
	v_pk_mul_f32 v[40:41], v[126:127], v[40:41]
	global_store_dwordx4 v[60:61], v[36:39], off
	s_nop 1
	v_cvt_pk_bf16_f32 v240, v44, v46
	v_cvt_pk_bf16_f32 v239, v45, v47
	v_cvt_pk_bf16_f32 v238, v40, v42
	v_cvt_pk_bf16_f32 v237, v41, v43
	v_mov_b32_e32 v39, v237
	v_mov_b32_e32 v38, v238
	v_mov_b32_e32 v37, v239
	v_mov_b32_e32 v36, v240
	global_store_dwordx4 v[60:61], v[36:39], off offset:16
	s_and_saveexec_b64 s[36:37], s[12:13]
	s_cbranch_execz .LBB0_494
	v_mul_f32_e32 v32, 0x3fb8aa3b, v32
	v_mul_f32_e32 v33, 0x3fb8aa3b, v33
	v_mul_f32_e32 v34, 0x3fb8aa3b, v34
	v_mul_f32_e32 v35, 0x3fb8aa3b, v35
	v_exp_f32_e32 v32, v32
	v_exp_f32_e32 v33, v33
	v_exp_f32_e32 v34, v34
	v_exp_f32_e32 v35, v35
	v_mul_f32_e32 v24, 0x3fb8aa3b, v24
	v_mul_f32_e32 v25, 0x3fb8aa3b, v25
	v_mul_f32_e32 v26, 0x3fb8aa3b, v26
	v_mul_f32_e32 v27, 0x3fb8aa3b, v27
	s_ashr_i32 s81, s80, 31
	v_exp_f32_e32 v24, v24
	v_exp_f32_e32 v25, v25
	v_exp_f32_e32 v26, v26
	v_exp_f32_e32 v27, v27
	v_mul_f32_e32 v28, 0x3fb8aa3b, v28
	v_mul_f32_e32 v29, 0x3fb8aa3b, v29
	v_mul_f32_e32 v30, 0x3fb8aa3b, v30
	v_mul_f32_e32 v31, 0x3fb8aa3b, v31
	s_lshl_b64 s[42:43], s[80:81], 9
	v_exp_f32_e32 v28, v28
	v_exp_f32_e32 v29, v29
	v_exp_f32_e32 v30, v30
	v_exp_f32_e32 v31, v31
	v_mul_f32_e32 v20, 0x3fb8aa3b, v20
	v_mul_f32_e32 v21, 0x3fb8aa3b, v21
	v_mul_f32_e32 v22, 0x3fb8aa3b, v22
	v_mul_f32_e32 v23, 0x3fb8aa3b, v23
	v_lshl_add_u64 v[36:37], v[54:55], 0, s[42:43]
	v_exp_f32_e32 v20, v20
	v_exp_f32_e32 v21, v21
	v_exp_f32_e32 v22, v22
	v_exp_f32_e32 v23, v23
	global_store_dwordx4 v[36:37], v[32:35], off
	global_store_dwordx4 v[36:37], v[24:27], off offset:16
	global_store_dwordx4 v[36:37], v[28:31], off offset:32
	global_store_dwordx4 v[36:37], v[20:23], off offset:48

; #define LAS __attribute__((address_space(3)))
; __device__ __forceinline__ float bflo(unsigned w) { return __uint_as_float(w << 16); }
; __device__ __forceinline__ float bfhi(unsigned w) { return __uint_as_float(w & 0xffff0000u); }
; __device__ __forceinline__ unsigned pk2(float lo, float hi) { return f2bf(lo) | (f2bf(hi) << 16); }
; template <bool FULL>
; __device__ __forceinline__ void gla_pass(const Params& P, LAS unsigned char* lds, f32x4 (&S)[8][2], int bh, int c0, int L, bool dry) {
;     ...
;         if (FULL) {
;             f32x4 gn[2];
; #pragma unroll
;             for (int vt = 0; vt < 2; ++vt) gn[vt] = *(const f32x4*)(P.gla_norm_g + 32 * w + 4 * g + 16 * vt);
; #pragma unroll
;             for (int tt = 0; tt < 4; ++tt) {
;                 const int t = 16 * tt + fr;
;                 const f32x4 r0 = *(const LAS f32x4*)(red + t * 8), r1 = *(const LAS f32x4*)(red + t * 8 + 4);
;                 const float rstd = 1.0f / sqrtf(((r0[0] + r0[1]) + (r0[2] + r0[3]) + (r1[0] + r1[1]) + (r1[2] + r1[3])) * (1.0f / 256.0f) + RMS_EPS);
; #pragma unroll
;                 for (int vt = 0; vt < 2; ++vt) {
;                     bf16_t* op = (bf16_t*)P.out + (row0 + t) * 2048 + 1024 + h * 256 + 32 * w + 16 * vt + 4 * g;
;                     const u32x2 z = zb[vt][tt]; const f32x4 ov = o[vt][tt] * rstd * gn[vt];
;                     u32x2 r; r.x = pk2(ov[0] * bflo(z.x), ov[1] * bfhi(z.x)); r.y = pk2(ov[2] * bflo(z.y), ov[3] * bfhi(z.y));
;                     if (!dry) *(u32x2*)op = r;
;                 }
;             }
.LBB0_564:
	global_load_dwordx4 v[140:143], v[162:163], off
	global_load_dwordx4 v[136:139], v[162:163], off offset:64
	ds_read_b128 v[212:215], v200
	ds_read_b128 v[216:219], v200 offset:16
	s_waitcnt vmcnt(9)
	v_lshlrev_b32_e32 v221, 16, v185
	v_lshlrev_b32_e32 v220, 16, v184
	v_and_b32_e32 v223, 0xffff0000, v185
	s_waitcnt lgkmcnt(1)
	v_mov_b32_e32 v224, v213
	v_mov_b32_e32 v225, v214
	v_mov_b32_e32 v213, v215
	s_waitcnt lgkmcnt(0)
	v_mov_b32_e32 v214, v218
	v_mov_b32_e32 v215, v216
	v_mov_b32_e32 v216, v219
	v_pk_add_f32 v[212:213], v[224:225], v[212:213]
	v_pk_add_f32 v[214:215], v[214:215], v[216:217]
	v_add_f32_e32 v211, v212, v213
	v_add_f32_e32 v211, v211, v215
	v_add_f32_e32 v211, v214, v211
	v_fmamk_f32 v211, v211, 0x3b800000, v186
	v_mul_f32_e32 v212, 0x4f800000, v211
	v_cmp_gt_f32_e32 vcc, s91, v211
	v_and_b32_e32 v222, 0xffff0000, v184
	s_waitcnt vmcnt(6)
	v_lshlrev_b32_e32 v213, 16, v183
	v_cndmask_b32_e32 v211, v211, v212, vcc
	v_sqrt_f32_e32 v214, v211
	v_lshlrev_b32_e32 v212, 16, v182
	v_and_b32_e32 v183, 0xffff0000, v183
	v_and_b32_e32 v182, 0xffff0000, v182
	v_add_u32_e32 v215, -1, v214
	v_add_u32_e32 v216, 1, v214
	v_fma_f32 v217, -v215, v214, v211
	v_fma_f32 v218, -v216, v214, v211
	v_cmp_ge_f32_e64 s[8:9], 0, v217
	v_lshl_add_u64 v[184:185], v[176:177], 0, v[172:173]
	s_add_u32 s28, s28, 0x8000
	v_cndmask_b32_e64 v214, v214, v215, s[8:9]
	v_cmp_lt_f32_e64 s[8:9], 0, v218
	s_addc_u32 s29, s29, 0
	s_add_u32 s30, s30, 0x4000
	v_cndmask_b32_e64 v214, v214, v216, s[8:9]
	v_mul_f32_e32 v215, 0x37800000, v214
	v_cndmask_b32_e32 v214, v214, v215, vcc
	v_cmp_class_f32_e32 vcc, v211, v187
	s_addc_u32 s31, s31, 0
	s_add_i32 s27, s27, 1
	v_cndmask_b32_e32 v211, v214, v211, vcc
	v_div_scale_f32 v214, s[8:9], v211, v211, 1.0
	v_rcp_f32_e32 v215, v214
	v_div_scale_f32 v216, vcc, 1.0, v211, 1.0
	v_lshl_add_u64 v[174:175], v[174:175], 0, s[22:23]
	v_fma_f32 v217, -v214, v215, 1.0
	v_fmac_f32_e32 v215, v217, v215
	v_mul_f32_e32 v217, v216, v215
	v_fma_f32 v218, -v214, v217, v216
	v_fmac_f32_e32 v217, v218, v215
	v_fma_f32 v214, -v214, v217, v216
	v_div_fmas_f32 v214, v214, v215, v217
	v_div_fixup_f32 v214, v214, v211, 1.0
	v_pk_mul_f32 v[134:135], v[134:135], v[214:215] op_sel_hi:[1,0]
	v_pk_mul_f32 v[132:133], v[132:133], v[214:215] op_sel_hi:[1,0]
	v_pk_mul_f32 v[130:131], v[130:131], v[214:215] op_sel_hi:[1,0]
	v_pk_mul_f32 v[128:129], v[128:129], v[214:215] op_sel_hi:[1,0]
	s_cmp_lg_u32 s28, 0x200000
	v_lshl_add_u64 v[176:177], v[176:177], 0, s[24:25]
	s_waitcnt vmcnt(1)
	v_pk_mul_f32 v[132:133], v[140:141], v[132:133]
	v_pk_mul_f32 v[134:135], v[142:143], v[134:135]
	s_waitcnt vmcnt(0)
	v_pk_mul_f32 v[128:129], v[136:137], v[128:129]
	v_pk_mul_f32 v[130:131], v[138:139], v[130:131]
	v_mov_b32_e32 v214, v132
	v_mov_b32_e32 v215, v134
	v_mov_b32_e32 v134, v133
	v_mov_b32_e32 v132, v128
	v_mov_b32_e32 v133, v130
	v_mov_b32_e32 v130, v129
	v_pk_mul_f32 v[128:129], v[214:215], v[220:221]
	v_pk_mul_f32 v[134:135], v[134:135], v[222:223]
	v_pk_mul_f32 v[132:133], v[132:133], v[212:213]
	v_pk_mul_f32 v[182:183], v[130:131], v[182:183]
	v_cvt_pk_bf16_f32 v238, v128, v134
	v_cvt_pk_bf16_f32 v237, v129, v135
	v_and_b32_sdwa v214, v132, v189 dst_sel:DWORD dst_unused:UNUSED_PAD src0_sel:WORD_1 src1_sel:DWORD
	v_mov_b32_e32 v129, v237
	v_mov_b32_e32 v128, v238
	global_store_dwordx2 v[184:185], v[128:129], off offset:2048
	v_add3_u32 v211, v132, v214, s89
	ds_read_b128 v[128:131], v208
	v_cvt_pk_bf16_f32 v240, v132, v182
	v_cvt_pk_bf16_f32 v239, v133, v183
	ds_read_b128 v[132:135], v208 offset:16
	s_waitcnt lgkmcnt(1)
	v_mov_b32_e32 v212, v129
	v_mov_b32_e32 v213, v130
	v_mov_b32_e32 v129, v131
	v_pk_add_f32 v[128:129], v[212:213], v[128:129]
	s_waitcnt lgkmcnt(0)
	v_mov_b32_e32 v130, v134
	v_mov_b32_e32 v131, v132
	v_mov_b32_e32 v132, v135
	v_pk_add_f32 v[130:131], v[130:131], v[132:133]
	v_add_f32_e32 v128, v128, v129
	v_add_f32_e32 v128, v128, v131
	v_add_f32_e32 v128, v130, v128
	v_fmamk_f32 v128, v128, 0x3b800000, v186
	v_mul_f32_e32 v129, 0x4f800000, v128
	v_cmp_gt_f32_e32 vcc, s91, v128
	v_and_b32_sdwa v215, v182, v189 dst_sel:DWORD dst_unused:UNUSED_PAD src0_sel:WORD_1 src1_sel:DWORD
	s_nop 0
	v_cndmask_b32_e32 v128, v128, v129, vcc
	v_sqrt_f32_e32 v129, v128
	s_nop 0
	v_add_u32_e32 v132, -1, v129
	v_fma_f32 v133, -v132, v129, v128
	v_cmp_ge_f32_e64 s[8:9], 0, v133
	v_add_u32_e32 v133, 1, v129
	s_nop 0
	v_cndmask_b32_e64 v132, v129, v132, s[8:9]
	v_fma_f32 v129, -v133, v129, v128
	v_cmp_lt_f32_e64 s[8:9], 0, v129
	s_nop 1
	v_cndmask_b32_e64 v129, v132, v133, s[8:9]
	v_mul_f32_e32 v132, 0x37800000, v129
	v_cndmask_b32_e32 v129, v129, v132, vcc
	v_cmp_class_f32_e32 vcc, v128, v187
	s_nop 1
	v_cndmask_b32_e32 v132, v129, v128, vcc
	v_div_scale_f32 v133, s[8:9], v132, v132, 1.0
	v_rcp_f32_e32 v134, v133
	v_mov_b32_e32 v129, v239
	v_mov_b32_e32 v128, v240
	global_store_dwordx2 v[184:185], v[128:129], off offset:2080
	v_fma_f32 v128, -v133, v134, 1.0
	v_fmac_f32_e32 v134, v128, v134
	v_div_scale_f32 v128, vcc, 1.0, v132, 1.0
	v_mul_f32_e32 v129, v128, v134
	v_fma_f32 v130, -v133, v129, v128
	v_fmac_f32_e32 v129, v130, v134
	v_fma_f32 v128, -v133, v129, v128
	v_div_fmas_f32 v128, v128, v134, v129
	v_div_fixup_f32 v128, v128, v132, 1.0
	v_pk_mul_f32 v[126:127], v[126:127], v[128:129] op_sel_hi:[1,0]
	v_pk_mul_f32 v[124:125], v[124:125], v[128:129] op_sel_hi:[1,0]
	v_pk_mul_f32 v[126:127], v[142:143], v[126:127]
	v_pk_mul_f32 v[124:125], v[140:141], v[124:125]
	v_lshlrev_b32_e32 v131, 16, v181
	v_lshlrev_b32_e32 v130, 16, v180
	v_mov_b32_e32 v132, v124
	v_mov_b32_e32 v133, v126
	v_pk_mul_f32 v[130:131], v[132:133], v[130:131]
	v_and_b32_e32 v133, 0xffff0000, v181
	v_and_b32_e32 v132, 0xffff0000, v180
	v_mov_b32_e32 v126, v125
	v_pk_mul_f32 v[124:125], v[126:127], v[132:133]
	v_and_b32_sdwa v129, v125, v189 dst_sel:DWORD dst_unused:UNUSED_PAD src0_sel:WORD_1 src1_sel:DWORD
	v_cvt_pk_bf16_f32 v242, v130, v124
	v_cvt_pk_bf16_f32 v241, v131, v125
	v_add_co_u32_e32 v130, vcc, s92, v184
	v_pk_mul_f32 v[122:123], v[122:123], v[128:129] op_sel_hi:[1,0]
	v_pk_mul_f32 v[120:121], v[120:121], v[128:129] op_sel_hi:[1,0]
	v_mov_b32_e32 v125, v241
	v_mov_b32_e32 v124, v242
	v_addc_co_u32_e32 v131, vcc, 0, v185, vcc
	v_pk_mul_f32 v[120:121], v[136:137], v[120:121]
	v_pk_mul_f32 v[122:123], v[138:139], v[122:123]
	global_store_dwordx2 v[130:131], v[124:125], off offset:2048
	v_lshlrev_b32_e32 v125, 16, v179
	v_lshlrev_b32_e32 v124, 16, v178
	v_mov_b32_e32 v126, v120
	v_mov_b32_e32 v127, v122
	v_pk_mul_f32 v[124:125], v[126:127], v[124:125]
	v_and_b32_e32 v127, 0xffff0000, v179
	v_and_b32_e32 v126, 0xffff0000, v178
	v_mov_b32_e32 v122, v121
	v_pk_mul_f32 v[128:129], v[122:123], v[126:127]
	ds_read_b128 v[120:123], v209
	v_cvt_pk_bf16_f32 v244, v124, v128
	v_cvt_pk_bf16_f32 v243, v125, v129
	ds_read_b128 v[124:127], v209 offset:16
	s_waitcnt lgkmcnt(1)
; #define LAS __attribute__((address_space(3)))
; __device__ __forceinline__ float bflo(unsigned w) { return __uint_as_float(w << 16); }
; __device__ __forceinline__ float bfhi(unsigned w) { return __uint_as_float(w & 0xffff0000u); }
; __device__ __forceinline__ unsigned pk2(float lo, float hi) { return f2bf(lo) | (f2bf(hi) << 16); }
; template <bool FULL>
; __device__ __forceinline__ void gla_pass(const Params& P, LAS unsigned char* lds, f32x4 (&S)[8][2], int bh, int c0, int L, bool dry) {
;     ...
;         if (FULL) {
;             f32x4 gn[2];
; #pragma unroll
;             for (int vt = 0; vt < 2; ++vt) gn[vt] = *(const f32x4*)(P.gla_norm_g + 32 * w + 4 * g + 16 * vt);
; #pragma unroll
;             for (int tt = 0; tt < 4; ++tt) {
;                 const int t = 16 * tt + fr;
;                 const f32x4 r0 = *(const LAS f32x4*)(red + t * 8), r1 = *(const LAS f32x4*)(red + t * 8 + 4);
;                 const float rstd = 1.0f / sqrtf(((r0[0] + r0[1]) + (r0[2] + r0[3]) + (r1[0] + r1[1]) + (r1[2] + r1[3])) * (1.0f / 256.0f) + RMS_EPS);
; #pragma unroll
;                 for (int vt = 0; vt < 2; ++vt) {
;                     bf16_t* op = (bf16_t*)P.out + (row0 + t) * 2048 + 1024 + h * 256 + 32 * w + 16 * vt + 4 * g;
;                     const u32x2 z = zb[vt][tt]; const f32x4 ov = o[vt][tt] * rstd * gn[vt];
;                     u32x2 r; r.x = pk2(ov[0] * bflo(z.x), ov[1] * bfhi(z.x)); r.y = pk2(ov[2] * bflo(z.y), ov[3] * bfhi(z.y));
;                     if (!dry) *(u32x2*)op = r;
;                 }
;             }
	v_mov_b32_e32 v132, v121
	v_mov_b32_e32 v133, v122
	v_mov_b32_e32 v121, v123
	v_pk_add_f32 v[120:121], v[132:133], v[120:121]
	s_waitcnt lgkmcnt(0)
	v_mov_b32_e32 v122, v126
	v_mov_b32_e32 v123, v124
	v_mov_b32_e32 v124, v127
	v_pk_add_f32 v[122:123], v[122:123], v[124:125]
	v_add_f32_e32 v120, v120, v121
	v_add_f32_e32 v120, v120, v123
	v_add_f32_e32 v120, v122, v120
	v_fmamk_f32 v120, v120, 0x3b800000, v186
	v_mul_f32_e32 v121, 0x4f800000, v120
	v_cmp_gt_f32_e32 vcc, s91, v120
	s_nop 1
	v_cndmask_b32_e32 v120, v120, v121, vcc
	v_sqrt_f32_e32 v121, v120
	s_nop 0
	v_add_u32_e32 v124, -1, v121
	v_fma_f32 v125, -v124, v121, v120
	v_cmp_ge_f32_e64 s[8:9], 0, v125
	v_add_u32_e32 v125, 1, v121
	s_nop 0
	v_cndmask_b32_e64 v124, v121, v124, s[8:9]
	v_fma_f32 v121, -v125, v121, v120
	v_cmp_lt_f32_e64 s[8:9], 0, v121
	s_nop 1
	v_cndmask_b32_e64 v121, v124, v125, s[8:9]
	v_mul_f32_e32 v124, 0x37800000, v121
	v_cndmask_b32_e32 v121, v121, v124, vcc
	v_cmp_class_f32_e32 vcc, v120, v187
	s_nop 1
	v_cndmask_b32_e32 v124, v121, v120, vcc
	v_div_scale_f32 v125, s[8:9], v124, v124, 1.0
	v_rcp_f32_e32 v126, v125
	v_mov_b32_e32 v121, v243
	v_mov_b32_e32 v120, v244
	global_store_dwordx2 v[130:131], v[120:121], off offset:2080
	v_fma_f32 v120, -v125, v126, 1.0
	v_fmac_f32_e32 v126, v120, v126
	v_div_scale_f32 v120, vcc, 1.0, v124, 1.0
	v_mul_f32_e32 v121, v120, v126
	v_fma_f32 v122, -v125, v121, v120
	v_fmac_f32_e32 v121, v122, v126
	v_fma_f32 v120, -v125, v121, v120
	v_div_fmas_f32 v120, v120, v126, v121
	v_div_fixup_f32 v120, v120, v124, 1.0
	v_pk_mul_f32 v[110:111], v[110:111], v[120:121] op_sel_hi:[1,0]
	v_pk_mul_f32 v[108:109], v[108:109], v[120:121] op_sel_hi:[1,0]
	v_pk_mul_f32 v[110:111], v[142:143], v[110:111]
	v_pk_mul_f32 v[108:109], v[140:141], v[108:109]
	v_lshlrev_b32_e32 v123, 16, v151
	v_lshlrev_b32_e32 v122, 16, v150
	v_mov_b32_e32 v124, v108
	v_mov_b32_e32 v125, v110
	v_pk_mul_f32 v[122:123], v[124:125], v[122:123]
	v_and_b32_e32 v125, 0xffff0000, v151
	v_and_b32_e32 v124, 0xffff0000, v150
	v_mov_b32_e32 v110, v109
	v_pk_mul_f32 v[108:109], v[110:111], v[124:125]
	v_and_b32_sdwa v121, v109, v189 dst_sel:DWORD dst_unused:UNUSED_PAD src0_sel:WORD_1 src1_sel:DWORD
	v_cvt_pk_bf16_f32 v246, v122, v108
	v_cvt_pk_bf16_f32 v245, v123, v109
	v_add_co_u32_e32 v122, vcc, s93, v184
	v_pk_mul_f32 v[106:107], v[106:107], v[120:121] op_sel_hi:[1,0]
	v_pk_mul_f32 v[104:105], v[104:105], v[120:121] op_sel_hi:[1,0]
	v_mov_b32_e32 v109, v245
	v_mov_b32_e32 v108, v246
	v_addc_co_u32_e32 v123, vcc, 0, v185, vcc
	v_pk_mul_f32 v[104:105], v[136:137], v[104:105]
	v_pk_mul_f32 v[106:107], v[138:139], v[106:107]
	global_store_dwordx2 v[122:123], v[108:109], off offset:2048
	v_lshlrev_b32_e32 v109, 16, v149
	v_lshlrev_b32_e32 v108, 16, v148
	v_mov_b32_e32 v110, v104
	v_mov_b32_e32 v111, v106
	v_pk_mul_f32 v[108:109], v[110:111], v[108:109]
	v_and_b32_e32 v111, 0xffff0000, v149
	v_and_b32_e32 v110, 0xffff0000, v148
	v_mov_b32_e32 v106, v105
	v_pk_mul_f32 v[120:121], v[106:107], v[110:111]
	ds_read_b128 v[104:107], v210
	v_cvt_pk_bf16_f32 v248, v108, v120
	v_cvt_pk_bf16_f32 v247, v109, v121
	ds_read_b128 v[108:111], v210 offset:16
	s_waitcnt lgkmcnt(1)
	v_mov_b32_e32 v124, v105
	v_mov_b32_e32 v125, v106
	v_mov_b32_e32 v105, v107
	v_pk_add_f32 v[104:105], v[124:125], v[104:105]
	s_waitcnt lgkmcnt(0)
	v_mov_b32_e32 v106, v110
	v_mov_b32_e32 v107, v108
	v_mov_b32_e32 v108, v111
	v_pk_add_f32 v[106:107], v[106:107], v[108:109]
	v_add_f32_e32 v104, v104, v105
	v_add_f32_e32 v104, v104, v107
	v_add_f32_e32 v104, v106, v104
	v_fmamk_f32 v104, v104, 0x3b800000, v186
	v_mul_f32_e32 v105, 0x4f800000, v104
	v_cmp_gt_f32_e32 vcc, s91, v104
	s_nop 1
	v_cndmask_b32_e32 v104, v104, v105, vcc
	v_sqrt_f32_e32 v105, v104
	v_lshlrev_b32_e32 v111, 16, v147
	v_add_u32_e32 v108, -1, v105
	v_fma_f32 v109, -v108, v105, v104
	v_cmp_ge_f32_e64 s[8:9], 0, v109
	v_add_u32_e32 v109, 1, v105
	s_nop 0
	v_cndmask_b32_e64 v108, v105, v108, s[8:9]
	v_fma_f32 v105, -v109, v105, v104
	v_cmp_lt_f32_e64 s[8:9], 0, v105
	s_nop 1
	v_cndmask_b32_e64 v105, v108, v109, s[8:9]
	v_mul_f32_e32 v108, 0x37800000, v105
	v_cndmask_b32_e32 v105, v105, v108, vcc
	v_cmp_class_f32_e32 vcc, v104, v187
	s_nop 1
	v_cndmask_b32_e32 v108, v105, v104, vcc
	v_div_scale_f32 v109, s[8:9], v108, v108, 1.0
	v_rcp_f32_e32 v110, v109
	v_mov_b32_e32 v105, v247
	v_mov_b32_e32 v104, v248
	global_store_dwordx2 v[122:123], v[104:105], off offset:2080
	v_fma_f32 v104, -v109, v110, 1.0
	v_fmac_f32_e32 v110, v104, v110
	v_div_scale_f32 v104, vcc, 1.0, v108, 1.0
	v_mul_f32_e32 v105, v104, v110
	v_fma_f32 v106, -v109, v105, v104
	v_fmac_f32_e32 v105, v106, v110
	v_fma_f32 v104, -v109, v105, v104
	v_div_fmas_f32 v104, v104, v110, v105
	v_div_fixup_f32 v104, v104, v108, 1.0
	v_pk_mul_f32 v[106:107], v[118:119], v[104:105] op_sel_hi:[1,0]
	v_pk_mul_f32 v[108:109], v[116:117], v[104:105] op_sel_hi:[1,0]
	v_pk_mul_f32 v[106:107], v[142:143], v[106:107]
	v_pk_mul_f32 v[108:109], v[140:141], v[108:109]
	v_lshlrev_b32_e32 v110, 16, v146
	v_mov_b32_e32 v116, v108
	v_mov_b32_e32 v117, v106
	v_pk_mul_f32 v[110:111], v[116:117], v[110:111]
	v_and_b32_e32 v117, 0xffff0000, v147
	v_and_b32_e32 v116, 0xffff0000, v146
	v_mov_b32_e32 v106, v109
	v_pk_mul_f32 v[106:107], v[106:107], v[116:117]
	v_cvt_pk_bf16_f32 v249, v110, v106
	v_and_b32_sdwa v105, v111, v189 dst_sel:DWORD dst_unused:UNUSED_PAD src0_sel:WORD_1 src1_sel:DWORD
	v_cvt_pk_bf16_f32 v250, v111, v107
	v_add3_u32 v105, v111, v105, s89
	v_mov_b32_e32 v106, v249
	v_add_co_u32_e32 v108, vcc, s94, v184
	v_mov_b32_e32 v107, v250
	s_nop 0
	v_addc_co_u32_e32 v109, vcc, 0, v185, vcc
	global_store_dwordx2 v[108:109], v[106:107], off offset:2048
	v_pk_mul_f32 v[106:107], v[114:115], v[104:105] op_sel_hi:[1,0]
	v_pk_mul_f32 v[104:105], v[112:113], v[104:105] op_sel_hi:[1,0]
	v_pk_mul_f32 v[106:107], v[138:139], v[106:107]
	v_pk_mul_f32 v[104:105], v[136:137], v[104:105]
	v_lshlrev_b32_e32 v111, 16, v145
	v_lshlrev_b32_e32 v110, 16, v144
	v_mov_b32_e32 v112, v104
	v_mov_b32_e32 v113, v106
	v_pk_mul_f32 v[110:111], v[112:113], v[110:111]
	v_and_b32_e32 v113, 0xffff0000, v145
	v_and_b32_e32 v112, 0xffff0000, v144
	v_mov_b32_e32 v106, v105
	v_pk_mul_f32 v[104:105], v[106:107], v[112:113]
	v_cvt_pk_bf16_f32 v252, v110, v104
	v_cvt_pk_bf16_f32 v251, v111, v105
	v_mov_b32_e32 v105, v251
	v_mov_b32_e32 v104, v252
	global_store_dwordx2 v[108:109], v[104:105], off offset:2080
	s_barrier
	s_cbranch_scc0 .LBB0_557

; #define LAS __attribute__((address_space(3)))
; __device__ __forceinline__ unsigned pk2(float lo, float hi) { return f2bf(lo) | (f2bf(hi) << 16); }
; __device__ __forceinline__ void gla_write_st(LAS unsigned char* Lst, const f32x4 (&S)[8][2], int w, int fr, int g) {
; #pragma unroll
;     for (int kt = 0; kt < 8; ++kt)
; #pragma unroll
;         for (int vt = 0; vt < 2; ++vt) { u32x2 sv; sv.x = pk2(S[kt][vt][0], S[kt][vt][1]); sv.y = pk2(S[kt][vt][2], S[kt][vt][3]);
;             *(LAS u32x2*)(Lst + (32 * w + 16 * vt + fr) * gla::ST_P + (16 * kt + 4 * g) * 2) = sv; }
; }
.LBB0_577:
	s_or_b64 exec, exec, s[34:35]
	s_waitcnt lgkmcnt(0)
	v_cvt_pk_bf16_f32 v136, v100, v101
	v_cvt_pk_bf16_f32 v137, v102, v103
	v_cvt_pk_bf16_f32 v138, v96, v97
	v_cvt_pk_bf16_f32 v139, v98, v99
	v_cvt_pk_bf16_f32 v140, v92, v93
	v_cvt_pk_bf16_f32 v141, v94, v95
	s_barrier
	ds_write2_b64 v207, v[136:137], v[140:141] offset1:4
	v_cvt_pk_bf16_f32 v136, v80, v81
	v_cvt_pk_bf16_f32 v137, v82, v83
	v_add_u32_e32 v142, 0x1000, v207
	ds_write2_b64 v142, v[138:139], v[136:137] offset0:32 offset1:36
	v_cvt_pk_bf16_f32 v136, v72, v73
	v_cvt_pk_bf16_f32 v137, v74, v75
	v_cvt_pk_bf16_f32 v138, v68, v69
	v_cvt_pk_bf16_f32 v139, v70, v71
	v_cvt_pk_bf16_f32 v140, v76, v77
	v_cvt_pk_bf16_f32 v141, v78, v79
	ds_write2_b64 v207, v[136:137], v[140:141] offset0:8 offset1:12
	v_cvt_pk_bf16_f32 v136, v88, v89
	v_cvt_pk_bf16_f32 v137, v90, v91
	ds_write2_b64 v142, v[138:139], v[136:137] offset0:40 offset1:44
	v_cvt_pk_bf16_f32 v136, v84, v85
	v_cvt_pk_bf16_f32 v137, v86, v87
	v_cvt_pk_bf16_f32 v138, v56, v57
	v_cvt_pk_bf16_f32 v139, v58, v59
	v_cvt_pk_bf16_f32 v140, v48, v49
	v_cvt_pk_bf16_f32 v141, v50, v51
	ds_write2_b64 v207, v[136:137], v[140:141] offset0:16 offset1:20
	v_cvt_pk_bf16_f32 v136, v64, v65
	v_cvt_pk_bf16_f32 v137, v66, v67
	ds_write2_b64 v142, v[138:139], v[136:137] offset0:48 offset1:52
	v_cvt_pk_bf16_f32 v136, v60, v61
	v_cvt_pk_bf16_f32 v137, v62, v63
	v_cvt_pk_bf16_f32 v138, v52, v53
	v_cvt_pk_bf16_f32 v139, v54, v55
	v_cvt_pk_bf16_f32 v140, v44, v45
	v_cvt_pk_bf16_f32 v141, v46, v47
	ds_write2_b64 v207, v[136:137], v[140:141] offset0:24 offset1:28
	v_cvt_pk_bf16_f32 v136, v40, v41
	v_cvt_pk_bf16_f32 v137, v42, v43
	s_and_b64 vcc, exec, s[8:9]
	ds_write2_b64 v142, v[138:139], v[136:137] offset0:56 offset1:60
	s_cbranch_vccz .LBB0_564
	s_waitcnt vmcnt(16)
	ds_write_b128 v190, v[0:3]
	s_waitcnt vmcnt(15)
	ds_write_b128 v191, v[4:7] offset:18432
	s_waitcnt vmcnt(14)
	ds_write_b128 v190, v[12:15] offset:9216
	s_waitcnt vmcnt(13)
	ds_write_b128 v191, v[8:11] offset:27136
	s_waitcnt vmcnt(12)
	ds_write_b128 v192, v[16:19] offset:35840
	s_waitcnt vmcnt(11)
	ds_write_b128 v192, v[20:23] offset:44544
	s_waitcnt vmcnt(10)
	ds_write_b128 v192, v[24:27] offset:53248
	s_waitcnt vmcnt(9)
	ds_write_b128 v192, v[32:35] offset:61952
	s_waitcnt vmcnt(8)
	ds_write_b128 v193, v[36:39]
	s_and_saveexec_b64 s[8:9], s[4:5]
	s_cbranch_execz .LBB0_563
	v_add_u32_e32 v136, 0x25000, v196
	ds_write_b128 v136, v[28:31]
	s_branch .LBB0_563

; #define LAS __attribute__((address_space(3)))
; __device__ __forceinline__ float bflo(unsigned w) { return __uint_as_float(w << 16); }
; __device__ __forceinline__ float bfhi(unsigned w) { return __uint_as_float(w & 0xffff0000u); }
; __device__ __forceinline__ unsigned pk2(float lo, float hi) { return f2bf(lo) | (f2bf(hi) << 16); }
; __device__ __forceinline__ void phase_mixer_a(const Params& P, LAS unsigned char* lds, int ustart, int ustride, bool dry) {
;     ...
;             u32x2 pv[8]; float bsv[8];
; #pragma unroll
;             for (int mt = 0; mt < 8; ++mt) { const int t = 16 * mt + (lane & 15);
;                 pv[mt] = *(const u32x2*)(PJ + T_P + (size_t)(r0 + t) * 1024 + h * 128 + 16 * w + 4 * g4); bsv[mt] = P.b_spatial[h * 128 + t]; }
;             f32x4 acc[8];
; #pragma unroll
;             for (int mt = 0; mt < 8; ++mt) acc[mt] = (f32x4){0.f, 0.f, 0.f, 0.f};
; #pragma unroll
;             for (int ks = 0; ks < 4; ++ks) {
;                 const unsigned a0 = (unsigned)((32 * ks + 8 * g4 + q) * VN_P + 32 * w + 8 * p);
;                 const s16x4 lo = __builtin_amdgcn_ds_read_tr16_b64_v4i16((LAS s16x4*)(lds + a0)), hi = __builtin_amdgcn_ds_read_tr16_b64_v4i16((LAS s16x4*)(lds + a0 + 4 * VN_P));
;                 const bf16x8 vf = (bf16x8){lo[0], lo[1], lo[2], lo[3], hi[0], hi[1], hi[2], hi[3]};
; #pragma unroll
;                 for (int mt = 2 * ks; mt < 8; ++mt) {
;                     const bf16x8 wf = *(const LAS bf16x8*)(lds + W_OFF + (16 * mt + (lane & 15)) * W_P + (32 * ks + 8 * g4) * 2);
;                     acc[mt] = __builtin_amdgcn_mfma_f32_16x16x32_bf16(vf, wf, acc[mt], 0, 0, 0);
;                 }
;             }
; #pragma unroll
;             for (int mt = 0; mt < 8; ++mt) {
;                 const int t = 16 * mt + (lane & 15); const float bs = bsv[mt];
;                 u32x2 o; o.x = pk2(bflo(pv[mt].x) * (acc[mt][0] + bs), bfhi(pv[mt].x) * (acc[mt][1] + bs)); o.y = pk2(bflo(pv[mt].y) * (acc[mt][2] + bs), bfhi(pv[mt].y) * (acc[mt][3] + bs));
;                 if (!dry) *(u32x2*)((bf16_t*)P.out + (size_t)(r0 + t) * 2048 + h * 128 + 16 * w + 4 * g4) = o;
;             }
.LBB0_594:
	ds_read_b64_tr_b16 v[16:17], v171
	ds_read_b64_tr_b16 v[18:19], v171 offset:1152
	v_add_u32_e32 v37, v150, v151
	ds_read_b128 v[20:23], v37 offset:36864
	ds_read_b128 v[24:27], v37 offset:41216
	v_lshl_add_u64 v[136:137], v[102:103], 0, s[12:13]
	v_lshl_add_u64 v[212:213], v[68:69], 0, s[6:7]
	s_waitcnt lgkmcnt(1)
	v_mfma_f32_16x16x32_bf16 v[28:31], v[16:19], v[20:23], 0
	ds_read_b128 v[20:23], v37 offset:45568
	global_load_dwordx2 v[192:193], v[136:137], off
	ds_read_b128 v[136:139], v37 offset:49920
	global_load_dword v214, v[212:213], off
	ds_read_b128 v[176:179], v37 offset:54272
	ds_read_b128 v[180:183], v37 offset:58624
	v_lshl_add_u64 v[200:201], v[104:105], 0, s[12:13]
	v_add_u32_e32 v39, v150, v152
	ds_read_b128 v[184:187], v37 offset:62976
	ds_read_b64_tr_b16 v[188:189], v172
	ds_read_b64_tr_b16 v[190:191], v172 offset:1152
	ds_read_b128 v[196:199], v39 offset:62976
	v_add_u32_e32 v37, v153, v151
	global_load_dwordx2 v[216:217], v[200:201], off
	ds_read_b128 v[200:203], v37 offset:45568
	s_waitcnt lgkmcnt(8)
	v_mfma_f32_16x16x32_bf16 v[20:23], v[16:19], v[20:23], 0
	global_load_dword v218, v[212:213], off offset:64
	v_add_u32_e32 v39, v153, v152
	v_lshl_add_u64 v[208:209], v[106:107], 0, s[12:13]
	v_mfma_f32_16x16x32_bf16 v[24:27], v[16:19], v[24:27], 0
	v_lshl_add_u64 v[210:211], v[108:109], 0, s[12:13]
	v_lshl_add_u64 v[220:221], v[110:111], 0, s[12:13]
	v_lshl_add_u64 v[222:223], v[112:113], 0, s[12:13]
	s_waitcnt lgkmcnt(7)
	v_mfma_f32_16x16x32_bf16 v[136:139], v[16:19], v[136:139], 0
	v_lshl_add_u64 v[224:225], v[114:115], 0, s[12:13]
	v_add_u32_e32 v41, v155, v152
	v_lshl_add_u64 v[226:227], v[116:117], 0, s[12:13]
	s_waitcnt lgkmcnt(6)
	v_mfma_f32_16x16x32_bf16 v[176:179], v[16:19], v[176:179], 0
	v_lshl_add_u64 v[134:135], v[134:135], 0, s[10:11]
	v_lshl_add_u64 v[132:133], v[132:133], 0, s[10:11]
	v_lshl_add_u64 v[130:131], v[130:131], 0, s[10:11]
	s_waitcnt lgkmcnt(5)
	v_mfma_f32_16x16x32_bf16 v[180:183], v[16:19], v[180:183], 0
	v_lshl_add_u64 v[128:129], v[128:129], 0, s[10:11]
	s_waitcnt lgkmcnt(4)
	v_mfma_f32_16x16x32_bf16 v[184:187], v[16:19], v[184:187], 0
	s_waitcnt lgkmcnt(1)
	v_mfma_f32_16x16x32_bf16 v[16:19], v[16:19], v[196:199], 0
	ds_read_b128 v[196:199], v37 offset:49920
	s_waitcnt lgkmcnt(1)
	v_mfma_f32_16x16x32_bf16 v[200:203], v[188:191], v[200:203], v[20:23]
	s_nop 2
	ds_read_b128 v[20:23], v37 offset:54272
	s_waitcnt lgkmcnt(1)
	v_mfma_f32_16x16x32_bf16 v[136:139], v[188:191], v[196:199], v[136:139]
	ds_read_b128 v[196:199], v37 offset:58624
	s_waitcnt lgkmcnt(1)
	v_mfma_f32_16x16x32_bf16 v[20:23], v[188:191], v[20:23], v[176:179]
	s_nop 2
	ds_read_b128 v[176:179], v37 offset:62976
	s_waitcnt lgkmcnt(1)
	v_mfma_f32_16x16x32_bf16 v[180:183], v[188:191], v[196:199], v[180:183]
	ds_read_b64_tr_b16 v[196:197], v173
	ds_read_b64_tr_b16 v[198:199], v173 offset:1152
	ds_read_b128 v[204:207], v39 offset:62976
	v_add_u32_e32 v37, v154, v151
	global_load_dwordx2 v[228:229], v[208:209], off
	s_waitcnt lgkmcnt(3)
	v_mfma_f32_16x16x32_bf16 v[176:179], v[188:191], v[176:179], v[184:187]
	global_load_dword v230, v[212:213], off offset:128
	v_add_u32_e32 v39, v154, v152
	s_nop 0
	ds_read_b128 v[184:187], v37 offset:54272
	s_waitcnt lgkmcnt(1)
	v_mfma_f32_16x16x32_bf16 v[16:19], v[188:191], v[204:207], v[16:19]
	ds_read_b128 v[188:191], v37 offset:58624
	s_waitcnt lgkmcnt(1)
	v_mfma_f32_16x16x32_bf16 v[184:187], v[196:199], v[184:187], v[20:23]
	ds_read_b64_tr_b16 v[204:205], v174
	ds_read_b64_tr_b16 v[206:207], v174 offset:1152
	s_nop 0
	ds_read_b128 v[20:23], v37 offset:62976
	v_add_u32_e32 v37, v155, v151
	s_waitcnt lgkmcnt(3)
	v_mfma_f32_16x16x32_bf16 v[180:183], v[196:199], v[188:191], v[180:183]
	ds_read_b128 v[188:191], v39 offset:62976
	global_load_dwordx2 v[232:233], v[210:211], off
	s_nop 0
	global_load_dwordx2 v[220:221], v[220:221], off
	ds_read_b128 v[208:211], v37 offset:62976
	s_waitcnt lgkmcnt(2)
	v_mfma_f32_16x16x32_bf16 v[176:179], v[196:199], v[20:23], v[176:179]
	s_waitcnt lgkmcnt(1)
	v_mfma_f32_16x16x32_bf16 v[16:19], v[196:199], v[188:191], v[16:19]
	global_load_dwordx2 v[196:197], v[222:223], off
	global_load_dwordx2 v[198:199], v[224:225], off
	global_load_dwordx2 v[20:21], v[226:227], off
	ds_read_b128 v[188:191], v41 offset:62976
	s_waitcnt lgkmcnt(1)
	v_mfma_f32_16x16x32_bf16 v[176:179], v[204:207], v[208:211], v[176:179]
	global_load_dword v208, v[212:213], off offset:192
	global_load_dword v210, v[212:213], off offset:256
	global_load_dword v222, v[212:213], off offset:320
	global_load_dword v224, v[212:213], off offset:384
	global_load_dword v22, v[212:213], off offset:448
	s_waitcnt lgkmcnt(0)
	v_mfma_f32_16x16x32_bf16 v[16:19], v[204:207], v[188:191], v[16:19]
	v_mov_b32_e32 v190, v28
	v_mov_b32_e32 v191, v30
	s_waitcnt vmcnt(15)
	v_lshlrev_b32_e32 v189, 16, v193
	v_lshlrev_b32_e32 v188, 16, v192
	s_waitcnt vmcnt(14)
	v_pk_add_f32 v[190:191], v[214:215], v[190:191] op_sel_hi:[0,1]
	v_mov_b32_e32 v30, v29
	v_pk_mul_f32 v[188:189], v[190:191], v[188:189]
	v_and_b32_e32 v191, 0xffff0000, v193
	v_and_b32_e32 v190, 0xffff0000, v192
	v_pk_add_f32 v[28:29], v[214:215], v[30:31] op_sel_hi:[0,1]
	v_pk_mul_f32 v[28:29], v[28:29], v[190:191]
	v_cvt_pk_bf16_f32 v253, v189, v29
	v_cvt_pk_bf16_f32 v254, v188, v28
	v_mov_b32_e32 v29, v253
	v_mov_b32_e32 v28, v254
	v_lshl_add_u64 v[30:31], v[118:119], 0, s[12:13]
	global_store_dwordx2 v[30:31], v[28:29], off
	v_mov_b32_e32 v30, v24
	v_mov_b32_e32 v31, v26
	s_waitcnt vmcnt(14)
	v_lshlrev_b32_e32 v29, 16, v217
	v_lshlrev_b32_e32 v28, 16, v216
	s_waitcnt vmcnt(13)
; __device__ __forceinline__ float bflo(unsigned w) { return __uint_as_float(w << 16); }
; __device__ __forceinline__ float bfhi(unsigned w) { return __uint_as_float(w & 0xffff0000u); }
; __device__ __forceinline__ unsigned pk2(float lo, float hi) { return f2bf(lo) | (f2bf(hi) << 16); }
; __device__ __forceinline__ void phase_mixer_a(const Params& P, LAS unsigned char* lds, int ustart, int ustride, bool dry) {
;     ...
; #pragma unroll
;             for (int mt = 0; mt < 8; ++mt) {
;                 const int t = 16 * mt + (lane & 15); const float bs = bsv[mt];
;                 u32x2 o; o.x = pk2(bflo(pv[mt].x) * (acc[mt][0] + bs), bfhi(pv[mt].x) * (acc[mt][1] + bs)); o.y = pk2(bflo(pv[mt].y) * (acc[mt][2] + bs), bfhi(pv[mt].y) * (acc[mt][3] + bs));
;                 if (!dry) *(u32x2*)((bf16_t*)P.out + (size_t)(r0 + t) * 2048 + h * 128 + 16 * w + 4 * g4) = o;
;             }
;             __syncthreads();
	v_pk_add_f32 v[30:31], v[218:219], v[30:31] op_sel_hi:[0,1]
	v_mov_b32_e32 v26, v25
	v_pk_mul_f32 v[28:29], v[30:31], v[28:29]
	v_and_b32_e32 v31, 0xffff0000, v217
	v_and_b32_e32 v30, 0xffff0000, v216
	v_pk_add_f32 v[24:25], v[218:219], v[26:27] op_sel_hi:[0,1]
	v_pk_mul_f32 v[24:25], v[24:25], v[30:31]
	v_cvt_pk_bf16_f32 v237, v28, v24
	v_cvt_pk_bf16_f32 v255, v29, v25
	v_mov_b32_e32 v25, v255
	v_mov_b32_e32 v24, v237
	v_lshl_add_u64 v[26:27], v[120:121], 0, s[12:13]
	global_store_dwordx2 v[26:27], v[24:25], off
	v_mov_b32_e32 v26, v200
	v_mov_b32_e32 v27, v202
	s_waitcnt vmcnt(13)
	v_lshlrev_b32_e32 v25, 16, v229
	v_lshlrev_b32_e32 v24, 16, v228
	s_waitcnt vmcnt(12)
	v_pk_add_f32 v[26:27], v[230:231], v[26:27] op_sel_hi:[0,1]
	v_mov_b32_e32 v202, v201
	v_pk_mul_f32 v[24:25], v[26:27], v[24:25]
	v_and_b32_e32 v27, 0xffff0000, v229
	v_and_b32_e32 v26, 0xffff0000, v228
	v_pk_add_f32 v[28:29], v[230:231], v[202:203] op_sel_hi:[0,1]
	v_pk_mul_f32 v[26:27], v[28:29], v[26:27]
	v_cvt_pk_bf16_f32 v239, v24, v26
	v_cvt_pk_bf16_f32 v238, v25, v27
	v_mov_b32_e32 v25, v238
	v_mov_b32_e32 v24, v239
	v_lshl_add_u64 v[26:27], v[122:123], 0, s[12:13]
	global_store_dwordx2 v[26:27], v[24:25], off
	v_mov_b32_e32 v26, v136
	v_mov_b32_e32 v27, v138
	s_waitcnt vmcnt(12)
	v_lshlrev_b32_e32 v25, 16, v233
	v_lshlrev_b32_e32 v24, 16, v232
	s_waitcnt vmcnt(7)
	v_pk_add_f32 v[26:27], v[208:209], v[26:27] op_sel_hi:[0,1]
	v_mov_b32_e32 v138, v137
	v_pk_mul_f32 v[24:25], v[26:27], v[24:25]
	v_and_b32_e32 v27, 0xffff0000, v233
	v_and_b32_e32 v26, 0xffff0000, v232
	v_pk_add_f32 v[28:29], v[208:209], v[138:139] op_sel_hi:[0,1]
	v_pk_mul_f32 v[26:27], v[28:29], v[26:27]
	v_cvt_pk_bf16_f32 v241, v24, v26
	v_cvt_pk_bf16_f32 v240, v25, v27
	v_mov_b32_e32 v25, v240
	v_mov_b32_e32 v24, v241
	v_lshl_add_u64 v[26:27], v[124:125], 0, s[12:13]
	global_store_dwordx2 v[26:27], v[24:25], off
	v_mov_b32_e32 v26, v184
	v_mov_b32_e32 v27, v186
	v_lshlrev_b32_e32 v25, 16, v221
	v_lshlrev_b32_e32 v24, 16, v220
	s_waitcnt vmcnt(7)
	v_pk_add_f32 v[26:27], v[210:211], v[26:27] op_sel_hi:[0,1]
	v_mov_b32_e32 v186, v185
	v_pk_mul_f32 v[24:25], v[26:27], v[24:25]
	v_and_b32_e32 v27, 0xffff0000, v221
	v_and_b32_e32 v26, 0xffff0000, v220
	v_pk_add_f32 v[28:29], v[210:211], v[186:187] op_sel_hi:[0,1]
	v_pk_mul_f32 v[26:27], v[28:29], v[26:27]
	v_cvt_pk_bf16_f32 v243, v24, v26
	v_cvt_pk_bf16_f32 v242, v25, v27
	v_mov_b32_e32 v25, v242
	v_mov_b32_e32 v24, v243
	v_lshl_add_u64 v[26:27], v[126:127], 0, s[12:13]
	global_store_dwordx2 v[26:27], v[24:25], off
	v_mov_b32_e32 v26, v180
	v_mov_b32_e32 v27, v182
	v_lshlrev_b32_e32 v25, 16, v197
	v_lshlrev_b32_e32 v24, 16, v196
	s_waitcnt vmcnt(7)
	v_pk_add_f32 v[26:27], v[222:223], v[26:27] op_sel_hi:[0,1]
	v_mov_b32_e32 v182, v181
	v_pk_mul_f32 v[24:25], v[26:27], v[24:25]
	v_and_b32_e32 v27, 0xffff0000, v197
	v_and_b32_e32 v26, 0xffff0000, v196
	v_pk_add_f32 v[28:29], v[222:223], v[182:183] op_sel_hi:[0,1]
	v_pk_mul_f32 v[26:27], v[28:29], v[26:27]
	v_cvt_pk_bf16_f32 v245, v24, v26
	v_cvt_pk_bf16_f32 v244, v25, v27
	v_mov_b32_e32 v25, v244
	v_mov_b32_e32 v24, v245
	v_lshl_add_u64 v[26:27], v[100:101], 0, s[12:13]
	global_store_dwordx2 v[26:27], v[24:25], off
	v_mov_b32_e32 v26, v176
	v_mov_b32_e32 v27, v178
	v_lshlrev_b32_e32 v25, 16, v199
	v_lshlrev_b32_e32 v24, 16, v198
	s_waitcnt vmcnt(7)
	v_pk_add_f32 v[26:27], v[224:225], v[26:27] op_sel_hi:[0,1]
	v_mov_b32_e32 v178, v177
	v_pk_mul_f32 v[24:25], v[26:27], v[24:25]
	v_and_b32_e32 v27, 0xffff0000, v199
	v_and_b32_e32 v26, 0xffff0000, v198
	v_pk_add_f32 v[28:29], v[224:225], v[178:179] op_sel_hi:[0,1]
	v_pk_mul_f32 v[26:27], v[28:29], v[26:27]
	v_and_b32_sdwa v23, v25, v175 dst_sel:DWORD dst_unused:UNUSED_PAD src0_sel:WORD_1 src1_sel:DWORD
	v_cvt_pk_bf16_f32 v247, v24, v26
	v_add3_u32 v23, v25, v23, s15
	v_cvt_pk_bf16_f32 v246, v25, v27
	v_mov_b32_e32 v25, v246
	v_mov_b32_e32 v24, v247
	v_lshl_add_u64 v[26:27], v[98:99], 0, s[12:13]
	global_store_dwordx2 v[26:27], v[24:25], off
	v_mov_b32_e32 v27, v18
	v_mov_b32_e32 v18, v17
	v_lshlrev_b32_e32 v25, 16, v21
	v_lshlrev_b32_e32 v24, 16, v20
	v_mov_b32_e32 v26, v16
	v_and_b32_e32 v21, 0xffff0000, v21
	v_and_b32_e32 v20, 0xffff0000, v20
	s_waitcnt vmcnt(7)
	v_pk_add_f32 v[16:17], v[22:23], v[18:19] op_sel_hi:[0,1]
	v_pk_add_f32 v[26:27], v[22:23], v[26:27] op_sel_hi:[0,1]
	v_pk_mul_f32 v[16:17], v[16:17], v[20:21]
	v_pk_mul_f32 v[24:25], v[26:27], v[24:25]
	v_cvt_pk_bf16_f32 v248, v25, v17
	v_cvt_pk_bf16_f32 v249, v24, v16
	v_mov_b32_e32 v17, v248
	v_mov_b32_e32 v16, v249
	v_lshl_add_u64 v[18:19], v[96:97], 0, s[12:13]
	s_add_u32 s12, s12, 0x100
	s_addc_u32 s13, s13, 0
	s_add_u32 s6, s6, 0x200
	s_addc_u32 s7, s7, 0
	s_cmpk_eq_i32 s12, 0x800
	global_store_dwordx2 v[18:19], v[16:17], off
	s_barrier
	s_cbranch_scc1 .LBB0_582
; #define LAS __attribute__((address_space(3)))
; __device__ __forceinline__ float bflo(unsigned w) { return __uint_as_float(w << 16); }
; __device__ __forceinline__ float bfhi(unsigned w) { return __uint_as_float(w & 0xffff0000u); }
; __device__ __forceinline__ unsigned pk2(float lo, float hi) { return f2bf(lo) | (f2bf(hi) << 16); }
; __device__ __forceinline__ void phase_mixer_a(const Params& P, LAS unsigned char* lds, int ustart, int ustride, bool dry) {
;     ...
;         for (int h = 0; h < 8; ++h) {
; #pragma unroll
;             for (int i = 0; i < 4; ++i) {
;                 const int item = tid + 512 * i, c8 = item & 15, s = item >> 4;
;                 const u32x4 gv = pgv[i];
;                 const float mean = stats[2 * s], rstd = stats[2 * s + 1];
;                 const f32x4 g0 = *(const f32x4*)(P.ln_v_g + h * 128 + c8 * 8), g1 = *(const f32x4*)(P.ln_v_g + h * 128 + c8 * 8 + 4);
;                 const f32x4 b0 = *(const f32x4*)(P.ln_v_b + h * 128 + c8 * 8), b1 = *(const f32x4*)(P.ln_v_b + h * 128 + c8 * 8 + 4);
;                 u32x4 o;
;                 o.x = pk2((bflo(gv.x) - mean) * rstd * g0[0] + b0[0], (bfhi(gv.x) - mean) * rstd * g0[1] + b0[1]);
;                 o.y = pk2((bflo(gv.y) - mean) * rstd * g0[2] + b0[2], (bfhi(gv.y) - mean) * rstd * g0[3] + b0[3]);
;                 o.z = pk2((bflo(gv.z) - mean) * rstd * g1[0] + b1[0], (bfhi(gv.z) - mean) * rstd * g1[1] + b1[1]);
;                 o.w = pk2((bflo(gv.w) - mean) * rstd * g1[2] + b1[2], (bfhi(gv.w) - mean) * rstd * g1[3] + b1[3]);
;                 *(LAS u32x4*)(lds + s * VN_P + c8 * 16) = o;
;                 *(LAS u32x4*)(lds + W_OFF + s * W_P + c8 * 16) = *(const u32x4*)(WsT + h * 16384 + item * 8);
;             }
;             __syncthreads();
.LBB0_595:
	v_lshl_add_u64 v[16:17], v[72:73], 0, s[6:7]
	global_load_dwordx4 v[24:27], v[16:17], off offset:-16
	v_lshl_add_u64 v[20:21], v[76:77], 0, s[6:7]
	global_load_dwordx4 v[28:31], v[20:21], off offset:-16
	s_nop 0
	global_load_dwordx4 v[16:19], v[16:17], off
	s_nop 0
	global_load_dwordx4 v[20:23], v[20:21], off
	s_nop 0
	global_load_dwordx4 v[176:179], v[134:135], off
	global_load_dwordx4 v[180:183], v[132:133], off
	ds_read_b64 v[136:137], v159
	s_waitcnt vmcnt(9)
	v_lshlrev_b32_e32 v139, 16, v1
	v_lshlrev_b32_e32 v138, 16, v0
	v_and_b32_e32 v185, 0xffff0000, v1
	v_and_b32_e32 v184, 0xffff0000, v0
	v_lshlrev_b32_e32 v187, 16, v3
	v_lshlrev_b32_e32 v186, 16, v2
	v_and_b32_e32 v189, 0xffff0000, v3
	v_and_b32_e32 v188, 0xffff0000, v2
	s_waitcnt lgkmcnt(0)
	v_pk_add_f32 v[138:139], v[138:139], v[136:137] op_sel_hi:[1,0] neg_lo:[0,1] neg_hi:[0,1]
	v_pk_add_f32 v[184:185], v[184:185], v[136:137] op_sel_hi:[1,0] neg_lo:[0,1] neg_hi:[0,1]
	v_pk_add_f32 v[186:187], v[186:187], v[136:137] op_sel_hi:[1,0] neg_lo:[0,1] neg_hi:[0,1]
	v_pk_add_f32 v[188:189], v[188:189], v[136:137] op_sel_hi:[1,0] neg_lo:[0,1] neg_hi:[0,1]
	v_pk_mul_f32 v[198:199], v[136:137], v[138:139] op_sel:[1,0]
	v_pk_mul_f32 v[184:185], v[136:137], v[184:185] op_sel:[1,0]
	v_pk_mul_f32 v[186:187], v[136:137], v[186:187] op_sel:[1,0]
	v_pk_mul_f32 v[188:189], v[136:137], v[188:189] op_sel:[1,0]
	s_waitcnt vmcnt(8)
	v_lshlrev_b32_e32 v191, 16, v5
	v_lshlrev_b32_e32 v190, 16, v4
	v_and_b32_e32 v193, 0xffff0000, v5
	v_and_b32_e32 v192, 0xffff0000, v4
	v_lshlrev_b32_e32 v197, 16, v7
	v_lshlrev_b32_e32 v196, 16, v6
	s_cmpk_lg_i32 s12, 0x700
	s_waitcnt vmcnt(4)
	v_mov_b32_e32 v138, v28
	v_mov_b32_e32 v136, v24
	v_mov_b32_e32 v137, v26
	v_mov_b32_e32 v139, v30
	v_mov_b32_e32 v26, v25
	v_mov_b32_e32 v30, v29
	s_waitcnt vmcnt(3)
	v_mov_b32_e32 v24, v16
	v_mov_b32_e32 v25, v18
	s_waitcnt vmcnt(2)
	v_mov_b32_e32 v28, v20
	v_mov_b32_e32 v29, v22
	v_mov_b32_e32 v18, v17
	v_mov_b32_e32 v22, v21
	v_pk_fma_f32 v[16:17], v[198:199], v[136:137], v[138:139]
	v_pk_fma_f32 v[20:21], v[184:185], v[26:27], v[30:31]
	v_pk_fma_f32 v[184:185], v[186:187], v[24:25], v[28:29]
	v_pk_fma_f32 v[186:187], v[188:189], v[18:19], v[22:23]
	v_cvt_pk_bf16_f32 v251, v16, v20
	v_cvt_pk_bf16_f32 v250, v17, v21
	v_cvt_pk_bf16_f32 v187, v185, v187
	v_cvt_pk_bf16_f32 v186, v184, v186
	v_mov_b32_e32 v185, v250
	v_mov_b32_e32 v184, v251
	ds_write_b128 v160, v[184:187]
	s_waitcnt vmcnt(1)
	ds_write_b128 v161, v[176:179] offset:36864
	ds_read_b64 v[16:17], v162
	global_load_dwordx4 v[176:179], v[130:131], off
	v_and_b32_e32 v21, 0xffff0000, v7
	v_and_b32_e32 v20, 0xffff0000, v6
	s_waitcnt lgkmcnt(0)
	v_pk_add_f32 v[184:185], v[190:191], v[16:17] op_sel_hi:[1,0] neg_lo:[0,1] neg_hi:[0,1]
	v_pk_add_f32 v[186:187], v[192:193], v[16:17] op_sel_hi:[1,0] neg_lo:[0,1] neg_hi:[0,1]
	v_pk_add_f32 v[188:189], v[196:197], v[16:17] op_sel_hi:[1,0] neg_lo:[0,1] neg_hi:[0,1]
	v_pk_add_f32 v[20:21], v[20:21], v[16:17] op_sel_hi:[1,0] neg_lo:[0,1] neg_hi:[0,1]
	v_pk_mul_f32 v[184:185], v[16:17], v[184:185] op_sel:[1,0]
	v_pk_mul_f32 v[186:187], v[16:17], v[186:187] op_sel:[1,0]
	v_pk_mul_f32 v[188:189], v[16:17], v[188:189] op_sel:[1,0]
	v_pk_mul_f32 v[16:17], v[16:17], v[20:21] op_sel:[1,0]
	v_pk_fma_f32 v[20:21], v[136:137], v[184:185], v[138:139]
	v_pk_fma_f32 v[16:17], v[18:19], v[16:17], v[22:23]
	v_pk_fma_f32 v[184:185], v[26:27], v[186:187], v[30:31]
	v_pk_fma_f32 v[186:187], v[24:25], v[188:189], v[28:29]
	v_cvt_pk_bf16_f32 v253, v186, v16
	v_cvt_pk_bf16_f32 v252, v187, v17
	v_cvt_pk_bf16_f32 v254, v21, v185
	v_cvt_pk_bf16_f32 v255, v20, v184
	v_mov_b32_e32 v187, v252
	v_mov_b32_e32 v186, v253
	v_mov_b32_e32 v185, v254
	v_mov_b32_e32 v184, v255
	ds_write_b128 v163, v[184:187]
	s_waitcnt vmcnt(1)
	ds_write_b128 v164, v[180:183] offset:36864
	ds_read_b64 v[16:17], v165
	v_and_b32_e32 v181, 0xffff0000, v9
	v_and_b32_e32 v180, 0xffff0000, v8
	v_lshlrev_b32_e32 v21, 16, v9
	v_lshlrev_b32_e32 v20, 16, v8
	s_waitcnt lgkmcnt(0)
	v_pk_add_f32 v[180:181], v[180:181], v[16:17] op_sel_hi:[1,0] neg_lo:[0,1] neg_hi:[0,1]
	v_and_b32_e32 v189, 0xffff0000, v11
	v_pk_mul_f32 v[180:181], v[16:17], v[180:181] op_sel:[1,0]
	v_and_b32_e32 v188, 0xffff0000, v10
	v_pk_fma_f32 v[184:185], v[26:27], v[180:181], v[30:31]
	v_lshlrev_b32_e32 v181, 16, v11
	v_lshlrev_b32_e32 v180, 16, v10
	v_pk_add_f32 v[180:181], v[180:181], v[16:17] op_sel_hi:[1,0] neg_lo:[0,1] neg_hi:[0,1]
	v_pk_add_f32 v[20:21], v[20:21], v[16:17] op_sel_hi:[1,0] neg_lo:[0,1] neg_hi:[0,1]
	v_pk_mul_f32 v[180:181], v[16:17], v[180:181] op_sel:[1,0]
	v_pk_add_f32 v[188:189], v[188:189], v[16:17] op_sel_hi:[1,0] neg_lo:[0,1] neg_hi:[0,1]
	v_pk_fma_f32 v[186:187], v[24:25], v[180:181], v[28:29]
	global_load_dwordx4 v[180:183], v[128:129], off
	v_pk_mul_f32 v[20:21], v[16:17], v[20:21] op_sel:[1,0]
	v_pk_mul_f32 v[16:17], v[16:17], v[188:189] op_sel:[1,0]
	v_pk_fma_f32 v[20:21], v[136:137], v[20:21], v[138:139]
	v_pk_fma_f32 v[16:17], v[18:19], v[16:17], v[22:23]
	v_cvt_pk_bf16_f32 v238, v186, v16
	v_cvt_pk_bf16_f32 v237, v187, v17
	v_cvt_pk_bf16_f32 v239, v21, v185
	v_cvt_pk_bf16_f32 v240, v20, v184
	v_mov_b32_e32 v187, v237
	v_mov_b32_e32 v186, v238
	v_mov_b32_e32 v185, v239
	v_mov_b32_e32 v184, v240
	ds_write_b128 v166, v[184:187]
	s_waitcnt vmcnt(1)
	ds_write_b128 v167, v[176:179] offset:36864
	ds_read_b64 v[16:17], v168
	v_lshlrev_b32_e32 v21, 16, v13
	v_lshlrev_b32_e32 v20, 16, v12
	s_waitcnt lgkmcnt(0)
	v_pk_add_f32 v[20:21], v[20:21], v[16:17] op_sel_hi:[1,0] neg_lo:[0,1] neg_hi:[0,1]
	s_nop 0
	v_pk_mul_f32 v[20:21], v[16:17], v[20:21] op_sel:[1,0]
	s_nop 0
	v_pk_fma_f32 v[20:21], v[136:137], v[20:21], v[138:139]
	v_and_b32_e32 v137, 0xffff0000, v13
	v_and_b32_e32 v136, 0xffff0000, v12
	v_pk_add_f32 v[136:137], v[136:137], v[16:17] op_sel_hi:[1,0] neg_lo:[0,1] neg_hi:[0,1]
	s_nop 0
	v_pk_mul_f32 v[136:137], v[16:17], v[136:137] op_sel:[1,0]
	s_nop 0
	v_pk_fma_f32 v[26:27], v[26:27], v[136:137], v[30:31]
	v_lshlrev_b32_e32 v31, 16, v15
	v_lshlrev_b32_e32 v30, 16, v14
	v_pk_add_f32 v[30:31], v[30:31], v[16:17] op_sel_hi:[1,0] neg_lo:[0,1] neg_hi:[0,1]
	s_nop 0
	v_pk_mul_f32 v[30:31], v[16:17], v[30:31] op_sel:[1,0]
	s_nop 0
	v_pk_fma_f32 v[24:25], v[24:25], v[30:31], v[28:29]
	v_and_b32_e32 v29, 0xffff0000, v15
	v_and_b32_e32 v28, 0xffff0000, v14
	v_pk_add_f32 v[28:29], v[28:29], v[16:17] op_sel_hi:[1,0] neg_lo:[0,1] neg_hi:[0,1]
	s_nop 0
	v_pk_mul_f32 v[16:17], v[16:17], v[28:29] op_sel:[1,0]
	s_nop 0
	v_pk_fma_f32 v[16:17], v[18:19], v[16:17], v[22:23]
	v_cvt_pk_bf16_f32 v242, v24, v16
	v_cvt_pk_bf16_f32 v241, v25, v17
	v_cvt_pk_bf16_f32 v244, v20, v26
	v_cvt_pk_bf16_f32 v243, v21, v27
	v_mov_b32_e32 v19, v241
	v_mov_b32_e32 v18, v242
	v_mov_b32_e32 v17, v243
	v_mov_b32_e32 v16, v244
	ds_write_b128 v169, v[16:19]
	s_waitcnt vmcnt(0)
	ds_write_b128 v170, v[180:183] offset:36864
	s_waitcnt lgkmcnt(0)
	s_barrier
; __device__ __forceinline__ void phase_mixer_a(const Params& P, LAS unsigned char* lds, int ustart, int ustride, bool dry) {
;     ...
;             if (h + 1 < 8) {
; #pragma unroll
;                 for (int i = 0; i < 4; ++i) { const int item = tid + 512 * i, c8 = item & 15, s = item >> 4;
;                     pgv[i] = *(const u32x4*)(PJ + T_GV + (size_t)(r0 + s) * 1024 + (h + 1) * 128 + c8 * 8); }
;             }
	s_cbranch_scc0 .LBB0_594
	v_lshl_add_u64 v[12:13], v[94:95], 0, s[12:13]
	v_lshl_add_u64 v[8:9], v[92:93], 0, s[12:13]
	v_lshl_add_u64 v[4:5], v[90:91], 0, s[12:13]
	v_lshl_add_u64 v[0:1], v[88:89], 0, s[12:13]
	global_load_dwordx4 v[0:3], v[0:1], off
	s_nop 0
	global_load_dwordx4 v[4:7], v[4:5], off
	s_nop 0
	global_load_dwordx4 v[8:11], v[8:9], off
	s_nop 0
	global_load_dwordx4 v[12:15], v[12:13], off
	s_branch .LBB0_594

; #define LAS __attribute__((address_space(3)))
; __device__ __forceinline__ void tr_item(const float* W, int ldw, int src_col0, int k0, bf16_t* dst, int ldd, int dst_row0, int dst_col0, LAS float* scr, int lane) {
; #pragma unroll 8
;     for (int i = 0; i < 32; ++i) { const int kk = 2 * i + (lane >> 5); scr[kk * 33 + (lane & 31)] = W[(size_t)(k0 + kk) * ldw + src_col0 + (lane & 31)]; }
;     asm volatile("s_waitcnt lgkmcnt(0)" ::: "memory");
.LBB0_603:
	s_lshl_b32 s19, s16, 1
	s_lshl_b32 s20, s17, 1
	v_or_b32_e32 v4, s19, v1
	v_or_b32_e32 v19, s20, v0
	s_add_i32 s21, s19, 4
	s_add_i32 s22, s20, 4
	s_add_i32 s23, s19, 8
	s_add_i32 s24, s20, 8
	s_add_i32 s25, s19, 12
	s_add_i32 s26, s20, 12
	s_add_i32 s27, s19, 16
	s_add_i32 s28, s20, 16
	s_add_i32 s29, s19, 20
	s_add_i32 s30, s20, 20
	s_add_i32 s31, s19, 24
	s_add_i32 s34, s20, 24
	s_add_i32 s19, s19, 28
	s_add_i32 s20, s20, 28
	v_add_u32_e32 v32, v19, v18
	v_or_b32_e32 v29, s21, v1
	v_or_b32_e32 v62, s22, v0
	v_or_b32_e32 v63, s23, v1
	v_or_b32_e32 v64, s24, v0
	v_or_b32_e32 v65, s25, v1
	v_or_b32_e32 v66, s26, v0
	v_or_b32_e32 v67, s27, v1
	v_or_b32_e32 v68, s28, v0
	v_or_b32_e32 v69, s29, v1
	v_or_b32_e32 v70, s30, v0
	v_or_b32_e32 v71, s31, v1
	v_or_b32_e32 v72, s34, v0
	v_or_b32_e32 v73, s19, v1
	v_or_b32_e32 v74, s20, v0
	v_add_u32_e32 v30, v4, v3
	v_ashrrev_i32_e32 v33, 31, v32
	v_add_u32_e32 v34, v29, v3
	v_add_u32_e32 v36, v62, v18
	v_add_u32_e32 v38, v63, v3
	v_add_u32_e32 v40, v64, v18
	v_add_u32_e32 v42, v65, v3
	v_add_u32_e32 v44, v66, v18
	v_add_u32_e32 v46, v67, v3
	v_add_u32_e32 v48, v68, v18
	v_add_u32_e32 v50, v69, v3
	v_add_u32_e32 v52, v70, v18
	v_add_u32_e32 v54, v71, v3
	v_add_u32_e32 v56, v72, v18
	v_add_u32_e32 v58, v73, v3
	v_add_u32_e32 v60, v74, v18
	v_ashrrev_i32_e32 v31, 31, v30
	v_lshlrev_b64 v[32:33], 12, v[32:33]
	v_ashrrev_i32_e32 v37, 31, v36
	v_ashrrev_i32_e32 v35, 31, v34
	v_ashrrev_i32_e32 v41, 31, v40
	v_ashrrev_i32_e32 v39, 31, v38
	v_ashrrev_i32_e32 v45, 31, v44
	v_ashrrev_i32_e32 v43, 31, v42
	v_ashrrev_i32_e32 v49, 31, v48
	v_ashrrev_i32_e32 v47, 31, v46
	v_ashrrev_i32_e32 v53, 31, v52
	v_ashrrev_i32_e32 v51, 31, v50
	v_ashrrev_i32_e32 v57, 31, v56
	v_ashrrev_i32_e32 v55, 31, v54
	v_ashrrev_i32_e32 v61, 31, v60
	v_ashrrev_i32_e32 v59, 31, v58
	v_lshlrev_b64 v[30:31], 12, v[30:31]
	v_lshl_add_u64 v[32:33], v[20:21], 0, v[32:33]
	v_lshlrev_b64 v[34:35], 12, v[34:35]
	v_lshlrev_b64 v[36:37], 12, v[36:37]
	v_lshlrev_b64 v[38:39], 12, v[38:39]
	v_lshlrev_b64 v[40:41], 12, v[40:41]
	v_lshlrev_b64 v[42:43], 12, v[42:43]
	v_lshlrev_b64 v[44:45], 12, v[44:45]
	v_lshlrev_b64 v[46:47], 12, v[46:47]
	v_lshlrev_b64 v[48:49], 12, v[48:49]
	v_lshlrev_b64 v[50:51], 12, v[50:51]
	v_lshlrev_b64 v[52:53], 12, v[52:53]
	v_lshlrev_b64 v[54:55], 12, v[54:55]
	v_lshlrev_b64 v[56:57], 12, v[56:57]
	v_lshlrev_b64 v[58:59], 12, v[58:59]
	v_lshlrev_b64 v[60:61], 12, v[60:61]
	v_lshl_add_u64 v[30:31], v[20:21], 0, v[30:31]
	v_lshl_add_u64 v[36:37], v[20:21], 0, v[36:37]
	v_lshl_add_u64 v[34:35], v[20:21], 0, v[34:35]
	v_lshl_add_u64 v[40:41], v[20:21], 0, v[40:41]
	v_lshl_add_u64 v[38:39], v[20:21], 0, v[38:39]
	v_lshl_add_u64 v[44:45], v[20:21], 0, v[44:45]
	v_lshl_add_u64 v[42:43], v[20:21], 0, v[42:43]
	v_lshl_add_u64 v[48:49], v[20:21], 0, v[48:49]
	v_lshl_add_u64 v[46:47], v[20:21], 0, v[46:47]
	v_lshl_add_u64 v[52:53], v[20:21], 0, v[52:53]
	v_lshl_add_u64 v[50:51], v[20:21], 0, v[50:51]
	v_lshl_add_u64 v[56:57], v[20:21], 0, v[56:57]
	v_lshl_add_u64 v[54:55], v[20:21], 0, v[54:55]
	v_lshl_add_u64 v[60:61], v[20:21], 0, v[60:61]
	v_lshl_add_u64 v[58:59], v[20:21], 0, v[58:59]
	global_load_dword v75, v[32:33], off
	global_load_dword v76, v[30:31], off
	global_load_dword v77, v[36:37], off
	global_load_dword v78, v[34:35], off
	global_load_dword v79, v[40:41], off
	global_load_dword v80, v[38:39], off
	global_load_dword v81, v[44:45], off
	global_load_dword v82, v[42:43], off
	global_load_dword v83, v[48:49], off
	global_load_dword v84, v[46:47], off
	global_load_dword v85, v[52:53], off
	global_load_dword v86, v[50:51], off
	global_load_dword v87, v[56:57], off
	global_load_dword v88, v[54:55], off
	global_load_dword v89, v[60:61], off
	global_load_dword v90, v[58:59], off
	s_add_i32 s17, s17, 16
	s_add_i32 s16, s16, 16
	s_add_i32 s18, s18, -16
	v_mad_u64_u32 v[30:31], s[20:21], v19, s1, v[2:3]
	s_cmp_lg_u32 s18, 0
	v_mad_u64_u32 v[32:33], s[20:21], v4, s1, v[2:3]
	v_mad_u64_u32 v[34:35], s[20:21], v62, s1, v[2:3]
	v_mad_u64_u32 v[36:37], s[20:21], v29, s1, v[2:3]
	v_mad_u64_u32 v[38:39], s[20:21], v64, s1, v[2:3]
	v_mad_u64_u32 v[40:41], s[20:21], v63, s1, v[2:3]
	v_mad_u64_u32 v[42:43], s[20:21], v66, s1, v[2:3]
	v_mad_u64_u32 v[44:45], s[20:21], v65, s1, v[2:3]
	v_mad_u64_u32 v[46:47], s[20:21], v68, s1, v[2:3]
	v_mad_u64_u32 v[48:49], s[20:21], v67, s1, v[2:3]
	v_mad_u64_u32 v[50:51], s[20:21], v70, s1, v[2:3]
	v_mad_u64_u32 v[52:53], s[20:21], v69, s1, v[2:3]
	v_mad_u64_u32 v[54:55], s[20:21], v72, s1, v[2:3]
	v_mad_u64_u32 v[56:57], s[20:21], v71, s1, v[2:3]
	v_mad_u64_u32 v[58:59], s[20:21], v74, s1, v[2:3]
	v_mad_u64_u32 v[60:61], s[20:21], v73, s1, v[2:3]
	s_waitcnt vmcnt(15)
	ds_write_b32 v30, v75
	s_waitcnt vmcnt(14)
	ds_write_b32 v32, v76
	s_waitcnt vmcnt(13)
	ds_write_b32 v34, v77
	s_waitcnt vmcnt(12)
	ds_write_b32 v36, v78
	s_waitcnt vmcnt(11)
	ds_write_b32 v38, v79
	s_waitcnt vmcnt(10)
	ds_write_b32 v40, v80
	s_waitcnt vmcnt(9)
	ds_write_b32 v42, v81
	s_waitcnt vmcnt(8)
	ds_write_b32 v44, v82
	s_waitcnt vmcnt(7)
	ds_write_b32 v46, v83
	s_waitcnt vmcnt(6)
	ds_write_b32 v48, v84
	s_waitcnt vmcnt(5)
	ds_write_b32 v50, v85
	s_waitcnt vmcnt(4)
	ds_write_b32 v52, v86
	s_waitcnt vmcnt(3)
	ds_write_b32 v54, v87
	s_waitcnt vmcnt(2)
	ds_write_b32 v56, v88
	s_waitcnt vmcnt(1)
	ds_write_b32 v58, v89
	s_waitcnt vmcnt(0)
	ds_write_b32 v60, v90
	s_cbranch_scc1 .LBB0_603
; #define LAS __attribute__((address_space(3)))
; __device__ __forceinline__ unsigned pk2(float lo, float hi) { return f2bf(lo) | (f2bf(hi) << 16); }
; __device__ __forceinline__ void tr_item(const float* W, int ldw, int src_col0, int k0, bf16_t* dst, int ldd, int dst_row0, int dst_col0, LAS float* scr, int lane) {
;     ...
;     const int c = lane & 7;
; #pragma unroll
;     for (int j = 0; j < 4; ++j) { const int n = (lane >> 3) + 8 * j; const LAS float* s = scr + (8 * c) * 33 + n;
;         u32x4 o; o.x = pk2(s[0 * 33], s[1 * 33]); o.y = pk2(s[2 * 33], s[3 * 33]); o.z = pk2(s[4 * 33], s[5 * 33]); o.w = pk2(s[6 * 33], s[7 * 33]);
;         *(u32x4*)(dst + (size_t)(dst_row0 + n) * ldd + dst_col0 + k0 + 8 * c) = o; }
;     asm volatile("s_waitcnt lgkmcnt(0)" ::: "memory");
	s_waitcnt lgkmcnt(0)
	ds_read2_b32 v[30:31], v24 offset1:8
	ds_read2_b32 v[34:35], v24 offset0:33 offset1:41
	ds_read2_b32 v[36:37], v24 offset0:66 offset1:74
	ds_read2_b32 v[38:39], v24 offset0:99 offset1:107
	ds_read2_b32 v[40:41], v24 offset0:132 offset1:140
	v_mov_b32_e32 v19, v5
	s_waitcnt lgkmcnt(4)
	s_waitcnt lgkmcnt(3)
	ds_read2_b32 v[42:43], v24 offset0:165 offset1:173
	v_lshl_add_u64 v[32:33], v[18:19], 1, v[6:7]
	v_cvt_pk_bf16_f32 v18, v30, v34
	s_waitcnt lgkmcnt(3)
	s_waitcnt lgkmcnt(2)
	ds_read2_b32 v[44:45], v24 offset0:198 offset1:206
	ds_read2_b32 v[46:47], v24 offset0:231 offset1:239
	v_cvt_pk_bf16_f32 v19, v36, v38
	s_waitcnt lgkmcnt(3)
	s_waitcnt lgkmcnt(2)
	v_cvt_pk_bf16_f32 v20, v40, v42
	s_waitcnt lgkmcnt(1)
	s_waitcnt lgkmcnt(0)
	v_cvt_pk_bf16_f32 v21, v44, v46
	v_or_b32_e32 v3, v28, v23
	v_lshlrev_b32_e32 v4, 11, v3
	v_lshl_add_u64 v[48:49], v[32:33], 0, v[4:5]
	global_store_dwordx4 v[48:49], v[18:21], off
	v_cvt_pk_bf16_f32 v245, v31, v35
	ds_read2_b32 v[30:31], v24 offset0:16 offset1:24
	s_nop 0
	v_mov_b32_e32 v18, v245
	v_cvt_pk_bf16_f32 v19, v37, v39
	v_cvt_pk_bf16_f32 v20, v41, v43
	v_cvt_pk_bf16_f32 v21, v45, v47
	v_or_b32_e32 v3, v28, v25
	v_lshlrev_b32_e32 v4, 11, v3
	v_lshl_add_u64 v[34:35], v[32:33], 0, v[4:5]
	global_store_dwordx4 v[34:35], v[18:21], off
	ds_read2_b32 v[34:35], v24 offset0:49 offset1:57
	ds_read2_b32 v[36:37], v24 offset0:82 offset1:90
	ds_read2_b32 v[38:39], v24 offset0:115 offset1:123
	s_waitcnt lgkmcnt(3)
	s_waitcnt lgkmcnt(2)
	ds_read2_b32 v[40:41], v24 offset0:148 offset1:156
	ds_read2_b32 v[42:43], v24 offset0:181 offset1:189
	v_cvt_pk_bf16_f32 v18, v30, v34
	s_waitcnt lgkmcnt(3)
	s_waitcnt lgkmcnt(2)
	ds_read2_b32 v[44:45], v24 offset0:214 offset1:222
	ds_read2_b32 v[46:47], v24 offset0:247 offset1:255
	v_cvt_pk_bf16_f32 v19, v36, v38
	s_waitcnt lgkmcnt(3)
	s_waitcnt lgkmcnt(2)
	v_cvt_pk_bf16_f32 v20, v40, v42
	s_waitcnt lgkmcnt(1)
	s_waitcnt lgkmcnt(0)
	v_cvt_pk_bf16_f32 v21, v44, v46
	v_or_b32_e32 v3, v28, v26
	v_lshlrev_b32_e32 v4, 11, v3
	v_lshl_add_u64 v[48:49], v[32:33], 0, v[4:5]
	global_store_dwordx4 v[48:49], v[18:21], off
	s_nop 1
	v_cvt_pk_bf16_f32 v18, v31, v35
	v_cvt_pk_bf16_f32 v19, v37, v39
	v_cvt_pk_bf16_f32 v20, v41, v43
	v_cvt_pk_bf16_f32 v21, v45, v47
	v_or_b32_e32 v3, v28, v27
	v_lshlrev_b32_e32 v4, 11, v3
	v_lshl_add_u64 v[28:29], v[32:33], 0, v[4:5]
	global_store_dwordx4 v[28:29], v[18:21], off
	s_waitcnt lgkmcnt(0)

; #define LAS __attribute__((address_space(3)))
; __device__ __forceinline__ void tr_item(const float* W, int ldw, int src_col0, int k0, bf16_t* dst, int ldd, int dst_row0, int dst_col0, LAS float* scr, int lane) {
; #pragma unroll 8
;     for (int i = 0; i < 32; ++i) { const int kk = 2 * i + (lane >> 5); scr[kk * 33 + (lane & 31)] = W[(size_t)(k0 + kk) * ldw + src_col0 + (lane & 31)]; }
;     asm volatile("s_waitcnt lgkmcnt(0)" ::: "memory");
.LBB0_607:
	s_lshl_b32 s19, s16, 1
	s_lshl_b32 s20, s17, 1
	v_or_b32_e32 v4, s19, v1
	v_or_b32_e32 v19, s20, v0
	s_add_i32 s21, s19, 4
	s_add_i32 s22, s20, 4
	s_add_i32 s23, s19, 8
	s_add_i32 s24, s20, 8
	s_add_i32 s25, s19, 12
	s_add_i32 s26, s20, 12
	s_add_i32 s27, s19, 16
	s_add_i32 s28, s20, 16
	s_add_i32 s29, s19, 20
	s_add_i32 s30, s20, 20
	s_add_i32 s31, s19, 24
	s_add_i32 s34, s20, 24
	s_add_i32 s19, s19, 28
	s_add_i32 s20, s20, 28
	v_add_u32_e32 v32, v19, v18
	v_or_b32_e32 v29, s21, v1
	v_or_b32_e32 v62, s22, v0
	v_or_b32_e32 v63, s23, v1
	v_or_b32_e32 v64, s24, v0
	v_or_b32_e32 v65, s25, v1
	v_or_b32_e32 v66, s26, v0
	v_or_b32_e32 v67, s27, v1
	v_or_b32_e32 v68, s28, v0
	v_or_b32_e32 v69, s29, v1
	v_or_b32_e32 v70, s30, v0
	v_or_b32_e32 v71, s31, v1
	v_or_b32_e32 v72, s34, v0
	v_or_b32_e32 v73, s19, v1
	v_or_b32_e32 v74, s20, v0
	v_add_u32_e32 v30, v4, v3
	v_ashrrev_i32_e32 v33, 31, v32
	v_add_u32_e32 v34, v29, v3
	v_add_u32_e32 v36, v62, v18
	v_add_u32_e32 v38, v63, v3
	v_add_u32_e32 v40, v64, v18
	v_add_u32_e32 v42, v65, v3
	v_add_u32_e32 v44, v66, v18
	v_add_u32_e32 v46, v67, v3
	v_add_u32_e32 v48, v68, v18
	v_add_u32_e32 v50, v69, v3
	v_add_u32_e32 v52, v70, v18
	v_add_u32_e32 v54, v71, v3
	v_add_u32_e32 v56, v72, v18
	v_add_u32_e32 v58, v73, v3
	v_add_u32_e32 v60, v74, v18
	v_ashrrev_i32_e32 v31, 31, v30
	v_lshlrev_b64 v[32:33], 12, v[32:33]
	v_ashrrev_i32_e32 v37, 31, v36
	v_ashrrev_i32_e32 v35, 31, v34
	v_ashrrev_i32_e32 v41, 31, v40
	v_ashrrev_i32_e32 v39, 31, v38
	v_ashrrev_i32_e32 v45, 31, v44
	v_ashrrev_i32_e32 v43, 31, v42
	v_ashrrev_i32_e32 v49, 31, v48
	v_ashrrev_i32_e32 v47, 31, v46
	v_ashrrev_i32_e32 v53, 31, v52
	v_ashrrev_i32_e32 v51, 31, v50
	v_ashrrev_i32_e32 v57, 31, v56
	v_ashrrev_i32_e32 v55, 31, v54
	v_ashrrev_i32_e32 v61, 31, v60
	v_ashrrev_i32_e32 v59, 31, v58
	v_lshlrev_b64 v[30:31], 12, v[30:31]
	v_lshl_add_u64 v[32:33], v[20:21], 0, v[32:33]
	v_lshlrev_b64 v[34:35], 12, v[34:35]
	v_lshlrev_b64 v[36:37], 12, v[36:37]
	v_lshlrev_b64 v[38:39], 12, v[38:39]
	v_lshlrev_b64 v[40:41], 12, v[40:41]
	v_lshlrev_b64 v[42:43], 12, v[42:43]
	v_lshlrev_b64 v[44:45], 12, v[44:45]
	v_lshlrev_b64 v[46:47], 12, v[46:47]
	v_lshlrev_b64 v[48:49], 12, v[48:49]
	v_lshlrev_b64 v[50:51], 12, v[50:51]
	v_lshlrev_b64 v[52:53], 12, v[52:53]
	v_lshlrev_b64 v[54:55], 12, v[54:55]
	v_lshlrev_b64 v[56:57], 12, v[56:57]
	v_lshlrev_b64 v[58:59], 12, v[58:59]
	v_lshlrev_b64 v[60:61], 12, v[60:61]
	v_lshl_add_u64 v[30:31], v[20:21], 0, v[30:31]
	v_lshl_add_u64 v[36:37], v[20:21], 0, v[36:37]
	v_lshl_add_u64 v[34:35], v[20:21], 0, v[34:35]
	v_lshl_add_u64 v[40:41], v[20:21], 0, v[40:41]
	v_lshl_add_u64 v[38:39], v[20:21], 0, v[38:39]
	v_lshl_add_u64 v[44:45], v[20:21], 0, v[44:45]
	v_lshl_add_u64 v[42:43], v[20:21], 0, v[42:43]
	v_lshl_add_u64 v[48:49], v[20:21], 0, v[48:49]
	v_lshl_add_u64 v[46:47], v[20:21], 0, v[46:47]
	v_lshl_add_u64 v[52:53], v[20:21], 0, v[52:53]
	v_lshl_add_u64 v[50:51], v[20:21], 0, v[50:51]
	v_lshl_add_u64 v[56:57], v[20:21], 0, v[56:57]
	v_lshl_add_u64 v[54:55], v[20:21], 0, v[54:55]
	v_lshl_add_u64 v[60:61], v[20:21], 0, v[60:61]
	v_lshl_add_u64 v[58:59], v[20:21], 0, v[58:59]
	global_load_dword v75, v[32:33], off
	global_load_dword v76, v[30:31], off
	global_load_dword v77, v[36:37], off
	global_load_dword v78, v[34:35], off
	global_load_dword v79, v[40:41], off
	global_load_dword v80, v[38:39], off
	global_load_dword v81, v[44:45], off
	global_load_dword v82, v[42:43], off
	global_load_dword v83, v[48:49], off
	global_load_dword v84, v[46:47], off
	global_load_dword v85, v[52:53], off
	global_load_dword v86, v[50:51], off
	global_load_dword v87, v[56:57], off
	global_load_dword v88, v[54:55], off
	global_load_dword v89, v[60:61], off
	global_load_dword v90, v[58:59], off
	s_add_i32 s17, s17, 16
	s_add_i32 s16, s16, 16
	s_add_i32 s18, s18, -16
	v_mad_u64_u32 v[30:31], s[20:21], v19, s1, v[2:3]
	s_cmp_lg_u32 s18, 0
	v_mad_u64_u32 v[32:33], s[20:21], v4, s1, v[2:3]
	v_mad_u64_u32 v[34:35], s[20:21], v62, s1, v[2:3]
	v_mad_u64_u32 v[36:37], s[20:21], v29, s1, v[2:3]
	v_mad_u64_u32 v[38:39], s[20:21], v64, s1, v[2:3]
	v_mad_u64_u32 v[40:41], s[20:21], v63, s1, v[2:3]
	v_mad_u64_u32 v[42:43], s[20:21], v66, s1, v[2:3]
	v_mad_u64_u32 v[44:45], s[20:21], v65, s1, v[2:3]
	v_mad_u64_u32 v[46:47], s[20:21], v68, s1, v[2:3]
	v_mad_u64_u32 v[48:49], s[20:21], v67, s1, v[2:3]
	v_mad_u64_u32 v[50:51], s[20:21], v70, s1, v[2:3]
	v_mad_u64_u32 v[52:53], s[20:21], v69, s1, v[2:3]
	v_mad_u64_u32 v[54:55], s[20:21], v72, s1, v[2:3]
	v_mad_u64_u32 v[56:57], s[20:21], v71, s1, v[2:3]
	v_mad_u64_u32 v[58:59], s[20:21], v74, s1, v[2:3]
	v_mad_u64_u32 v[60:61], s[20:21], v73, s1, v[2:3]
	s_waitcnt vmcnt(15)
	ds_write_b32 v30, v75
	s_waitcnt vmcnt(14)
	ds_write_b32 v32, v76
	s_waitcnt vmcnt(13)
	ds_write_b32 v34, v77
	s_waitcnt vmcnt(12)
	ds_write_b32 v36, v78
	s_waitcnt vmcnt(11)
	ds_write_b32 v38, v79
	s_waitcnt vmcnt(10)
	ds_write_b32 v40, v80
	s_waitcnt vmcnt(9)
	ds_write_b32 v42, v81
	s_waitcnt vmcnt(8)
	ds_write_b32 v44, v82
	s_waitcnt vmcnt(7)
	ds_write_b32 v46, v83
	s_waitcnt vmcnt(6)
	ds_write_b32 v48, v84
	s_waitcnt vmcnt(5)
	ds_write_b32 v50, v85
	s_waitcnt vmcnt(4)
	ds_write_b32 v52, v86
	s_waitcnt vmcnt(3)
	ds_write_b32 v54, v87
	s_waitcnt vmcnt(2)
	ds_write_b32 v56, v88
	s_waitcnt vmcnt(1)
	ds_write_b32 v58, v89
	s_waitcnt vmcnt(0)
	ds_write_b32 v60, v90
	s_cbranch_scc1 .LBB0_607
; #define LAS __attribute__((address_space(3)))
; __device__ __forceinline__ unsigned pk2(float lo, float hi) { return f2bf(lo) | (f2bf(hi) << 16); }
; __device__ __forceinline__ void tr_item(const float* W, int ldw, int src_col0, int k0, bf16_t* dst, int ldd, int dst_row0, int dst_col0, LAS float* scr, int lane) {
;     ...
;     const int c = lane & 7;
; #pragma unroll
;     for (int j = 0; j < 4; ++j) { const int n = (lane >> 3) + 8 * j; const LAS float* s = scr + (8 * c) * 33 + n;
;         u32x4 o; o.x = pk2(s[0 * 33], s[1 * 33]); o.y = pk2(s[2 * 33], s[3 * 33]); o.z = pk2(s[4 * 33], s[5 * 33]); o.w = pk2(s[6 * 33], s[7 * 33]);
;         *(u32x4*)(dst + (size_t)(dst_row0 + n) * ldd + dst_col0 + k0 + 8 * c) = o; }
;     asm volatile("s_waitcnt lgkmcnt(0)" ::: "memory");
	s_waitcnt lgkmcnt(0)
	ds_read2_b32 v[30:31], v24 offset1:8
	ds_read2_b32 v[34:35], v24 offset0:33 offset1:41
	ds_read2_b32 v[36:37], v24 offset0:66 offset1:74
	ds_read2_b32 v[38:39], v24 offset0:99 offset1:107
	ds_read2_b32 v[40:41], v24 offset0:132 offset1:140
	v_mov_b32_e32 v19, v5
	s_waitcnt lgkmcnt(4)
	s_waitcnt lgkmcnt(3)
	ds_read2_b32 v[42:43], v24 offset0:165 offset1:173
	v_lshl_add_u64 v[32:33], v[18:19], 1, v[8:9]
	v_cvt_pk_bf16_f32 v18, v30, v34
	s_waitcnt lgkmcnt(3)
	s_waitcnt lgkmcnt(2)
	ds_read2_b32 v[44:45], v24 offset0:198 offset1:206
	ds_read2_b32 v[46:47], v24 offset0:231 offset1:239
	v_cvt_pk_bf16_f32 v19, v36, v38
	s_waitcnt lgkmcnt(3)
	s_waitcnt lgkmcnt(2)
	v_cvt_pk_bf16_f32 v20, v40, v42
	s_waitcnt lgkmcnt(1)
	s_waitcnt lgkmcnt(0)
	v_cvt_pk_bf16_f32 v21, v44, v46
	v_or_b32_e32 v3, v28, v23
	v_lshlrev_b32_e32 v4, 12, v3
	v_lshl_add_u64 v[48:49], v[32:33], 0, v[4:5]
	global_store_dwordx4 v[48:49], v[18:21], off
	v_cvt_pk_bf16_f32 v246, v31, v35
	ds_read2_b32 v[30:31], v24 offset0:16 offset1:24
	s_nop 0
	v_mov_b32_e32 v18, v246
	v_cvt_pk_bf16_f32 v19, v37, v39
	v_cvt_pk_bf16_f32 v20, v41, v43
	v_cvt_pk_bf16_f32 v21, v45, v47
	v_or_b32_e32 v3, v28, v25
	v_lshlrev_b32_e32 v4, 12, v3
	v_lshl_add_u64 v[34:35], v[32:33], 0, v[4:5]
	global_store_dwordx4 v[34:35], v[18:21], off
	ds_read2_b32 v[34:35], v24 offset0:49 offset1:57
	ds_read2_b32 v[36:37], v24 offset0:82 offset1:90
	ds_read2_b32 v[38:39], v24 offset0:115 offset1:123
	s_waitcnt lgkmcnt(3)
	s_waitcnt lgkmcnt(2)
	ds_read2_b32 v[40:41], v24 offset0:148 offset1:156
	ds_read2_b32 v[42:43], v24 offset0:181 offset1:189
	v_cvt_pk_bf16_f32 v18, v30, v34
	s_waitcnt lgkmcnt(3)
	s_waitcnt lgkmcnt(2)
	ds_read2_b32 v[44:45], v24 offset0:214 offset1:222
	ds_read2_b32 v[46:47], v24 offset0:247 offset1:255
	v_cvt_pk_bf16_f32 v19, v36, v38
	s_waitcnt lgkmcnt(3)
	s_waitcnt lgkmcnt(2)
	v_cvt_pk_bf16_f32 v20, v40, v42
	s_waitcnt lgkmcnt(1)
	s_waitcnt lgkmcnt(0)
	v_cvt_pk_bf16_f32 v21, v44, v46
	v_or_b32_e32 v3, v28, v26
	v_lshlrev_b32_e32 v4, 12, v3
	v_lshl_add_u64 v[48:49], v[32:33], 0, v[4:5]
	global_store_dwordx4 v[48:49], v[18:21], off
	s_nop 1
	v_cvt_pk_bf16_f32 v18, v31, v35
	v_cvt_pk_bf16_f32 v19, v37, v39
	v_cvt_pk_bf16_f32 v20, v41, v43
	v_cvt_pk_bf16_f32 v21, v45, v47
	v_or_b32_e32 v3, v28, v27
	v_lshlrev_b32_e32 v4, 12, v3
	v_lshl_add_u64 v[28:29], v[32:33], 0, v[4:5]
	global_store_dwordx4 v[28:29], v[18:21], off
	s_waitcnt lgkmcnt(0)

; #define LAS __attribute__((address_space(3)))
; __device__ __forceinline__ void tr_item(const float* W, int ldw, int src_col0, int k0, bf16_t* dst, int ldd, int dst_row0, int dst_col0, LAS float* scr, int lane) {
; #pragma unroll 8
;     for (int i = 0; i < 32; ++i) { const int kk = 2 * i + (lane >> 5); scr[kk * 33 + (lane & 31)] = W[(size_t)(k0 + kk) * ldw + src_col0 + (lane & 31)]; }
;     asm volatile("s_waitcnt lgkmcnt(0)" ::: "memory");
.LBB0_612:
	s_lshl_b32 s17, s10, 1
	s_lshl_b32 s18, s11, 1
	v_or_b32_e32 v4, s17, v1
	v_or_b32_e32 v19, s18, v0
	s_add_i32 s19, s17, 4
	s_add_i32 s20, s18, 4
	s_add_i32 s21, s17, 8
	s_add_i32 s22, s18, 8
	s_add_i32 s23, s17, 12
	s_add_i32 s24, s18, 12
	s_add_i32 s25, s17, 16
	s_add_i32 s26, s18, 16
	s_add_i32 s27, s17, 20
	s_add_i32 s28, s18, 20
	s_add_i32 s29, s17, 24
	s_add_i32 s30, s18, 24
	s_add_i32 s17, s17, 28
	s_add_i32 s18, s18, 28
	v_add_u32_e32 v32, v19, v18
	v_or_b32_e32 v29, s19, v1
	v_or_b32_e32 v62, s20, v0
	v_or_b32_e32 v63, s21, v1
	v_or_b32_e32 v64, s22, v0
	v_or_b32_e32 v65, s23, v1
	v_or_b32_e32 v66, s24, v0
	v_or_b32_e32 v67, s25, v1
	v_or_b32_e32 v68, s26, v0
	v_or_b32_e32 v69, s27, v1
	v_or_b32_e32 v70, s28, v0
	v_or_b32_e32 v71, s29, v1
	v_or_b32_e32 v72, s30, v0
	v_or_b32_e32 v73, s17, v1
	v_or_b32_e32 v74, s18, v0
	v_add_u32_e32 v30, v4, v3
	v_ashrrev_i32_e32 v33, 31, v32
	v_add_u32_e32 v34, v29, v3
	v_add_u32_e32 v36, v62, v18
	v_add_u32_e32 v38, v63, v3
	v_add_u32_e32 v40, v64, v18
	v_add_u32_e32 v42, v65, v3
	v_add_u32_e32 v44, v66, v18
	v_add_u32_e32 v46, v67, v3
	v_add_u32_e32 v48, v68, v18
	v_add_u32_e32 v50, v69, v3
	v_add_u32_e32 v52, v70, v18
	v_add_u32_e32 v54, v71, v3
	v_add_u32_e32 v56, v72, v18
	v_add_u32_e32 v58, v73, v3
	v_add_u32_e32 v60, v74, v18
	v_ashrrev_i32_e32 v31, 31, v30
	v_lshlrev_b64 v[32:33], 12, v[32:33]
	v_ashrrev_i32_e32 v37, 31, v36
	v_ashrrev_i32_e32 v35, 31, v34
	v_ashrrev_i32_e32 v41, 31, v40
	v_ashrrev_i32_e32 v39, 31, v38
	v_ashrrev_i32_e32 v45, 31, v44
	v_ashrrev_i32_e32 v43, 31, v42
	v_ashrrev_i32_e32 v49, 31, v48
	v_ashrrev_i32_e32 v47, 31, v46
	v_ashrrev_i32_e32 v53, 31, v52
	v_ashrrev_i32_e32 v51, 31, v50
	v_ashrrev_i32_e32 v57, 31, v56
	v_ashrrev_i32_e32 v55, 31, v54
	v_ashrrev_i32_e32 v61, 31, v60
	v_ashrrev_i32_e32 v59, 31, v58
	v_lshlrev_b64 v[30:31], 12, v[30:31]
	v_lshl_add_u64 v[32:33], v[20:21], 0, v[32:33]
	v_lshlrev_b64 v[34:35], 12, v[34:35]
	v_lshlrev_b64 v[36:37], 12, v[36:37]
	v_lshlrev_b64 v[38:39], 12, v[38:39]
	v_lshlrev_b64 v[40:41], 12, v[40:41]
	v_lshlrev_b64 v[42:43], 12, v[42:43]
	v_lshlrev_b64 v[44:45], 12, v[44:45]
	v_lshlrev_b64 v[46:47], 12, v[46:47]
	v_lshlrev_b64 v[48:49], 12, v[48:49]
	v_lshlrev_b64 v[50:51], 12, v[50:51]
	v_lshlrev_b64 v[52:53], 12, v[52:53]
	v_lshlrev_b64 v[54:55], 12, v[54:55]
	v_lshlrev_b64 v[56:57], 12, v[56:57]
	v_lshlrev_b64 v[58:59], 12, v[58:59]
	v_lshlrev_b64 v[60:61], 12, v[60:61]
	v_lshl_add_u64 v[30:31], v[20:21], 0, v[30:31]
	v_lshl_add_u64 v[36:37], v[20:21], 0, v[36:37]
	v_lshl_add_u64 v[34:35], v[20:21], 0, v[34:35]
	v_lshl_add_u64 v[40:41], v[20:21], 0, v[40:41]
	v_lshl_add_u64 v[38:39], v[20:21], 0, v[38:39]
	v_lshl_add_u64 v[44:45], v[20:21], 0, v[44:45]
	v_lshl_add_u64 v[42:43], v[20:21], 0, v[42:43]
	v_lshl_add_u64 v[48:49], v[20:21], 0, v[48:49]
	v_lshl_add_u64 v[46:47], v[20:21], 0, v[46:47]
	v_lshl_add_u64 v[52:53], v[20:21], 0, v[52:53]
	v_lshl_add_u64 v[50:51], v[20:21], 0, v[50:51]
	v_lshl_add_u64 v[56:57], v[20:21], 0, v[56:57]
	v_lshl_add_u64 v[54:55], v[20:21], 0, v[54:55]
	v_lshl_add_u64 v[60:61], v[20:21], 0, v[60:61]
	v_lshl_add_u64 v[58:59], v[20:21], 0, v[58:59]
	global_load_dword v75, v[32:33], off
	global_load_dword v76, v[30:31], off
	global_load_dword v77, v[36:37], off
	global_load_dword v78, v[34:35], off
	global_load_dword v79, v[40:41], off
	global_load_dword v80, v[38:39], off
	global_load_dword v81, v[44:45], off
	global_load_dword v82, v[42:43], off
	global_load_dword v83, v[48:49], off
	global_load_dword v84, v[46:47], off
	global_load_dword v85, v[52:53], off
	global_load_dword v86, v[50:51], off
	global_load_dword v87, v[56:57], off
	global_load_dword v88, v[54:55], off
	global_load_dword v89, v[60:61], off
	global_load_dword v90, v[58:59], off
	s_add_i32 s11, s11, 16
	s_add_i32 s10, s10, 16
	s_add_i32 s16, s16, -16
	v_mad_u64_u32 v[30:31], s[18:19], v19, s1, v[2:3]
	s_cmp_lg_u32 s16, 0
	v_mad_u64_u32 v[32:33], s[18:19], v4, s1, v[2:3]
	v_mad_u64_u32 v[34:35], s[18:19], v62, s1, v[2:3]
	v_mad_u64_u32 v[36:37], s[18:19], v29, s1, v[2:3]
	v_mad_u64_u32 v[38:39], s[18:19], v64, s1, v[2:3]
	v_mad_u64_u32 v[40:41], s[18:19], v63, s1, v[2:3]
	v_mad_u64_u32 v[42:43], s[18:19], v66, s1, v[2:3]
	v_mad_u64_u32 v[44:45], s[18:19], v65, s1, v[2:3]
	v_mad_u64_u32 v[46:47], s[18:19], v68, s1, v[2:3]
	v_mad_u64_u32 v[48:49], s[18:19], v67, s1, v[2:3]
	v_mad_u64_u32 v[50:51], s[18:19], v70, s1, v[2:3]
	v_mad_u64_u32 v[52:53], s[18:19], v69, s1, v[2:3]
	v_mad_u64_u32 v[54:55], s[18:19], v72, s1, v[2:3]
	v_mad_u64_u32 v[56:57], s[18:19], v71, s1, v[2:3]
	v_mad_u64_u32 v[58:59], s[18:19], v74, s1, v[2:3]
	v_mad_u64_u32 v[60:61], s[18:19], v73, s1, v[2:3]
	s_waitcnt vmcnt(15)
	ds_write_b32 v30, v75
	s_waitcnt vmcnt(14)
	ds_write_b32 v32, v76
	s_waitcnt vmcnt(13)
	ds_write_b32 v34, v77
	s_waitcnt vmcnt(12)
	ds_write_b32 v36, v78
	s_waitcnt vmcnt(11)
	ds_write_b32 v38, v79
	s_waitcnt vmcnt(10)
	ds_write_b32 v40, v80
	s_waitcnt vmcnt(9)
	ds_write_b32 v42, v81
	s_waitcnt vmcnt(8)
	ds_write_b32 v44, v82
	s_waitcnt vmcnt(7)
	ds_write_b32 v46, v83
	s_waitcnt vmcnt(6)
	ds_write_b32 v48, v84
	s_waitcnt vmcnt(5)
	ds_write_b32 v50, v85
	s_waitcnt vmcnt(4)
	ds_write_b32 v52, v86
	s_waitcnt vmcnt(3)
	ds_write_b32 v54, v87
	s_waitcnt vmcnt(2)
	ds_write_b32 v56, v88
	s_waitcnt vmcnt(1)
	ds_write_b32 v58, v89
	s_waitcnt vmcnt(0)
	ds_write_b32 v60, v90
	s_cbranch_scc1 .LBB0_612
; #define LAS __attribute__((address_space(3)))
; __device__ __forceinline__ unsigned pk2(float lo, float hi) { return f2bf(lo) | (f2bf(hi) << 16); }
; __device__ __forceinline__ void tr_item(const float* W, int ldw, int src_col0, int k0, bf16_t* dst, int ldd, int dst_row0, int dst_col0, LAS float* scr, int lane) {
;     ...
;     const int c = lane & 7;
; #pragma unroll
;     for (int j = 0; j < 4; ++j) { const int n = (lane >> 3) + 8 * j; const LAS float* s = scr + (8 * c) * 33 + n;
;         u32x4 o; o.x = pk2(s[0 * 33], s[1 * 33]); o.y = pk2(s[2 * 33], s[3 * 33]); o.z = pk2(s[4 * 33], s[5 * 33]); o.w = pk2(s[6 * 33], s[7 * 33]);
;         *(u32x4*)(dst + (size_t)(dst_row0 + n) * ldd + dst_col0 + k0 + 8 * c) = o; }
;     asm volatile("s_waitcnt lgkmcnt(0)" ::: "memory");
	s_waitcnt lgkmcnt(0)
	ds_read2_b32 v[30:31], v24 offset1:8
	ds_read2_b32 v[34:35], v24 offset0:33 offset1:41
	ds_read2_b32 v[36:37], v24 offset0:66 offset1:74
	ds_read2_b32 v[38:39], v24 offset0:99 offset1:107
	ds_read2_b32 v[40:41], v24 offset0:132 offset1:140
	v_ashrrev_i32_e32 v19, 31, v18
	s_waitcnt lgkmcnt(4)
	s_waitcnt lgkmcnt(3)
	ds_read2_b32 v[42:43], v24 offset0:165 offset1:173
	v_lshl_add_u64 v[32:33], v[18:19], 1, v[10:11]
	v_cvt_pk_bf16_f32 v18, v30, v34
	s_waitcnt lgkmcnt(3)
	s_waitcnt lgkmcnt(2)
	ds_read2_b32 v[44:45], v24 offset0:198 offset1:206
	ds_read2_b32 v[46:47], v24 offset0:231 offset1:239
	v_cvt_pk_bf16_f32 v19, v36, v38
	s_waitcnt lgkmcnt(3)
	s_waitcnt lgkmcnt(2)
	v_cvt_pk_bf16_f32 v20, v40, v42
	s_waitcnt lgkmcnt(1)
	s_waitcnt lgkmcnt(0)
	v_cvt_pk_bf16_f32 v21, v44, v46
	v_or_b32_e32 v3, v28, v23
	v_lshlrev_b32_e32 v4, 12, v3
	v_lshl_add_u64 v[48:49], v[32:33], 0, v[4:5]
	global_store_dwordx4 v[48:49], v[18:21], off
	v_cvt_pk_bf16_f32 v247, v31, v35
	ds_read2_b32 v[30:31], v24 offset0:16 offset1:24
	s_nop 0
	v_mov_b32_e32 v18, v247
	v_cvt_pk_bf16_f32 v19, v37, v39
	v_cvt_pk_bf16_f32 v20, v41, v43
	v_cvt_pk_bf16_f32 v21, v45, v47
	v_or_b32_e32 v3, v28, v25
	v_lshlrev_b32_e32 v4, 12, v3
	v_lshl_add_u64 v[34:35], v[32:33], 0, v[4:5]
	global_store_dwordx4 v[34:35], v[18:21], off
	ds_read2_b32 v[34:35], v24 offset0:49 offset1:57
	ds_read2_b32 v[36:37], v24 offset0:82 offset1:90
	ds_read2_b32 v[38:39], v24 offset0:115 offset1:123
	s_waitcnt lgkmcnt(3)
	s_waitcnt lgkmcnt(2)
	ds_read2_b32 v[40:41], v24 offset0:148 offset1:156
	ds_read2_b32 v[42:43], v24 offset0:181 offset1:189
	v_cvt_pk_bf16_f32 v18, v30, v34
	s_waitcnt lgkmcnt(3)
	s_waitcnt lgkmcnt(2)
	ds_read2_b32 v[44:45], v24 offset0:214 offset1:222
	ds_read2_b32 v[46:47], v24 offset0:247 offset1:255
	v_cvt_pk_bf16_f32 v19, v36, v38
	s_waitcnt lgkmcnt(3)
	s_waitcnt lgkmcnt(2)
	v_cvt_pk_bf16_f32 v20, v40, v42
	s_waitcnt lgkmcnt(1)
	s_waitcnt lgkmcnt(0)
	v_cvt_pk_bf16_f32 v21, v44, v46
	v_or_b32_e32 v3, v28, v26
	v_lshlrev_b32_e32 v4, 12, v3
	v_lshl_add_u64 v[48:49], v[32:33], 0, v[4:5]
	global_store_dwordx4 v[48:49], v[18:21], off
	s_nop 1
	v_cvt_pk_bf16_f32 v18, v31, v35
	v_cvt_pk_bf16_f32 v19, v37, v39
	v_cvt_pk_bf16_f32 v20, v41, v43
	v_cvt_pk_bf16_f32 v21, v45, v47
	v_or_b32_e32 v3, v28, v27
	v_lshlrev_b32_e32 v4, 12, v3
	v_lshl_add_u64 v[28:29], v[32:33], 0, v[4:5]
	global_store_dwordx4 v[28:29], v[18:21], off
	s_waitcnt lgkmcnt(0)
	s_branch .LBB0_599

; #define LAS __attribute__((address_space(3)))
; __device__ __forceinline__ float bflo(unsigned w) { return __uint_as_float(w << 16); }
; __device__ __forceinline__ float bfhi(unsigned w) { return __uint_as_float(w & 0xffff0000u); }
; __device__ __forceinline__ unsigned pk2(float lo, float hi) { return f2bf(lo) | (f2bf(hi) << 16); }
; __device__ __forceinline__ void phase_mixer_a(const Params& P, LAS unsigned char* lds, int ustart, int ustride, bool dry) {
;     ...
;             u32x2 pv[8]; float bsv[8];
; #pragma unroll
;             for (int mt = 0; mt < 8; ++mt) { const int t = 16 * mt + (lane & 15);
;                 pv[mt] = *(const u32x2*)(PJ + T_P + (size_t)(r0 + t) * 1024 + h * 128 + 16 * w + 4 * g4); bsv[mt] = P.b_spatial[h * 128 + t]; }
;             f32x4 acc[8];
; #pragma unroll
;             for (int mt = 0; mt < 8; ++mt) acc[mt] = (f32x4){0.f, 0.f, 0.f, 0.f};
; #pragma unroll
;             for (int ks = 0; ks < 4; ++ks) {
;                 const unsigned a0 = (unsigned)((32 * ks + 8 * g4 + q) * VN_P + 32 * w + 8 * p);
;                 const s16x4 lo = __builtin_amdgcn_ds_read_tr16_b64_v4i16((LAS s16x4*)(lds + a0)), hi = __builtin_amdgcn_ds_read_tr16_b64_v4i16((LAS s16x4*)(lds + a0 + 4 * VN_P));
;                 const bf16x8 vf = (bf16x8){lo[0], lo[1], lo[2], lo[3], hi[0], hi[1], hi[2], hi[3]};
; #pragma unroll
;                 for (int mt = 2 * ks; mt < 8; ++mt) {
;                     const bf16x8 wf = *(const LAS bf16x8*)(lds + W_OFF + (16 * mt + (lane & 15)) * W_P + (32 * ks + 8 * g4) * 2);
;                     acc[mt] = __builtin_amdgcn_mfma_f32_16x16x32_bf16(vf, wf, acc[mt], 0, 0, 0);
;                 }
;             }
; #pragma unroll
;             for (int mt = 0; mt < 8; ++mt) {
;                 const int t = 16 * mt + (lane & 15); const float bs = bsv[mt];
;                 u32x2 o; o.x = pk2(bflo(pv[mt].x) * (acc[mt][0] + bs), bfhi(pv[mt].x) * (acc[mt][1] + bs)); o.y = pk2(bflo(pv[mt].y) * (acc[mt][2] + bs), bfhi(pv[mt].y) * (acc[mt][3] + bs));
;                 if (!dry) *(u32x2*)((bf16_t*)P.out + (size_t)(r0 + t) * 2048 + h * 128 + 16 * w + 4 * g4) = o;
;             }
.LBB0_631:
	ds_read_b64_tr_b16 v[16:17], v163
	ds_read_b64_tr_b16 v[18:19], v163 offset:1152
	v_add_u32_e32 v41, v142, v143
	ds_read_b128 v[20:23], v41 offset:36864
	ds_read_b128 v[24:27], v41 offset:41216
	v_lshl_add_u64 v[128:129], v[94:95], 0, s[16:17]
	v_lshl_add_u64 v[204:205], v[58:59], 0, s[6:7]
	s_waitcnt lgkmcnt(1)
	v_mfma_f32_16x16x32_bf16 v[28:31], v[16:19], v[20:23], 0
	ds_read_b128 v[20:23], v41 offset:45568
	global_load_dwordx2 v[192:193], v[128:129], off
	ds_read_b128 v[128:131], v41 offset:49920
	global_load_dword v206, v[204:205], off
	ds_read_b128 v[168:171], v41 offset:54272
	ds_read_b128 v[172:175], v41 offset:58624
	v_lshl_add_u64 v[188:189], v[96:97], 0, s[16:17]
	v_add_u32_e32 v43, v142, v144
	ds_read_b128 v[176:179], v41 offset:62976
	ds_read_b64_tr_b16 v[180:181], v164
	ds_read_b64_tr_b16 v[182:183], v164 offset:1152
	ds_read_b128 v[184:187], v43 offset:62976
	v_add_u32_e32 v41, v145, v143
	global_load_dwordx2 v[208:209], v[188:189], off
	ds_read_b128 v[188:191], v41 offset:45568
	s_waitcnt lgkmcnt(8)
	v_mfma_f32_16x16x32_bf16 v[20:23], v[16:19], v[20:23], 0
	global_load_dword v210, v[204:205], off offset:64
	v_add_u32_e32 v43, v145, v144
	v_lshl_add_u64 v[200:201], v[98:99], 0, s[16:17]
	v_mfma_f32_16x16x32_bf16 v[24:27], v[16:19], v[24:27], 0
	v_lshl_add_u64 v[202:203], v[100:101], 0, s[16:17]
	v_lshl_add_u64 v[212:213], v[102:103], 0, s[16:17]
	v_lshl_add_u64 v[214:215], v[104:105], 0, s[16:17]
	s_waitcnt lgkmcnt(7)
	v_mfma_f32_16x16x32_bf16 v[128:131], v[16:19], v[128:131], 0
	v_lshl_add_u64 v[216:217], v[106:107], 0, s[16:17]
	v_add_u32_e32 v45, v147, v144
	v_lshl_add_u64 v[218:219], v[108:109], 0, s[16:17]
	s_waitcnt lgkmcnt(6)
	v_mfma_f32_16x16x32_bf16 v[168:171], v[16:19], v[168:171], 0
	v_lshl_add_u64 v[126:127], v[126:127], 0, s[14:15]
	v_lshl_add_u64 v[124:125], v[124:125], 0, s[14:15]
	v_lshl_add_u64 v[122:123], v[122:123], 0, s[14:15]
	s_waitcnt lgkmcnt(5)
	v_mfma_f32_16x16x32_bf16 v[172:175], v[16:19], v[172:175], 0
	v_lshl_add_u64 v[120:121], v[120:121], 0, s[14:15]
	s_waitcnt lgkmcnt(4)
	v_mfma_f32_16x16x32_bf16 v[176:179], v[16:19], v[176:179], 0
	s_waitcnt lgkmcnt(1)
	v_mfma_f32_16x16x32_bf16 v[16:19], v[16:19], v[184:187], 0
	ds_read_b128 v[184:187], v41 offset:49920
	s_waitcnt lgkmcnt(1)
	v_mfma_f32_16x16x32_bf16 v[188:191], v[180:183], v[188:191], v[20:23]
	s_nop 2
	ds_read_b128 v[20:23], v41 offset:54272
	s_waitcnt lgkmcnt(1)
	v_mfma_f32_16x16x32_bf16 v[128:131], v[180:183], v[184:187], v[128:131]
	ds_read_b128 v[184:187], v41 offset:58624
	s_waitcnt lgkmcnt(1)
	v_mfma_f32_16x16x32_bf16 v[20:23], v[180:183], v[20:23], v[168:171]
	s_nop 2
	ds_read_b128 v[168:171], v41 offset:62976
	s_waitcnt lgkmcnt(1)
	v_mfma_f32_16x16x32_bf16 v[172:175], v[180:183], v[184:187], v[172:175]
	ds_read_b64_tr_b16 v[184:185], v165
	ds_read_b64_tr_b16 v[186:187], v165 offset:1152
	ds_read_b128 v[196:199], v43 offset:62976
	v_add_u32_e32 v41, v146, v143
	global_load_dwordx2 v[220:221], v[200:201], off
	s_waitcnt lgkmcnt(3)
	v_mfma_f32_16x16x32_bf16 v[168:171], v[180:183], v[168:171], v[176:179]
	global_load_dword v222, v[204:205], off offset:128
	v_add_u32_e32 v43, v146, v144
	s_nop 0
	ds_read_b128 v[176:179], v41 offset:54272
	s_waitcnt lgkmcnt(1)
	v_mfma_f32_16x16x32_bf16 v[16:19], v[180:183], v[196:199], v[16:19]
	ds_read_b128 v[180:183], v41 offset:58624
	s_waitcnt lgkmcnt(1)
	v_mfma_f32_16x16x32_bf16 v[176:179], v[184:187], v[176:179], v[20:23]
	ds_read_b64_tr_b16 v[196:197], v166
	ds_read_b64_tr_b16 v[198:199], v166 offset:1152
	s_nop 0
	ds_read_b128 v[20:23], v41 offset:62976
	v_add_u32_e32 v41, v147, v143
	s_waitcnt lgkmcnt(3)
	v_mfma_f32_16x16x32_bf16 v[172:175], v[184:187], v[180:183], v[172:175]
	ds_read_b128 v[180:183], v43 offset:62976
	global_load_dwordx2 v[224:225], v[202:203], off
	s_nop 0
	global_load_dwordx2 v[212:213], v[212:213], off
	ds_read_b128 v[200:203], v41 offset:62976
	s_waitcnt lgkmcnt(2)
	v_mfma_f32_16x16x32_bf16 v[168:171], v[184:187], v[20:23], v[168:171]
	s_waitcnt lgkmcnt(1)
	v_mfma_f32_16x16x32_bf16 v[16:19], v[184:187], v[180:183], v[16:19]
	global_load_dwordx2 v[184:185], v[214:215], off
	global_load_dwordx2 v[186:187], v[216:217], off
	global_load_dwordx2 v[20:21], v[218:219], off
	ds_read_b128 v[180:183], v45 offset:62976
	s_waitcnt lgkmcnt(1)
	v_mfma_f32_16x16x32_bf16 v[168:171], v[196:199], v[200:203], v[168:171]
	global_load_dword v200, v[204:205], off offset:192
	global_load_dword v202, v[204:205], off offset:256
	global_load_dword v214, v[204:205], off offset:320
	global_load_dword v216, v[204:205], off offset:384
	global_load_dword v22, v[204:205], off offset:448
	s_waitcnt lgkmcnt(0)
	v_mfma_f32_16x16x32_bf16 v[16:19], v[196:199], v[180:183], v[16:19]
	v_mov_b32_e32 v182, v28
	v_mov_b32_e32 v183, v30
	s_waitcnt vmcnt(15)
	v_lshlrev_b32_e32 v181, 16, v193
	v_lshlrev_b32_e32 v180, 16, v192
	s_waitcnt vmcnt(14)
	v_pk_add_f32 v[182:183], v[206:207], v[182:183] op_sel_hi:[0,1]
	v_mov_b32_e32 v30, v29
	v_pk_mul_f32 v[180:181], v[182:183], v[180:181]
	v_and_b32_e32 v183, 0xffff0000, v193
	v_and_b32_e32 v182, 0xffff0000, v192
	v_pk_add_f32 v[28:29], v[206:207], v[30:31] op_sel_hi:[0,1]
	v_pk_mul_f32 v[28:29], v[28:29], v[182:183]
	v_cvt_pk_bf16_f32 v232, v181, v29
	v_cvt_pk_bf16_f32 v233, v180, v28
	v_mov_b32_e32 v29, v232
	v_mov_b32_e32 v28, v233
	v_lshl_add_u64 v[30:31], v[110:111], 0, s[16:17]
	global_store_dwordx2 v[30:31], v[28:29], off
	v_mov_b32_e32 v30, v24
	v_mov_b32_e32 v31, v26
	s_waitcnt vmcnt(14)
	v_lshlrev_b32_e32 v29, 16, v209
	v_lshlrev_b32_e32 v28, 16, v208
	s_waitcnt vmcnt(13)
; __device__ __forceinline__ float bflo(unsigned w) { return __uint_as_float(w << 16); }
; __device__ __forceinline__ float bfhi(unsigned w) { return __uint_as_float(w & 0xffff0000u); }
; __device__ __forceinline__ unsigned pk2(float lo, float hi) { return f2bf(lo) | (f2bf(hi) << 16); }
; __device__ __forceinline__ void phase_mixer_a(const Params& P, LAS unsigned char* lds, int ustart, int ustride, bool dry) {
;     ...
; #pragma unroll
;             for (int mt = 0; mt < 8; ++mt) {
;                 const int t = 16 * mt + (lane & 15); const float bs = bsv[mt];
;                 u32x2 o; o.x = pk2(bflo(pv[mt].x) * (acc[mt][0] + bs), bfhi(pv[mt].x) * (acc[mt][1] + bs)); o.y = pk2(bflo(pv[mt].y) * (acc[mt][2] + bs), bfhi(pv[mt].y) * (acc[mt][3] + bs));
;                 if (!dry) *(u32x2*)((bf16_t*)P.out + (size_t)(r0 + t) * 2048 + h * 128 + 16 * w + 4 * g4) = o;
;             }
;             __syncthreads();
	v_pk_add_f32 v[30:31], v[210:211], v[30:31] op_sel_hi:[0,1]
	v_mov_b32_e32 v26, v25
	v_pk_mul_f32 v[28:29], v[30:31], v[28:29]
	v_and_b32_e32 v31, 0xffff0000, v209
	v_and_b32_e32 v30, 0xffff0000, v208
	v_pk_add_f32 v[24:25], v[210:211], v[26:27] op_sel_hi:[0,1]
	v_pk_mul_f32 v[24:25], v[24:25], v[30:31]
	v_cvt_pk_bf16_f32 v235, v28, v24
	v_cvt_pk_bf16_f32 v234, v29, v25
	v_mov_b32_e32 v25, v234
	v_mov_b32_e32 v24, v235
	v_lshl_add_u64 v[26:27], v[112:113], 0, s[16:17]
	global_store_dwordx2 v[26:27], v[24:25], off
	v_mov_b32_e32 v26, v188
	v_mov_b32_e32 v27, v190
	s_waitcnt vmcnt(13)
	v_lshlrev_b32_e32 v25, 16, v221
	v_lshlrev_b32_e32 v24, 16, v220
	s_waitcnt vmcnt(12)
	v_pk_add_f32 v[26:27], v[222:223], v[26:27] op_sel_hi:[0,1]
	v_mov_b32_e32 v190, v189
	v_pk_mul_f32 v[24:25], v[26:27], v[24:25]
	v_and_b32_e32 v27, 0xffff0000, v221
	v_and_b32_e32 v26, 0xffff0000, v220
	v_pk_add_f32 v[28:29], v[222:223], v[190:191] op_sel_hi:[0,1]
	v_pk_mul_f32 v[26:27], v[28:29], v[26:27]
	v_cvt_pk_bf16_f32 v252, v24, v26
	v_cvt_pk_bf16_f32 v237, v25, v27
	v_mov_b32_e32 v25, v237
	v_mov_b32_e32 v24, v252
	v_lshl_add_u64 v[26:27], v[114:115], 0, s[16:17]
	global_store_dwordx2 v[26:27], v[24:25], off
	v_mov_b32_e32 v26, v128
	v_mov_b32_e32 v27, v130
	s_waitcnt vmcnt(12)
	v_lshlrev_b32_e32 v25, 16, v225
	v_lshlrev_b32_e32 v24, 16, v224
	s_waitcnt vmcnt(7)
	v_pk_add_f32 v[26:27], v[200:201], v[26:27] op_sel_hi:[0,1]
	v_mov_b32_e32 v130, v129
	v_pk_mul_f32 v[24:25], v[26:27], v[24:25]
	v_and_b32_e32 v27, 0xffff0000, v225
	v_and_b32_e32 v26, 0xffff0000, v224
	v_pk_add_f32 v[28:29], v[200:201], v[130:131] op_sel_hi:[0,1]
	v_pk_mul_f32 v[26:27], v[28:29], v[26:27]
	v_cvt_pk_bf16_f32 v254, v24, v26
	v_cvt_pk_bf16_f32 v253, v25, v27
	v_mov_b32_e32 v25, v253
	v_mov_b32_e32 v24, v254
	v_lshl_add_u64 v[26:27], v[116:117], 0, s[16:17]
	global_store_dwordx2 v[26:27], v[24:25], off
	v_mov_b32_e32 v26, v176
	v_mov_b32_e32 v27, v178
	v_lshlrev_b32_e32 v25, 16, v213
	v_lshlrev_b32_e32 v24, 16, v212
	s_waitcnt vmcnt(7)
	v_pk_add_f32 v[26:27], v[202:203], v[26:27] op_sel_hi:[0,1]
	v_mov_b32_e32 v178, v177
	v_pk_mul_f32 v[24:25], v[26:27], v[24:25]
	v_and_b32_e32 v27, 0xffff0000, v213
	v_and_b32_e32 v26, 0xffff0000, v212
	v_pk_add_f32 v[28:29], v[202:203], v[178:179] op_sel_hi:[0,1]
	v_pk_mul_f32 v[26:27], v[28:29], v[26:27]
	v_cvt_pk_bf16_f32 v232, v24, v26
	v_cvt_pk_bf16_f32 v255, v25, v27
	v_mov_b32_e32 v25, v255
	v_mov_b32_e32 v24, v232
	v_lshl_add_u64 v[26:27], v[118:119], 0, s[16:17]
	global_store_dwordx2 v[26:27], v[24:25], off
	v_mov_b32_e32 v26, v172
	v_mov_b32_e32 v27, v174
	v_lshlrev_b32_e32 v25, 16, v185
	v_lshlrev_b32_e32 v24, 16, v184
	s_waitcnt vmcnt(7)
	v_pk_add_f32 v[26:27], v[214:215], v[26:27] op_sel_hi:[0,1]
	v_mov_b32_e32 v174, v173
	v_pk_mul_f32 v[24:25], v[26:27], v[24:25]
	v_and_b32_e32 v27, 0xffff0000, v185
	v_and_b32_e32 v26, 0xffff0000, v184
	v_pk_add_f32 v[28:29], v[214:215], v[174:175] op_sel_hi:[0,1]
	v_pk_mul_f32 v[26:27], v[28:29], v[26:27]
	v_cvt_pk_bf16_f32 v234, v24, v26
	v_cvt_pk_bf16_f32 v233, v25, v27
	v_mov_b32_e32 v25, v233
	v_mov_b32_e32 v24, v234
	v_lshl_add_u64 v[26:27], v[92:93], 0, s[16:17]
	global_store_dwordx2 v[26:27], v[24:25], off
	v_mov_b32_e32 v26, v168
	v_mov_b32_e32 v27, v170
	v_lshlrev_b32_e32 v25, 16, v187
	v_lshlrev_b32_e32 v24, 16, v186
	s_waitcnt vmcnt(7)
	v_pk_add_f32 v[26:27], v[216:217], v[26:27] op_sel_hi:[0,1]
	v_mov_b32_e32 v170, v169
	v_pk_mul_f32 v[24:25], v[26:27], v[24:25]
	v_and_b32_e32 v27, 0xffff0000, v187
	v_and_b32_e32 v26, 0xffff0000, v186
	v_pk_add_f32 v[28:29], v[216:217], v[170:171] op_sel_hi:[0,1]
	v_pk_mul_f32 v[26:27], v[28:29], v[26:27]
	v_and_b32_sdwa v23, v25, v167 dst_sel:DWORD dst_unused:UNUSED_PAD src0_sel:WORD_1 src1_sel:DWORD
	v_cvt_pk_bf16_f32 v237, v24, v26
	v_add3_u32 v23, v25, v23, s18
	v_cvt_pk_bf16_f32 v235, v25, v27
	v_mov_b32_e32 v25, v235
	v_mov_b32_e32 v24, v237
	v_lshl_add_u64 v[26:27], v[90:91], 0, s[16:17]
	global_store_dwordx2 v[26:27], v[24:25], off
	v_mov_b32_e32 v27, v18
	v_mov_b32_e32 v18, v17
	v_lshlrev_b32_e32 v25, 16, v21
	v_lshlrev_b32_e32 v24, 16, v20
	v_mov_b32_e32 v26, v16
	v_and_b32_e32 v21, 0xffff0000, v21
	v_and_b32_e32 v20, 0xffff0000, v20
	s_waitcnt vmcnt(7)
	v_pk_add_f32 v[16:17], v[22:23], v[18:19] op_sel_hi:[0,1]
	v_pk_add_f32 v[26:27], v[22:23], v[26:27] op_sel_hi:[0,1]
	v_pk_mul_f32 v[16:17], v[16:17], v[20:21]
	v_pk_mul_f32 v[24:25], v[26:27], v[24:25]
	v_cvt_pk_bf16_f32 v252, v25, v17
	v_cvt_pk_bf16_f32 v253, v24, v16
	v_mov_b32_e32 v17, v252
	v_mov_b32_e32 v16, v253
	v_lshl_add_u64 v[18:19], v[88:89], 0, s[16:17]
	s_add_u32 s16, s16, 0x100
	s_addc_u32 s17, s17, 0
	s_add_u32 s6, s6, 0x200
	s_addc_u32 s7, s7, 0
	s_cmpk_eq_i32 s16, 0x800
	global_store_dwordx2 v[18:19], v[16:17], off
	s_barrier
	s_cbranch_scc1 .LBB0_619
; #define LAS __attribute__((address_space(3)))
; __device__ __forceinline__ float bflo(unsigned w) { return __uint_as_float(w << 16); }
; __device__ __forceinline__ float bfhi(unsigned w) { return __uint_as_float(w & 0xffff0000u); }
; __device__ __forceinline__ unsigned pk2(float lo, float hi) { return f2bf(lo) | (f2bf(hi) << 16); }
; __device__ __forceinline__ void phase_mixer_a(const Params& P, LAS unsigned char* lds, int ustart, int ustride, bool dry) {
;     ...
;         for (int h = 0; h < 8; ++h) {
; #pragma unroll
;             for (int i = 0; i < 4; ++i) {
;                 const int item = tid + 512 * i, c8 = item & 15, s = item >> 4;
;                 const u32x4 gv = pgv[i];
;                 const float mean = stats[2 * s], rstd = stats[2 * s + 1];
;                 const f32x4 g0 = *(const f32x4*)(P.ln_v_g + h * 128 + c8 * 8), g1 = *(const f32x4*)(P.ln_v_g + h * 128 + c8 * 8 + 4);
;                 const f32x4 b0 = *(const f32x4*)(P.ln_v_b + h * 128 + c8 * 8), b1 = *(const f32x4*)(P.ln_v_b + h * 128 + c8 * 8 + 4);
;                 u32x4 o;
;                 o.x = pk2((bflo(gv.x) - mean) * rstd * g0[0] + b0[0], (bfhi(gv.x) - mean) * rstd * g0[1] + b0[1]);
;                 o.y = pk2((bflo(gv.y) - mean) * rstd * g0[2] + b0[2], (bfhi(gv.y) - mean) * rstd * g0[3] + b0[3]);
;                 o.z = pk2((bflo(gv.z) - mean) * rstd * g1[0] + b1[0], (bfhi(gv.z) - mean) * rstd * g1[1] + b1[1]);
;                 o.w = pk2((bflo(gv.w) - mean) * rstd * g1[2] + b1[2], (bfhi(gv.w) - mean) * rstd * g1[3] + b1[3]);
;                 *(LAS u32x4*)(lds + s * VN_P + c8 * 16) = o;
;                 *(LAS u32x4*)(lds + W_OFF + s * W_P + c8 * 16) = *(const u32x4*)(WsT + h * 16384 + item * 8);
;             }
;             __syncthreads();
.LBB0_632:
	v_lshl_add_u64 v[16:17], v[62:63], 0, s[6:7]
	global_load_dwordx4 v[24:27], v[16:17], off offset:-16
	v_lshl_add_u64 v[20:21], v[66:67], 0, s[6:7]
	global_load_dwordx4 v[28:31], v[20:21], off offset:-16
	s_nop 0
	global_load_dwordx4 v[16:19], v[16:17], off
	s_nop 0
	global_load_dwordx4 v[20:23], v[20:21], off
	s_nop 0
	global_load_dwordx4 v[168:171], v[126:127], off
	global_load_dwordx4 v[172:175], v[124:125], off
	ds_read_b64 v[128:129], v151
	s_waitcnt vmcnt(9)
	v_lshlrev_b32_e32 v131, 16, v1
	v_lshlrev_b32_e32 v130, 16, v0
	v_and_b32_e32 v177, 0xffff0000, v1
	v_and_b32_e32 v176, 0xffff0000, v0
	v_lshlrev_b32_e32 v179, 16, v3
	v_lshlrev_b32_e32 v178, 16, v2
	v_and_b32_e32 v181, 0xffff0000, v3
	v_and_b32_e32 v180, 0xffff0000, v2
	s_waitcnt lgkmcnt(0)
	v_pk_add_f32 v[130:131], v[130:131], v[128:129] op_sel_hi:[1,0] neg_lo:[0,1] neg_hi:[0,1]
	v_pk_add_f32 v[176:177], v[176:177], v[128:129] op_sel_hi:[1,0] neg_lo:[0,1] neg_hi:[0,1]
	v_pk_add_f32 v[178:179], v[178:179], v[128:129] op_sel_hi:[1,0] neg_lo:[0,1] neg_hi:[0,1]
	v_pk_add_f32 v[180:181], v[180:181], v[128:129] op_sel_hi:[1,0] neg_lo:[0,1] neg_hi:[0,1]
	v_pk_mul_f32 v[188:189], v[128:129], v[130:131] op_sel:[1,0]
	v_pk_mul_f32 v[176:177], v[128:129], v[176:177] op_sel:[1,0]
	v_pk_mul_f32 v[178:179], v[128:129], v[178:179] op_sel:[1,0]
	v_pk_mul_f32 v[180:181], v[128:129], v[180:181] op_sel:[1,0]
	s_waitcnt vmcnt(8)
	v_lshlrev_b32_e32 v183, 16, v5
	v_lshlrev_b32_e32 v182, 16, v4
	v_and_b32_e32 v185, 0xffff0000, v5
	v_and_b32_e32 v184, 0xffff0000, v4
	v_lshlrev_b32_e32 v187, 16, v7
	v_lshlrev_b32_e32 v186, 16, v6
	s_cmpk_lg_i32 s16, 0x700
	s_waitcnt vmcnt(4)
	v_mov_b32_e32 v130, v28
	v_mov_b32_e32 v128, v24
	v_mov_b32_e32 v129, v26
	v_mov_b32_e32 v131, v30
	v_mov_b32_e32 v26, v25
	v_mov_b32_e32 v30, v29
	s_waitcnt vmcnt(3)
	v_mov_b32_e32 v24, v16
	v_mov_b32_e32 v25, v18
	s_waitcnt vmcnt(2)
	v_mov_b32_e32 v28, v20
	v_mov_b32_e32 v29, v22
	v_mov_b32_e32 v18, v17
	v_mov_b32_e32 v22, v21
	v_pk_fma_f32 v[16:17], v[188:189], v[128:129], v[130:131]
	v_pk_fma_f32 v[20:21], v[176:177], v[26:27], v[30:31]
	v_pk_fma_f32 v[176:177], v[178:179], v[24:25], v[28:29]
	v_pk_fma_f32 v[178:179], v[180:181], v[18:19], v[22:23]
	v_cvt_pk_bf16_f32 v255, v16, v20
	v_cvt_pk_bf16_f32 v254, v17, v21
	v_cvt_pk_bf16_f32 v179, v177, v179
	v_cvt_pk_bf16_f32 v178, v176, v178
	v_mov_b32_e32 v177, v254
	v_mov_b32_e32 v176, v255
	ds_write_b128 v152, v[176:179]
	s_waitcnt vmcnt(1)
	ds_write_b128 v153, v[168:171] offset:36864
	ds_read_b64 v[16:17], v154
	global_load_dwordx4 v[168:171], v[122:123], off
	v_and_b32_e32 v21, 0xffff0000, v7
	v_and_b32_e32 v20, 0xffff0000, v6
	s_waitcnt lgkmcnt(0)
	v_pk_add_f32 v[176:177], v[182:183], v[16:17] op_sel_hi:[1,0] neg_lo:[0,1] neg_hi:[0,1]
	v_pk_add_f32 v[178:179], v[184:185], v[16:17] op_sel_hi:[1,0] neg_lo:[0,1] neg_hi:[0,1]
	v_pk_add_f32 v[180:181], v[186:187], v[16:17] op_sel_hi:[1,0] neg_lo:[0,1] neg_hi:[0,1]
	v_pk_add_f32 v[20:21], v[20:21], v[16:17] op_sel_hi:[1,0] neg_lo:[0,1] neg_hi:[0,1]
	v_pk_mul_f32 v[176:177], v[16:17], v[176:177] op_sel:[1,0]
	v_pk_mul_f32 v[178:179], v[16:17], v[178:179] op_sel:[1,0]
	v_pk_mul_f32 v[180:181], v[16:17], v[180:181] op_sel:[1,0]
	v_pk_mul_f32 v[16:17], v[16:17], v[20:21] op_sel:[1,0]
	v_pk_fma_f32 v[20:21], v[128:129], v[176:177], v[130:131]
	v_pk_fma_f32 v[16:17], v[18:19], v[16:17], v[22:23]
	v_pk_fma_f32 v[176:177], v[26:27], v[178:179], v[30:31]
	v_pk_fma_f32 v[178:179], v[24:25], v[180:181], v[28:29]
	v_cvt_pk_bf16_f32 v233, v178, v16
	v_cvt_pk_bf16_f32 v232, v179, v17
	v_cvt_pk_bf16_f32 v234, v21, v177
	v_cvt_pk_bf16_f32 v235, v20, v176
	v_mov_b32_e32 v179, v232
	v_mov_b32_e32 v178, v233
	v_mov_b32_e32 v177, v234
	v_mov_b32_e32 v176, v235
	ds_write_b128 v155, v[176:179]
	s_waitcnt vmcnt(1)
	ds_write_b128 v156, v[172:175] offset:36864
	ds_read_b64 v[16:17], v157
	v_and_b32_e32 v173, 0xffff0000, v9
	v_and_b32_e32 v172, 0xffff0000, v8
	v_lshlrev_b32_e32 v21, 16, v9
	v_lshlrev_b32_e32 v20, 16, v8
	s_waitcnt lgkmcnt(0)
	v_pk_add_f32 v[172:173], v[172:173], v[16:17] op_sel_hi:[1,0] neg_lo:[0,1] neg_hi:[0,1]
	v_and_b32_e32 v181, 0xffff0000, v11
	v_pk_mul_f32 v[172:173], v[16:17], v[172:173] op_sel:[1,0]
	v_and_b32_e32 v180, 0xffff0000, v10
	v_pk_fma_f32 v[176:177], v[26:27], v[172:173], v[30:31]
	v_lshlrev_b32_e32 v173, 16, v11
	v_lshlrev_b32_e32 v172, 16, v10
	v_pk_add_f32 v[172:173], v[172:173], v[16:17] op_sel_hi:[1,0] neg_lo:[0,1] neg_hi:[0,1]
	v_pk_add_f32 v[20:21], v[20:21], v[16:17] op_sel_hi:[1,0] neg_lo:[0,1] neg_hi:[0,1]
	v_pk_mul_f32 v[172:173], v[16:17], v[172:173] op_sel:[1,0]
	v_pk_add_f32 v[180:181], v[180:181], v[16:17] op_sel_hi:[1,0] neg_lo:[0,1] neg_hi:[0,1]
	v_pk_fma_f32 v[178:179], v[24:25], v[172:173], v[28:29]
	global_load_dwordx4 v[172:175], v[120:121], off
	v_pk_mul_f32 v[20:21], v[16:17], v[20:21] op_sel:[1,0]
	v_pk_mul_f32 v[16:17], v[16:17], v[180:181] op_sel:[1,0]
	v_pk_fma_f32 v[20:21], v[128:129], v[20:21], v[130:131]
	v_pk_fma_f32 v[16:17], v[18:19], v[16:17], v[22:23]
	v_cvt_pk_bf16_f32 v252, v178, v16
	v_cvt_pk_bf16_f32 v237, v179, v17
	v_cvt_pk_bf16_f32 v253, v21, v177
	v_cvt_pk_bf16_f32 v254, v20, v176
	v_mov_b32_e32 v179, v237
	v_mov_b32_e32 v178, v252
	v_mov_b32_e32 v177, v253
	v_mov_b32_e32 v176, v254
	ds_write_b128 v158, v[176:179]
	s_waitcnt vmcnt(1)
	ds_write_b128 v159, v[168:171] offset:36864
	ds_read_b64 v[16:17], v160
	v_lshlrev_b32_e32 v21, 16, v13
	v_lshlrev_b32_e32 v20, 16, v12
	s_waitcnt lgkmcnt(0)
	v_pk_add_f32 v[20:21], v[20:21], v[16:17] op_sel_hi:[1,0] neg_lo:[0,1] neg_hi:[0,1]
	s_nop 0
	v_pk_mul_f32 v[20:21], v[16:17], v[20:21] op_sel:[1,0]
	s_nop 0
	v_pk_fma_f32 v[20:21], v[128:129], v[20:21], v[130:131]
	v_and_b32_e32 v129, 0xffff0000, v13
	v_and_b32_e32 v128, 0xffff0000, v12
	v_pk_add_f32 v[128:129], v[128:129], v[16:17] op_sel_hi:[1,0] neg_lo:[0,1] neg_hi:[0,1]
	s_nop 0
	v_pk_mul_f32 v[128:129], v[16:17], v[128:129] op_sel:[1,0]
	s_nop 0
	v_pk_fma_f32 v[26:27], v[26:27], v[128:129], v[30:31]
	v_lshlrev_b32_e32 v31, 16, v15
	v_lshlrev_b32_e32 v30, 16, v14
	v_pk_add_f32 v[30:31], v[30:31], v[16:17] op_sel_hi:[1,0] neg_lo:[0,1] neg_hi:[0,1]
	s_nop 0
	v_pk_mul_f32 v[30:31], v[16:17], v[30:31] op_sel:[1,0]
	s_nop 0
	v_pk_fma_f32 v[24:25], v[24:25], v[30:31], v[28:29]
	v_and_b32_e32 v29, 0xffff0000, v15
	v_and_b32_e32 v28, 0xffff0000, v14
	v_pk_add_f32 v[28:29], v[28:29], v[16:17] op_sel_hi:[1,0] neg_lo:[0,1] neg_hi:[0,1]
	s_nop 0
	v_pk_mul_f32 v[16:17], v[16:17], v[28:29] op_sel:[1,0]
	s_nop 0
	v_pk_fma_f32 v[16:17], v[18:19], v[16:17], v[22:23]
	v_cvt_pk_bf16_f32 v232, v24, v16
	v_cvt_pk_bf16_f32 v255, v25, v17
	v_cvt_pk_bf16_f32 v234, v20, v26
	v_cvt_pk_bf16_f32 v233, v21, v27
	v_mov_b32_e32 v19, v255
	v_mov_b32_e32 v18, v232
	v_mov_b32_e32 v17, v233
	v_mov_b32_e32 v16, v234
	ds_write_b128 v161, v[16:19]
	s_waitcnt vmcnt(0)
	ds_write_b128 v162, v[172:175] offset:36864
	s_waitcnt lgkmcnt(0)
	s_barrier
; __device__ __forceinline__ void phase_mixer_a(const Params& P, LAS unsigned char* lds, int ustart, int ustride, bool dry) {
;     ...
;             if (h + 1 < 8) {
; #pragma unroll
;                 for (int i = 0; i < 4; ++i) { const int item = tid + 512 * i, c8 = item & 15, s = item >> 4;
;                     pgv[i] = *(const u32x4*)(PJ + T_GV + (size_t)(r0 + s) * 1024 + (h + 1) * 128 + c8 * 8); }
;             }
	s_cbranch_scc0 .LBB0_631
	v_lshl_add_u64 v[12:13], v[86:87], 0, s[16:17]
	v_lshl_add_u64 v[8:9], v[84:85], 0, s[16:17]
	v_lshl_add_u64 v[4:5], v[82:83], 0, s[16:17]
	v_lshl_add_u64 v[0:1], v[80:81], 0, s[16:17]
	global_load_dwordx4 v[0:3], v[0:1], off
	s_nop 0
	global_load_dwordx4 v[4:7], v[4:5], off
	s_nop 0
	global_load_dwordx4 v[8:11], v[8:9], off
	s_nop 0
	global_load_dwordx4 v[12:15], v[12:13], off
	s_branch .LBB0_631

; #define LAS __attribute__((address_space(3)))
; __device__ __forceinline__ void tr_item(const float* W, int ldw, int src_col0, int k0, bf16_t* dst, int ldd, int dst_row0, int dst_col0, LAS float* scr, int lane) {
; #pragma unroll 8
;     for (int i = 0; i < 32; ++i) { const int kk = 2 * i + (lane >> 5); scr[kk * 33 + (lane & 31)] = W[(size_t)(k0 + kk) * ldw + src_col0 + (lane & 31)]; }
;     asm volatile("s_waitcnt lgkmcnt(0)" ::: "memory");
; __device__ __forceinline__ void phase_branch_weights(const Params& P, LAS unsigned char* lds, int wstart, int wstride) {
;     ...
;     for (int it = wstart * 8 + wave; it < 3 * I_B; it += wstride * 8) {
;         int r = it;
;         if (r < I_B) { const int kb = r >> 5, nb = r & 31; tr_item(P.w_branch_a, 1024, 32 * nb, 64 * kb, WabT, 2048, 32 * nb, 0, scr, lane); continue; } r -= I_B;
;         if (r < I_B) { const int kb = r >> 5, nb = r & 31; tr_item(P.w_branch_b, 1024, 32 * nb, 64 * kb, WabT, 2048, 32 * nb, 1024, scr, lane); continue; } r -= I_B;
;         { const int kb = r >> 5, nb = r & 31; tr_item(P.w_out, 1024, 32 * nb, 64 * kb, WoT, 1024, 32 * nb, 0, scr, lane); }
.LBB0_640:
	s_lshl_b32 s19, s16, 1
	s_lshl_b32 s20, s17, 1
	v_or_b32_e32 v4, s19, v1
	v_or_b32_e32 v19, s20, v0
	s_add_i32 s21, s19, 4
	s_add_i32 s22, s20, 4
	s_add_i32 s23, s19, 8
	s_add_i32 s24, s20, 8
	s_add_i32 s25, s19, 12
	s_add_i32 s26, s20, 12
	s_add_i32 s27, s19, 16
	s_add_i32 s28, s20, 16
	s_add_i32 s29, s19, 20
	s_add_i32 s30, s20, 20
	s_add_i32 s31, s19, 24
	s_add_i32 s34, s20, 24
	s_add_i32 s19, s19, 28
	s_add_i32 s20, s20, 28
	v_add_u32_e32 v32, v19, v18
	v_or_b32_e32 v29, s21, v1
	v_or_b32_e32 v62, s22, v0
	v_or_b32_e32 v63, s23, v1
	v_or_b32_e32 v64, s24, v0
	v_or_b32_e32 v65, s25, v1
	v_or_b32_e32 v66, s26, v0
	v_or_b32_e32 v67, s27, v1
	v_or_b32_e32 v68, s28, v0
	v_or_b32_e32 v69, s29, v1
	v_or_b32_e32 v70, s30, v0
	v_or_b32_e32 v71, s31, v1
	v_or_b32_e32 v72, s34, v0
	v_or_b32_e32 v73, s19, v1
	v_or_b32_e32 v74, s20, v0
	v_add_u32_e32 v30, v4, v3
	v_ashrrev_i32_e32 v33, 31, v32
	v_add_u32_e32 v34, v29, v3
	v_add_u32_e32 v36, v62, v18
	v_add_u32_e32 v38, v63, v3
	v_add_u32_e32 v40, v64, v18
	v_add_u32_e32 v42, v65, v3
	v_add_u32_e32 v44, v66, v18
	v_add_u32_e32 v46, v67, v3
	v_add_u32_e32 v48, v68, v18
	v_add_u32_e32 v50, v69, v3
	v_add_u32_e32 v52, v70, v18
	v_add_u32_e32 v54, v71, v3
	v_add_u32_e32 v56, v72, v18
	v_add_u32_e32 v58, v73, v3
	v_add_u32_e32 v60, v74, v18
	v_ashrrev_i32_e32 v31, 31, v30
	v_lshlrev_b64 v[32:33], 12, v[32:33]
	v_ashrrev_i32_e32 v37, 31, v36
	v_ashrrev_i32_e32 v35, 31, v34
	v_ashrrev_i32_e32 v41, 31, v40
	v_ashrrev_i32_e32 v39, 31, v38
	v_ashrrev_i32_e32 v45, 31, v44
	v_ashrrev_i32_e32 v43, 31, v42
	v_ashrrev_i32_e32 v49, 31, v48
	v_ashrrev_i32_e32 v47, 31, v46
	v_ashrrev_i32_e32 v53, 31, v52
	v_ashrrev_i32_e32 v51, 31, v50
	v_ashrrev_i32_e32 v57, 31, v56
	v_ashrrev_i32_e32 v55, 31, v54
	v_ashrrev_i32_e32 v61, 31, v60
	v_ashrrev_i32_e32 v59, 31, v58
	v_lshlrev_b64 v[30:31], 12, v[30:31]
	v_lshl_add_u64 v[32:33], v[20:21], 0, v[32:33]
	v_lshlrev_b64 v[34:35], 12, v[34:35]
	v_lshlrev_b64 v[36:37], 12, v[36:37]
	v_lshlrev_b64 v[38:39], 12, v[38:39]
	v_lshlrev_b64 v[40:41], 12, v[40:41]
	v_lshlrev_b64 v[42:43], 12, v[42:43]
	v_lshlrev_b64 v[44:45], 12, v[44:45]
	v_lshlrev_b64 v[46:47], 12, v[46:47]
	v_lshlrev_b64 v[48:49], 12, v[48:49]
	v_lshlrev_b64 v[50:51], 12, v[50:51]
	v_lshlrev_b64 v[52:53], 12, v[52:53]
	v_lshlrev_b64 v[54:55], 12, v[54:55]
	v_lshlrev_b64 v[56:57], 12, v[56:57]
	v_lshlrev_b64 v[58:59], 12, v[58:59]
	v_lshlrev_b64 v[60:61], 12, v[60:61]
	v_lshl_add_u64 v[30:31], v[20:21], 0, v[30:31]
	v_lshl_add_u64 v[36:37], v[20:21], 0, v[36:37]
	v_lshl_add_u64 v[34:35], v[20:21], 0, v[34:35]
	v_lshl_add_u64 v[40:41], v[20:21], 0, v[40:41]
	v_lshl_add_u64 v[38:39], v[20:21], 0, v[38:39]
	v_lshl_add_u64 v[44:45], v[20:21], 0, v[44:45]
	v_lshl_add_u64 v[42:43], v[20:21], 0, v[42:43]
	v_lshl_add_u64 v[48:49], v[20:21], 0, v[48:49]
	v_lshl_add_u64 v[46:47], v[20:21], 0, v[46:47]
	v_lshl_add_u64 v[52:53], v[20:21], 0, v[52:53]
	v_lshl_add_u64 v[50:51], v[20:21], 0, v[50:51]
	v_lshl_add_u64 v[56:57], v[20:21], 0, v[56:57]
	v_lshl_add_u64 v[54:55], v[20:21], 0, v[54:55]
	v_lshl_add_u64 v[60:61], v[20:21], 0, v[60:61]
	v_lshl_add_u64 v[58:59], v[20:21], 0, v[58:59]
	global_load_dword v75, v[32:33], off
	global_load_dword v76, v[30:31], off
	global_load_dword v77, v[36:37], off
	global_load_dword v78, v[34:35], off
	global_load_dword v79, v[40:41], off
	global_load_dword v80, v[38:39], off
	global_load_dword v81, v[44:45], off
	global_load_dword v82, v[42:43], off
	global_load_dword v83, v[48:49], off
	global_load_dword v84, v[46:47], off
	global_load_dword v85, v[52:53], off
	global_load_dword v86, v[50:51], off
	global_load_dword v87, v[56:57], off
	global_load_dword v88, v[54:55], off
	global_load_dword v89, v[60:61], off
	global_load_dword v90, v[58:59], off
	s_add_i32 s17, s17, 16
	s_add_i32 s16, s16, 16
	s_add_i32 s18, s18, -16
	v_mad_u64_u32 v[30:31], s[20:21], v19, s1, v[2:3]
	s_cmp_lg_u32 s18, 0
	v_mad_u64_u32 v[32:33], s[20:21], v4, s1, v[2:3]
	v_mad_u64_u32 v[34:35], s[20:21], v62, s1, v[2:3]
	v_mad_u64_u32 v[36:37], s[20:21], v29, s1, v[2:3]
	v_mad_u64_u32 v[38:39], s[20:21], v64, s1, v[2:3]
	v_mad_u64_u32 v[40:41], s[20:21], v63, s1, v[2:3]
	v_mad_u64_u32 v[42:43], s[20:21], v66, s1, v[2:3]
	v_mad_u64_u32 v[44:45], s[20:21], v65, s1, v[2:3]
	v_mad_u64_u32 v[46:47], s[20:21], v68, s1, v[2:3]
	v_mad_u64_u32 v[48:49], s[20:21], v67, s1, v[2:3]
	v_mad_u64_u32 v[50:51], s[20:21], v70, s1, v[2:3]
	v_mad_u64_u32 v[52:53], s[20:21], v69, s1, v[2:3]
	v_mad_u64_u32 v[54:55], s[20:21], v72, s1, v[2:3]
	v_mad_u64_u32 v[56:57], s[20:21], v71, s1, v[2:3]
	v_mad_u64_u32 v[58:59], s[20:21], v74, s1, v[2:3]
	v_mad_u64_u32 v[60:61], s[20:21], v73, s1, v[2:3]
	s_waitcnt vmcnt(15)
	ds_write_b32 v30, v75
	s_waitcnt vmcnt(14)
	ds_write_b32 v32, v76
	s_waitcnt vmcnt(13)
	ds_write_b32 v34, v77
	s_waitcnt vmcnt(12)
	ds_write_b32 v36, v78
	s_waitcnt vmcnt(11)
	ds_write_b32 v38, v79
	s_waitcnt vmcnt(10)
	ds_write_b32 v40, v80
	s_waitcnt vmcnt(9)
	ds_write_b32 v42, v81
	s_waitcnt vmcnt(8)
	ds_write_b32 v44, v82
	s_waitcnt vmcnt(7)
	ds_write_b32 v46, v83
	s_waitcnt vmcnt(6)
	ds_write_b32 v48, v84
	s_waitcnt vmcnt(5)
	ds_write_b32 v50, v85
	s_waitcnt vmcnt(4)
	ds_write_b32 v52, v86
	s_waitcnt vmcnt(3)
	ds_write_b32 v54, v87
	s_waitcnt vmcnt(2)
	ds_write_b32 v56, v88
	s_waitcnt vmcnt(1)
	ds_write_b32 v58, v89
	s_waitcnt vmcnt(0)
	ds_write_b32 v60, v90
	s_cbranch_scc1 .LBB0_640
; #define LAS __attribute__((address_space(3)))
; __device__ __forceinline__ unsigned pk2(float lo, float hi) { return f2bf(lo) | (f2bf(hi) << 16); }
; __device__ __forceinline__ void tr_item(const float* W, int ldw, int src_col0, int k0, bf16_t* dst, int ldd, int dst_row0, int dst_col0, LAS float* scr, int lane) {
;     ...
;     const int c = lane & 7;
; #pragma unroll
;     for (int j = 0; j < 4; ++j) { const int n = (lane >> 3) + 8 * j; const LAS float* s = scr + (8 * c) * 33 + n;
;         u32x4 o; o.x = pk2(s[0 * 33], s[1 * 33]); o.y = pk2(s[2 * 33], s[3 * 33]); o.z = pk2(s[4 * 33], s[5 * 33]); o.w = pk2(s[6 * 33], s[7 * 33]);
;         *(u32x4*)(dst + (size_t)(dst_row0 + n) * ldd + dst_col0 + k0 + 8 * c) = o; }
;     asm volatile("s_waitcnt lgkmcnt(0)" ::: "memory");
	s_waitcnt lgkmcnt(0)
	ds_read2_b32 v[30:31], v24 offset1:8
	ds_read2_b32 v[34:35], v24 offset0:33 offset1:41
	ds_read2_b32 v[36:37], v24 offset0:66 offset1:74
	ds_read2_b32 v[38:39], v24 offset0:99 offset1:107
	ds_read2_b32 v[40:41], v24 offset0:132 offset1:140
	v_mov_b32_e32 v19, v5
	s_waitcnt lgkmcnt(4)
	s_waitcnt lgkmcnt(3)
	ds_read2_b32 v[42:43], v24 offset0:165 offset1:173
	v_lshl_add_u64 v[32:33], v[18:19], 1, v[6:7]
	v_cvt_pk_bf16_f32 v18, v30, v34
	s_waitcnt lgkmcnt(3)
	s_waitcnt lgkmcnt(2)
	ds_read2_b32 v[44:45], v24 offset0:198 offset1:206
	ds_read2_b32 v[46:47], v24 offset0:231 offset1:239
	v_cvt_pk_bf16_f32 v19, v36, v38
	s_waitcnt lgkmcnt(3)
	s_waitcnt lgkmcnt(2)
	v_cvt_pk_bf16_f32 v20, v40, v42
	s_waitcnt lgkmcnt(1)
	s_waitcnt lgkmcnt(0)
	v_cvt_pk_bf16_f32 v21, v44, v46
	v_or_b32_e32 v3, v28, v23
	v_lshlrev_b32_e32 v4, 11, v3
	v_lshl_add_u64 v[48:49], v[32:33], 0, v[4:5]
	global_store_dwordx4 v[48:49], v[18:21], off
	v_cvt_pk_bf16_f32 v235, v31, v35
	ds_read2_b32 v[30:31], v24 offset0:16 offset1:24
	s_nop 0
	v_mov_b32_e32 v18, v235
	v_cvt_pk_bf16_f32 v19, v37, v39
	v_cvt_pk_bf16_f32 v20, v41, v43
	v_cvt_pk_bf16_f32 v21, v45, v47
	v_or_b32_e32 v3, v28, v25
	v_lshlrev_b32_e32 v4, 11, v3
	v_lshl_add_u64 v[34:35], v[32:33], 0, v[4:5]
	global_store_dwordx4 v[34:35], v[18:21], off
	ds_read2_b32 v[34:35], v24 offset0:49 offset1:57
	ds_read2_b32 v[36:37], v24 offset0:82 offset1:90
	ds_read2_b32 v[38:39], v24 offset0:115 offset1:123
	s_waitcnt lgkmcnt(3)
	s_waitcnt lgkmcnt(2)
	ds_read2_b32 v[40:41], v24 offset0:148 offset1:156
	ds_read2_b32 v[42:43], v24 offset0:181 offset1:189
	v_cvt_pk_bf16_f32 v18, v30, v34
	s_waitcnt lgkmcnt(3)
	s_waitcnt lgkmcnt(2)
	ds_read2_b32 v[44:45], v24 offset0:214 offset1:222
	ds_read2_b32 v[46:47], v24 offset0:247 offset1:255
	v_cvt_pk_bf16_f32 v19, v36, v38
	s_waitcnt lgkmcnt(3)
	s_waitcnt lgkmcnt(2)
	v_cvt_pk_bf16_f32 v20, v40, v42
	s_waitcnt lgkmcnt(1)
	s_waitcnt lgkmcnt(0)
	v_cvt_pk_bf16_f32 v21, v44, v46
	v_or_b32_e32 v3, v28, v26
	v_lshlrev_b32_e32 v4, 11, v3
	v_lshl_add_u64 v[48:49], v[32:33], 0, v[4:5]
	global_store_dwordx4 v[48:49], v[18:21], off
	s_nop 1
	v_cvt_pk_bf16_f32 v18, v31, v35
	v_cvt_pk_bf16_f32 v19, v37, v39
	v_cvt_pk_bf16_f32 v20, v41, v43
	v_cvt_pk_bf16_f32 v21, v45, v47
	v_or_b32_e32 v3, v28, v27
	v_lshlrev_b32_e32 v4, 11, v3
	v_lshl_add_u64 v[28:29], v[32:33], 0, v[4:5]
	global_store_dwordx4 v[28:29], v[18:21], off
	s_waitcnt lgkmcnt(0)

; #define LAS __attribute__((address_space(3)))
; __device__ __forceinline__ void tr_item(const float* W, int ldw, int src_col0, int k0, bf16_t* dst, int ldd, int dst_row0, int dst_col0, LAS float* scr, int lane) {
; #pragma unroll 8
;     for (int i = 0; i < 32; ++i) { const int kk = 2 * i + (lane >> 5); scr[kk * 33 + (lane & 31)] = W[(size_t)(k0 + kk) * ldw + src_col0 + (lane & 31)]; }
;     asm volatile("s_waitcnt lgkmcnt(0)" ::: "memory");
.LBB0_644:
	s_lshl_b32 s19, s16, 1
	s_lshl_b32 s20, s17, 1
	v_or_b32_e32 v4, s19, v1
	v_or_b32_e32 v19, s20, v0
	s_add_i32 s21, s19, 4
	s_add_i32 s22, s20, 4
	s_add_i32 s23, s19, 8
	s_add_i32 s24, s20, 8
	s_add_i32 s25, s19, 12
	s_add_i32 s26, s20, 12
	s_add_i32 s27, s19, 16
	s_add_i32 s28, s20, 16
	s_add_i32 s29, s19, 20
	s_add_i32 s30, s20, 20
	s_add_i32 s31, s19, 24
	s_add_i32 s34, s20, 24
	s_add_i32 s19, s19, 28
	s_add_i32 s20, s20, 28
	v_add_u32_e32 v32, v19, v18
	v_or_b32_e32 v29, s21, v1
	v_or_b32_e32 v62, s22, v0
	v_or_b32_e32 v63, s23, v1
	v_or_b32_e32 v64, s24, v0
	v_or_b32_e32 v65, s25, v1
	v_or_b32_e32 v66, s26, v0
	v_or_b32_e32 v67, s27, v1
	v_or_b32_e32 v68, s28, v0
	v_or_b32_e32 v69, s29, v1
	v_or_b32_e32 v70, s30, v0
	v_or_b32_e32 v71, s31, v1
	v_or_b32_e32 v72, s34, v0
	v_or_b32_e32 v73, s19, v1
	v_or_b32_e32 v74, s20, v0
	v_add_u32_e32 v30, v4, v3
	v_ashrrev_i32_e32 v33, 31, v32
	v_add_u32_e32 v34, v29, v3
	v_add_u32_e32 v36, v62, v18
	v_add_u32_e32 v38, v63, v3
	v_add_u32_e32 v40, v64, v18
	v_add_u32_e32 v42, v65, v3
	v_add_u32_e32 v44, v66, v18
	v_add_u32_e32 v46, v67, v3
	v_add_u32_e32 v48, v68, v18
	v_add_u32_e32 v50, v69, v3
	v_add_u32_e32 v52, v70, v18
	v_add_u32_e32 v54, v71, v3
	v_add_u32_e32 v56, v72, v18
	v_add_u32_e32 v58, v73, v3
	v_add_u32_e32 v60, v74, v18
	v_ashrrev_i32_e32 v31, 31, v30
	v_lshlrev_b64 v[32:33], 12, v[32:33]
	v_ashrrev_i32_e32 v37, 31, v36
	v_ashrrev_i32_e32 v35, 31, v34
	v_ashrrev_i32_e32 v41, 31, v40
	v_ashrrev_i32_e32 v39, 31, v38
	v_ashrrev_i32_e32 v45, 31, v44
	v_ashrrev_i32_e32 v43, 31, v42
	v_ashrrev_i32_e32 v49, 31, v48
	v_ashrrev_i32_e32 v47, 31, v46
	v_ashrrev_i32_e32 v53, 31, v52
	v_ashrrev_i32_e32 v51, 31, v50
	v_ashrrev_i32_e32 v57, 31, v56
	v_ashrrev_i32_e32 v55, 31, v54
	v_ashrrev_i32_e32 v61, 31, v60
	v_ashrrev_i32_e32 v59, 31, v58
	v_lshlrev_b64 v[30:31], 12, v[30:31]
	v_lshl_add_u64 v[32:33], v[20:21], 0, v[32:33]
	v_lshlrev_b64 v[34:35], 12, v[34:35]
	v_lshlrev_b64 v[36:37], 12, v[36:37]
	v_lshlrev_b64 v[38:39], 12, v[38:39]
	v_lshlrev_b64 v[40:41], 12, v[40:41]
	v_lshlrev_b64 v[42:43], 12, v[42:43]
	v_lshlrev_b64 v[44:45], 12, v[44:45]
	v_lshlrev_b64 v[46:47], 12, v[46:47]
	v_lshlrev_b64 v[48:49], 12, v[48:49]
	v_lshlrev_b64 v[50:51], 12, v[50:51]
	v_lshlrev_b64 v[52:53], 12, v[52:53]
	v_lshlrev_b64 v[54:55], 12, v[54:55]
	v_lshlrev_b64 v[56:57], 12, v[56:57]
	v_lshlrev_b64 v[58:59], 12, v[58:59]
	v_lshlrev_b64 v[60:61], 12, v[60:61]
	v_lshl_add_u64 v[30:31], v[20:21], 0, v[30:31]
	v_lshl_add_u64 v[36:37], v[20:21], 0, v[36:37]
	v_lshl_add_u64 v[34:35], v[20:21], 0, v[34:35]
	v_lshl_add_u64 v[40:41], v[20:21], 0, v[40:41]
	v_lshl_add_u64 v[38:39], v[20:21], 0, v[38:39]
	v_lshl_add_u64 v[44:45], v[20:21], 0, v[44:45]
	v_lshl_add_u64 v[42:43], v[20:21], 0, v[42:43]
	v_lshl_add_u64 v[48:49], v[20:21], 0, v[48:49]
	v_lshl_add_u64 v[46:47], v[20:21], 0, v[46:47]
	v_lshl_add_u64 v[52:53], v[20:21], 0, v[52:53]
	v_lshl_add_u64 v[50:51], v[20:21], 0, v[50:51]
	v_lshl_add_u64 v[56:57], v[20:21], 0, v[56:57]
	v_lshl_add_u64 v[54:55], v[20:21], 0, v[54:55]
	v_lshl_add_u64 v[60:61], v[20:21], 0, v[60:61]
	v_lshl_add_u64 v[58:59], v[20:21], 0, v[58:59]
	global_load_dword v75, v[32:33], off
	global_load_dword v76, v[30:31], off
	global_load_dword v77, v[36:37], off
	global_load_dword v78, v[34:35], off
	global_load_dword v79, v[40:41], off
	global_load_dword v80, v[38:39], off
	global_load_dword v81, v[44:45], off
	global_load_dword v82, v[42:43], off
	global_load_dword v83, v[48:49], off
	global_load_dword v84, v[46:47], off
	global_load_dword v85, v[52:53], off
	global_load_dword v86, v[50:51], off
	global_load_dword v87, v[56:57], off
	global_load_dword v88, v[54:55], off
	global_load_dword v89, v[60:61], off
	global_load_dword v90, v[58:59], off
	s_add_i32 s17, s17, 16
	s_add_i32 s16, s16, 16
	s_add_i32 s18, s18, -16
	v_mad_u64_u32 v[30:31], s[20:21], v19, s1, v[2:3]
	s_cmp_lg_u32 s18, 0
	v_mad_u64_u32 v[32:33], s[20:21], v4, s1, v[2:3]
	v_mad_u64_u32 v[34:35], s[20:21], v62, s1, v[2:3]
	v_mad_u64_u32 v[36:37], s[20:21], v29, s1, v[2:3]
	v_mad_u64_u32 v[38:39], s[20:21], v64, s1, v[2:3]
	v_mad_u64_u32 v[40:41], s[20:21], v63, s1, v[2:3]
	v_mad_u64_u32 v[42:43], s[20:21], v66, s1, v[2:3]
	v_mad_u64_u32 v[44:45], s[20:21], v65, s1, v[2:3]
	v_mad_u64_u32 v[46:47], s[20:21], v68, s1, v[2:3]
	v_mad_u64_u32 v[48:49], s[20:21], v67, s1, v[2:3]
	v_mad_u64_u32 v[50:51], s[20:21], v70, s1, v[2:3]
	v_mad_u64_u32 v[52:53], s[20:21], v69, s1, v[2:3]
	v_mad_u64_u32 v[54:55], s[20:21], v72, s1, v[2:3]
	v_mad_u64_u32 v[56:57], s[20:21], v71, s1, v[2:3]
	v_mad_u64_u32 v[58:59], s[20:21], v74, s1, v[2:3]
	v_mad_u64_u32 v[60:61], s[20:21], v73, s1, v[2:3]
	s_waitcnt vmcnt(15)
	ds_write_b32 v30, v75
	s_waitcnt vmcnt(14)
	ds_write_b32 v32, v76
	s_waitcnt vmcnt(13)
	ds_write_b32 v34, v77
	s_waitcnt vmcnt(12)
	ds_write_b32 v36, v78
	s_waitcnt vmcnt(11)
	ds_write_b32 v38, v79
	s_waitcnt vmcnt(10)
	ds_write_b32 v40, v80
	s_waitcnt vmcnt(9)
	ds_write_b32 v42, v81
	s_waitcnt vmcnt(8)
	ds_write_b32 v44, v82
	s_waitcnt vmcnt(7)
	ds_write_b32 v46, v83
	s_waitcnt vmcnt(6)
	ds_write_b32 v48, v84
	s_waitcnt vmcnt(5)
	ds_write_b32 v50, v85
	s_waitcnt vmcnt(4)
	ds_write_b32 v52, v86
	s_waitcnt vmcnt(3)
	ds_write_b32 v54, v87
	s_waitcnt vmcnt(2)
	ds_write_b32 v56, v88
	s_waitcnt vmcnt(1)
	ds_write_b32 v58, v89
	s_waitcnt vmcnt(0)
	ds_write_b32 v60, v90
	s_cbranch_scc1 .LBB0_644
; #define LAS __attribute__((address_space(3)))
; __device__ __forceinline__ unsigned pk2(float lo, float hi) { return f2bf(lo) | (f2bf(hi) << 16); }
; __device__ __forceinline__ void tr_item(const float* W, int ldw, int src_col0, int k0, bf16_t* dst, int ldd, int dst_row0, int dst_col0, LAS float* scr, int lane) {
;     ...
;     const int c = lane & 7;
; #pragma unroll
;     for (int j = 0; j < 4; ++j) { const int n = (lane >> 3) + 8 * j; const LAS float* s = scr + (8 * c) * 33 + n;
;         u32x4 o; o.x = pk2(s[0 * 33], s[1 * 33]); o.y = pk2(s[2 * 33], s[3 * 33]); o.z = pk2(s[4 * 33], s[5 * 33]); o.w = pk2(s[6 * 33], s[7 * 33]);
;         *(u32x4*)(dst + (size_t)(dst_row0 + n) * ldd + dst_col0 + k0 + 8 * c) = o; }
;     asm volatile("s_waitcnt lgkmcnt(0)" ::: "memory");
	s_waitcnt lgkmcnt(0)
	ds_read2_b32 v[30:31], v24 offset1:8
	ds_read2_b32 v[34:35], v24 offset0:33 offset1:41
	ds_read2_b32 v[36:37], v24 offset0:66 offset1:74
	ds_read2_b32 v[38:39], v24 offset0:99 offset1:107
	ds_read2_b32 v[40:41], v24 offset0:132 offset1:140
	v_mov_b32_e32 v19, v5
	s_waitcnt lgkmcnt(4)
	s_waitcnt lgkmcnt(3)
	ds_read2_b32 v[42:43], v24 offset0:165 offset1:173
	v_lshl_add_u64 v[32:33], v[18:19], 1, v[8:9]
	v_cvt_pk_bf16_f32 v18, v30, v34
	s_waitcnt lgkmcnt(3)
	s_waitcnt lgkmcnt(2)
	ds_read2_b32 v[44:45], v24 offset0:198 offset1:206
	ds_read2_b32 v[46:47], v24 offset0:231 offset1:239
	v_cvt_pk_bf16_f32 v19, v36, v38
	s_waitcnt lgkmcnt(3)
	s_waitcnt lgkmcnt(2)
	v_cvt_pk_bf16_f32 v20, v40, v42
	s_waitcnt lgkmcnt(1)
	s_waitcnt lgkmcnt(0)
	v_cvt_pk_bf16_f32 v21, v44, v46
	v_or_b32_e32 v3, v28, v23
	v_lshlrev_b32_e32 v4, 12, v3
	v_lshl_add_u64 v[48:49], v[32:33], 0, v[4:5]
	global_store_dwordx4 v[48:49], v[18:21], off
	v_cvt_pk_bf16_f32 v237, v31, v35
	ds_read2_b32 v[30:31], v24 offset0:16 offset1:24
	s_nop 0
	v_mov_b32_e32 v18, v237
	v_cvt_pk_bf16_f32 v19, v37, v39
	v_cvt_pk_bf16_f32 v20, v41, v43
	v_cvt_pk_bf16_f32 v21, v45, v47
	v_or_b32_e32 v3, v28, v25
	v_lshlrev_b32_e32 v4, 12, v3
	v_lshl_add_u64 v[34:35], v[32:33], 0, v[4:5]
	global_store_dwordx4 v[34:35], v[18:21], off
	ds_read2_b32 v[34:35], v24 offset0:49 offset1:57
	ds_read2_b32 v[36:37], v24 offset0:82 offset1:90
	ds_read2_b32 v[38:39], v24 offset0:115 offset1:123
	s_waitcnt lgkmcnt(3)
	s_waitcnt lgkmcnt(2)
	ds_read2_b32 v[40:41], v24 offset0:148 offset1:156
	ds_read2_b32 v[42:43], v24 offset0:181 offset1:189
	v_cvt_pk_bf16_f32 v18, v30, v34
	s_waitcnt lgkmcnt(3)
	s_waitcnt lgkmcnt(2)
	ds_read2_b32 v[44:45], v24 offset0:214 offset1:222
	ds_read2_b32 v[46:47], v24 offset0:247 offset1:255
	v_cvt_pk_bf16_f32 v19, v36, v38
	s_waitcnt lgkmcnt(3)
	s_waitcnt lgkmcnt(2)
	v_cvt_pk_bf16_f32 v20, v40, v42
	s_waitcnt lgkmcnt(1)
	s_waitcnt lgkmcnt(0)
	v_cvt_pk_bf16_f32 v21, v44, v46
	v_or_b32_e32 v3, v28, v26
	v_lshlrev_b32_e32 v4, 12, v3
	v_lshl_add_u64 v[48:49], v[32:33], 0, v[4:5]
	global_store_dwordx4 v[48:49], v[18:21], off
	s_nop 1
	v_cvt_pk_bf16_f32 v18, v31, v35
	v_cvt_pk_bf16_f32 v19, v37, v39
	v_cvt_pk_bf16_f32 v20, v41, v43
	v_cvt_pk_bf16_f32 v21, v45, v47
	v_or_b32_e32 v3, v28, v27
	v_lshlrev_b32_e32 v4, 12, v3
	v_lshl_add_u64 v[28:29], v[32:33], 0, v[4:5]
	global_store_dwordx4 v[28:29], v[18:21], off
	s_waitcnt lgkmcnt(0)

; #define LAS __attribute__((address_space(3)))
; __device__ __forceinline__ void tr_item(const float* W, int ldw, int src_col0, int k0, bf16_t* dst, int ldd, int dst_row0, int dst_col0, LAS float* scr, int lane) {
; #pragma unroll 8
;     for (int i = 0; i < 32; ++i) { const int kk = 2 * i + (lane >> 5); scr[kk * 33 + (lane & 31)] = W[(size_t)(k0 + kk) * ldw + src_col0 + (lane & 31)]; }
;     asm volatile("s_waitcnt lgkmcnt(0)" ::: "memory");
.LBB0_649:
	s_lshl_b32 s17, s10, 1
	s_lshl_b32 s18, s11, 1
	v_or_b32_e32 v4, s17, v1
	v_or_b32_e32 v19, s18, v0
	s_add_i32 s19, s17, 4
	s_add_i32 s20, s18, 4
	s_add_i32 s21, s17, 8
	s_add_i32 s22, s18, 8
	s_add_i32 s23, s17, 12
	s_add_i32 s24, s18, 12
	s_add_i32 s25, s17, 16
	s_add_i32 s26, s18, 16
	s_add_i32 s27, s17, 20
	s_add_i32 s28, s18, 20
	s_add_i32 s29, s17, 24
	s_add_i32 s30, s18, 24
	s_add_i32 s17, s17, 28
	s_add_i32 s18, s18, 28
	v_add_u32_e32 v32, v19, v18
	v_or_b32_e32 v29, s19, v1
	v_or_b32_e32 v62, s20, v0
	v_or_b32_e32 v63, s21, v1
	v_or_b32_e32 v64, s22, v0
	v_or_b32_e32 v65, s23, v1
	v_or_b32_e32 v66, s24, v0
	v_or_b32_e32 v67, s25, v1
	v_or_b32_e32 v68, s26, v0
	v_or_b32_e32 v69, s27, v1
	v_or_b32_e32 v70, s28, v0
	v_or_b32_e32 v71, s29, v1
	v_or_b32_e32 v72, s30, v0
	v_or_b32_e32 v73, s17, v1
	v_or_b32_e32 v74, s18, v0
	v_add_u32_e32 v30, v4, v3
	v_ashrrev_i32_e32 v33, 31, v32
	v_add_u32_e32 v34, v29, v3
	v_add_u32_e32 v36, v62, v18
	v_add_u32_e32 v38, v63, v3
	v_add_u32_e32 v40, v64, v18
	v_add_u32_e32 v42, v65, v3
	v_add_u32_e32 v44, v66, v18
	v_add_u32_e32 v46, v67, v3
	v_add_u32_e32 v48, v68, v18
	v_add_u32_e32 v50, v69, v3
	v_add_u32_e32 v52, v70, v18
	v_add_u32_e32 v54, v71, v3
	v_add_u32_e32 v56, v72, v18
	v_add_u32_e32 v58, v73, v3
	v_add_u32_e32 v60, v74, v18
	v_ashrrev_i32_e32 v31, 31, v30
	v_lshlrev_b64 v[32:33], 12, v[32:33]
	v_ashrrev_i32_e32 v37, 31, v36
	v_ashrrev_i32_e32 v35, 31, v34
	v_ashrrev_i32_e32 v41, 31, v40
	v_ashrrev_i32_e32 v39, 31, v38
	v_ashrrev_i32_e32 v45, 31, v44
	v_ashrrev_i32_e32 v43, 31, v42
	v_ashrrev_i32_e32 v49, 31, v48
	v_ashrrev_i32_e32 v47, 31, v46
	v_ashrrev_i32_e32 v53, 31, v52
	v_ashrrev_i32_e32 v51, 31, v50
	v_ashrrev_i32_e32 v57, 31, v56
	v_ashrrev_i32_e32 v55, 31, v54
	v_ashrrev_i32_e32 v61, 31, v60
	v_ashrrev_i32_e32 v59, 31, v58
	v_lshlrev_b64 v[30:31], 12, v[30:31]
	v_lshl_add_u64 v[32:33], v[20:21], 0, v[32:33]
	v_lshlrev_b64 v[34:35], 12, v[34:35]
	v_lshlrev_b64 v[36:37], 12, v[36:37]
	v_lshlrev_b64 v[38:39], 12, v[38:39]
	v_lshlrev_b64 v[40:41], 12, v[40:41]
	v_lshlrev_b64 v[42:43], 12, v[42:43]
	v_lshlrev_b64 v[44:45], 12, v[44:45]
	v_lshlrev_b64 v[46:47], 12, v[46:47]
	v_lshlrev_b64 v[48:49], 12, v[48:49]
	v_lshlrev_b64 v[50:51], 12, v[50:51]
	v_lshlrev_b64 v[52:53], 12, v[52:53]
	v_lshlrev_b64 v[54:55], 12, v[54:55]
	v_lshlrev_b64 v[56:57], 12, v[56:57]
	v_lshlrev_b64 v[58:59], 12, v[58:59]
	v_lshlrev_b64 v[60:61], 12, v[60:61]
	v_lshl_add_u64 v[30:31], v[20:21], 0, v[30:31]
	v_lshl_add_u64 v[36:37], v[20:21], 0, v[36:37]
	v_lshl_add_u64 v[34:35], v[20:21], 0, v[34:35]
	v_lshl_add_u64 v[40:41], v[20:21], 0, v[40:41]
	v_lshl_add_u64 v[38:39], v[20:21], 0, v[38:39]
	v_lshl_add_u64 v[44:45], v[20:21], 0, v[44:45]
	v_lshl_add_u64 v[42:43], v[20:21], 0, v[42:43]
	v_lshl_add_u64 v[48:49], v[20:21], 0, v[48:49]
	v_lshl_add_u64 v[46:47], v[20:21], 0, v[46:47]
	v_lshl_add_u64 v[52:53], v[20:21], 0, v[52:53]
	v_lshl_add_u64 v[50:51], v[20:21], 0, v[50:51]
	v_lshl_add_u64 v[56:57], v[20:21], 0, v[56:57]
	v_lshl_add_u64 v[54:55], v[20:21], 0, v[54:55]
	v_lshl_add_u64 v[60:61], v[20:21], 0, v[60:61]
	v_lshl_add_u64 v[58:59], v[20:21], 0, v[58:59]
	global_load_dword v75, v[32:33], off
	global_load_dword v76, v[30:31], off
	global_load_dword v77, v[36:37], off
	global_load_dword v78, v[34:35], off
	global_load_dword v79, v[40:41], off
	global_load_dword v80, v[38:39], off
	global_load_dword v81, v[44:45], off
	global_load_dword v82, v[42:43], off
	global_load_dword v83, v[48:49], off
	global_load_dword v84, v[46:47], off
	global_load_dword v85, v[52:53], off
	global_load_dword v86, v[50:51], off
	global_load_dword v87, v[56:57], off
	global_load_dword v88, v[54:55], off
	global_load_dword v89, v[60:61], off
	global_load_dword v90, v[58:59], off
	s_add_i32 s11, s11, 16
	s_add_i32 s10, s10, 16
	s_add_i32 s16, s16, -16
	v_mad_u64_u32 v[30:31], s[18:19], v19, s1, v[2:3]
	s_cmp_lg_u32 s16, 0
	v_mad_u64_u32 v[32:33], s[18:19], v4, s1, v[2:3]
	v_mad_u64_u32 v[34:35], s[18:19], v62, s1, v[2:3]
	v_mad_u64_u32 v[36:37], s[18:19], v29, s1, v[2:3]
	v_mad_u64_u32 v[38:39], s[18:19], v64, s1, v[2:3]
	v_mad_u64_u32 v[40:41], s[18:19], v63, s1, v[2:3]
	v_mad_u64_u32 v[42:43], s[18:19], v66, s1, v[2:3]
	v_mad_u64_u32 v[44:45], s[18:19], v65, s1, v[2:3]
	v_mad_u64_u32 v[46:47], s[18:19], v68, s1, v[2:3]
	v_mad_u64_u32 v[48:49], s[18:19], v67, s1, v[2:3]
	v_mad_u64_u32 v[50:51], s[18:19], v70, s1, v[2:3]
	v_mad_u64_u32 v[52:53], s[18:19], v69, s1, v[2:3]
	v_mad_u64_u32 v[54:55], s[18:19], v72, s1, v[2:3]
	v_mad_u64_u32 v[56:57], s[18:19], v71, s1, v[2:3]
	v_mad_u64_u32 v[58:59], s[18:19], v74, s1, v[2:3]
	v_mad_u64_u32 v[60:61], s[18:19], v73, s1, v[2:3]
	s_waitcnt vmcnt(15)
	ds_write_b32 v30, v75
	s_waitcnt vmcnt(14)
	ds_write_b32 v32, v76
	s_waitcnt vmcnt(13)
	ds_write_b32 v34, v77
	s_waitcnt vmcnt(12)
	ds_write_b32 v36, v78
	s_waitcnt vmcnt(11)
	ds_write_b32 v38, v79
	s_waitcnt vmcnt(10)
	ds_write_b32 v40, v80
	s_waitcnt vmcnt(9)
	ds_write_b32 v42, v81
	s_waitcnt vmcnt(8)
	ds_write_b32 v44, v82
	s_waitcnt vmcnt(7)
	ds_write_b32 v46, v83
	s_waitcnt vmcnt(6)
	ds_write_b32 v48, v84
	s_waitcnt vmcnt(5)
	ds_write_b32 v50, v85
	s_waitcnt vmcnt(4)
	ds_write_b32 v52, v86
	s_waitcnt vmcnt(3)
	ds_write_b32 v54, v87
	s_waitcnt vmcnt(2)
	ds_write_b32 v56, v88
	s_waitcnt vmcnt(1)
	ds_write_b32 v58, v89
	s_waitcnt vmcnt(0)
	ds_write_b32 v60, v90
	s_cbranch_scc1 .LBB0_649
; #define LAS __attribute__((address_space(3)))
; __device__ __forceinline__ unsigned pk2(float lo, float hi) { return f2bf(lo) | (f2bf(hi) << 16); }
; __device__ __forceinline__ void tr_item(const float* W, int ldw, int src_col0, int k0, bf16_t* dst, int ldd, int dst_row0, int dst_col0, LAS float* scr, int lane) {
;     ...
;     const int c = lane & 7;
; #pragma unroll
;     for (int j = 0; j < 4; ++j) { const int n = (lane >> 3) + 8 * j; const LAS float* s = scr + (8 * c) * 33 + n;
;         u32x4 o; o.x = pk2(s[0 * 33], s[1 * 33]); o.y = pk2(s[2 * 33], s[3 * 33]); o.z = pk2(s[4 * 33], s[5 * 33]); o.w = pk2(s[6 * 33], s[7 * 33]);
;         *(u32x4*)(dst + (size_t)(dst_row0 + n) * ldd + dst_col0 + k0 + 8 * c) = o; }
;     asm volatile("s_waitcnt lgkmcnt(0)" ::: "memory");
; __device__ __forceinline__ void phase_branch_weights(const Params& P, LAS unsigned char* lds, int wstart, int wstride) {
;     ...
;     for (int it = wstart * 8 + wave; it < 3 * I_B; it += wstride * 8) {
;         int r = it;
;         if (r < I_B) { const int kb = r >> 5, nb = r & 31; tr_item(P.w_branch_a, 1024, 32 * nb, 64 * kb, WabT, 2048, 32 * nb, 0, scr, lane); continue; } r -= I_B;
;         if (r < I_B) { const int kb = r >> 5, nb = r & 31; tr_item(P.w_branch_b, 1024, 32 * nb, 64 * kb, WabT, 2048, 32 * nb, 1024, scr, lane); continue; } r -= I_B;
;         { const int kb = r >> 5, nb = r & 31; tr_item(P.w_out, 1024, 32 * nb, 64 * kb, WoT, 1024, 32 * nb, 0, scr, lane); }
;     }
	s_waitcnt lgkmcnt(0)
	ds_read2_b32 v[30:31], v24 offset1:8
	ds_read2_b32 v[34:35], v24 offset0:33 offset1:41
	ds_read2_b32 v[36:37], v24 offset0:66 offset1:74
	ds_read2_b32 v[38:39], v24 offset0:99 offset1:107
	ds_read2_b32 v[40:41], v24 offset0:132 offset1:140
	v_ashrrev_i32_e32 v19, 31, v18
	s_waitcnt lgkmcnt(4)
	s_waitcnt lgkmcnt(3)
	ds_read2_b32 v[42:43], v24 offset0:165 offset1:173
	v_lshl_add_u64 v[32:33], v[18:19], 1, v[10:11]
	v_cvt_pk_bf16_f32 v18, v30, v34
	s_waitcnt lgkmcnt(3)
	s_waitcnt lgkmcnt(2)
	ds_read2_b32 v[44:45], v24 offset0:198 offset1:206
	ds_read2_b32 v[46:47], v24 offset0:231 offset1:239
	v_cvt_pk_bf16_f32 v19, v36, v38
	s_waitcnt lgkmcnt(3)
	s_waitcnt lgkmcnt(2)
	v_cvt_pk_bf16_f32 v20, v40, v42
	s_waitcnt lgkmcnt(1)
	s_waitcnt lgkmcnt(0)
	v_cvt_pk_bf16_f32 v21, v44, v46
	v_or_b32_e32 v3, v28, v23
	v_lshlrev_b32_e32 v4, 12, v3
	v_lshl_add_u64 v[48:49], v[32:33], 0, v[4:5]
	global_store_dwordx4 v[48:49], v[18:21], off
	v_cvt_pk_bf16_f32 v252, v31, v35
	ds_read2_b32 v[30:31], v24 offset0:16 offset1:24
	s_nop 0
	v_mov_b32_e32 v18, v252
	v_cvt_pk_bf16_f32 v19, v37, v39
	v_cvt_pk_bf16_f32 v20, v41, v43
	v_cvt_pk_bf16_f32 v21, v45, v47
	v_or_b32_e32 v3, v28, v25
	v_lshlrev_b32_e32 v4, 12, v3
	v_lshl_add_u64 v[34:35], v[32:33], 0, v[4:5]
	global_store_dwordx4 v[34:35], v[18:21], off
	ds_read2_b32 v[34:35], v24 offset0:49 offset1:57
	ds_read2_b32 v[36:37], v24 offset0:82 offset1:90
	ds_read2_b32 v[38:39], v24 offset0:115 offset1:123
	s_waitcnt lgkmcnt(3)
	s_waitcnt lgkmcnt(2)
	ds_read2_b32 v[40:41], v24 offset0:148 offset1:156
	ds_read2_b32 v[42:43], v24 offset0:181 offset1:189
	v_cvt_pk_bf16_f32 v18, v30, v34
	s_waitcnt lgkmcnt(3)
	s_waitcnt lgkmcnt(2)
	ds_read2_b32 v[44:45], v24 offset0:214 offset1:222
	ds_read2_b32 v[46:47], v24 offset0:247 offset1:255
	v_cvt_pk_bf16_f32 v19, v36, v38
	s_waitcnt lgkmcnt(3)
	s_waitcnt lgkmcnt(2)
	v_cvt_pk_bf16_f32 v20, v40, v42
	s_waitcnt lgkmcnt(1)
	s_waitcnt lgkmcnt(0)
	v_cvt_pk_bf16_f32 v21, v44, v46
	v_or_b32_e32 v3, v28, v26
	v_lshlrev_b32_e32 v4, 12, v3
	v_lshl_add_u64 v[48:49], v[32:33], 0, v[4:5]
	global_store_dwordx4 v[48:49], v[18:21], off
	s_nop 1
	v_cvt_pk_bf16_f32 v18, v31, v35
	v_cvt_pk_bf16_f32 v19, v37, v39
	v_cvt_pk_bf16_f32 v20, v41, v43
	v_cvt_pk_bf16_f32 v21, v45, v47
	v_or_b32_e32 v3, v28, v27
	v_lshlrev_b32_e32 v4, 12, v3
	v_lshl_add_u64 v[28:29], v[32:33], 0, v[4:5]
	global_store_dwordx4 v[28:29], v[18:21], off
	s_waitcnt lgkmcnt(0)
	s_branch .LBB0_636

; #define LAS __attribute__((address_space(3)))
; __device__ __forceinline__ float bflo(unsigned w) { return __uint_as_float(w << 16); }
; __device__ __forceinline__ float bfhi(unsigned w) { return __uint_as_float(w & 0xffff0000u); }
; __device__ __forceinline__ unsigned pk2(float lo, float hi) { return f2bf(lo) | (f2bf(hi) << 16); }
; template <bool FULL>
; __device__ __forceinline__ void gla_pass(const Params& P, LAS unsigned char* lds, f32x4 (&S)[8][2], int bh, int c0, int L, bool dry) {
;     ...
;         if (FULL) {
;             f32x4 gn[2];
; #pragma unroll
;             for (int vt = 0; vt < 2; ++vt) gn[vt] = *(const f32x4*)(P.gla_norm_g + 32 * w + 4 * g + 16 * vt);
; #pragma unroll
;             for (int tt = 0; tt < 4; ++tt) {
;                 const int t = 16 * tt + fr;
;                 const f32x4 r0 = *(const LAS f32x4*)(red + t * 8), r1 = *(const LAS f32x4*)(red + t * 8 + 4);
;                 const float rstd = 1.0f / sqrtf(((r0[0] + r0[1]) + (r0[2] + r0[3]) + (r1[0] + r1[1]) + (r1[2] + r1[3])) * (1.0f / 256.0f) + RMS_EPS);
; #pragma unroll
;                 for (int vt = 0; vt < 2; ++vt) {
;                     bf16_t* op = (bf16_t*)P.out + (row0 + t) * 2048 + 1024 + h * 256 + 32 * w + 16 * vt + 4 * g;
;                     const u32x2 z = zb[vt][tt]; const f32x4 ov = o[vt][tt] * rstd * gn[vt];
;                     u32x2 r; r.x = pk2(ov[0] * bflo(z.x), ov[1] * bfhi(z.x)); r.y = pk2(ov[2] * bflo(z.y), ov[3] * bfhi(z.y));
;                     if (!dry) *(u32x2*)op = r;
;                 }
;             }
.LBB0_698:
	v_mov_b32_e32 v140, v238
	v_mov_b32_e32 v141, v239
	v_mov_b32_e32 v142, v240
	v_mov_b32_e32 v143, v241
	v_mov_b32_e32 v136, v242
	v_mov_b32_e32 v137, v243
	v_mov_b32_e32 v138, v244
	v_mov_b32_e32 v139, v245
	ds_read_b128 v[208:211], v190
	ds_read_b128 v[212:215], v190 offset:16
	s_waitcnt vmcnt(7)
	v_lshlrev_b32_e32 v217, 16, v181
	v_lshlrev_b32_e32 v216, 16, v180
	v_and_b32_e32 v181, 0xffff0000, v181
	s_waitcnt lgkmcnt(1)
	v_mov_b32_e32 v220, v209
	v_mov_b32_e32 v221, v210
	v_mov_b32_e32 v209, v211
	s_waitcnt lgkmcnt(0)
	v_mov_b32_e32 v210, v214
	v_mov_b32_e32 v211, v212
	v_mov_b32_e32 v212, v215
	v_pk_add_f32 v[208:209], v[220:221], v[208:209]
	v_pk_add_f32 v[210:211], v[210:211], v[212:213]
	v_add_f32_e32 v208, v208, v209
	v_add_f32_e32 v208, v208, v211
	v_add_f32_e32 v208, v210, v208
	v_fmamk_f32 v208, v208, 0x3b800000, v202
	v_mul_f32_e32 v209, 0x4f800000, v208
	v_cmp_gt_f32_e32 vcc, s26, v208
	v_and_b32_e32 v180, 0xffff0000, v180
	s_waitcnt vmcnt(4)
	v_lshlrev_b32_e32 v219, 16, v179
	v_cndmask_b32_e32 v210, v208, v209, vcc
	v_sqrt_f32_e32 v211, v210
	v_lshlrev_b32_e32 v218, 16, v178
	v_and_b32_e32 v179, 0xffff0000, v179
	v_and_b32_e32 v178, 0xffff0000, v178
	v_add_u32_e32 v212, -1, v211
	v_add_u32_e32 v213, 1, v211
	v_fma_f32 v214, -v212, v211, v210
	v_fma_f32 v215, -v213, v211, v210
	v_cmp_ge_f32_e64 s[8:9], 0, v214
	v_add_u32_e32 v160, s27, v193
	v_lshlrev_b64 v[208:209], 12, v[160:161]
	v_cndmask_b32_e64 v211, v211, v212, s[8:9]
	v_cmp_lt_f32_e64 s[8:9], 0, v215
	v_lshl_add_u64 v[208:209], v[168:169], 0, v[208:209]
	s_add_i32 s27, s27, 64
	v_cndmask_b32_e64 v211, v211, v213, s[8:9]
	v_mul_f32_e32 v212, 0x37800000, v211
	v_cndmask_b32_e32 v211, v211, v212, vcc
	v_cmp_class_f32_e32 vcc, v210, v203
	s_add_i32 s0, s0, 1
	v_lshl_add_u64 v[170:171], v[170:171], 0, s[14:15]
	v_cndmask_b32_e32 v210, v211, v210, vcc
	v_div_scale_f32 v211, s[8:9], v210, v210, 1.0
	v_rcp_f32_e32 v212, v211
	v_div_scale_f32 v213, vcc, 1.0, v210, 1.0
	s_cmpk_eq_i32 s27, 0x400
	v_fma_f32 v214, -v211, v212, 1.0
	v_fmac_f32_e32 v212, v214, v212
	v_mul_f32_e32 v214, v213, v212
	v_fma_f32 v215, -v211, v214, v213
	v_fmac_f32_e32 v214, v215, v212
	v_fma_f32 v211, -v211, v214, v213
	v_div_fmas_f32 v211, v211, v212, v214
	v_div_fixup_f32 v210, v211, v210, 1.0
	v_pk_mul_f32 v[134:135], v[134:135], v[210:211] op_sel_hi:[1,0]
	v_pk_mul_f32 v[132:133], v[132:133], v[210:211] op_sel_hi:[1,0]
	v_pk_mul_f32 v[130:131], v[130:131], v[210:211] op_sel_hi:[1,0]
	v_pk_mul_f32 v[128:129], v[128:129], v[210:211] op_sel_hi:[1,0]
	v_lshl_add_u64 v[172:173], v[172:173], 0, s[16:17]
	s_waitcnt vmcnt(0)
	v_pk_mul_f32 v[132:133], v[140:141], v[132:133]
	v_pk_mul_f32 v[134:135], v[142:143], v[134:135]
	v_pk_mul_f32 v[128:129], v[136:137], v[128:129]
	v_pk_mul_f32 v[130:131], v[138:139], v[130:131]
	v_mov_b32_e32 v210, v132
	v_mov_b32_e32 v211, v134
	v_mov_b32_e32 v134, v133
	v_mov_b32_e32 v132, v128
	v_mov_b32_e32 v133, v130
	v_mov_b32_e32 v130, v129
	v_pk_mul_f32 v[128:129], v[210:211], v[216:217]
	v_pk_mul_f32 v[134:135], v[134:135], v[180:181]
	v_pk_mul_f32 v[178:179], v[130:131], v[178:179]
	v_cvt_pk_bf16_f32 v254, v128, v134
	v_cvt_pk_bf16_f32 v253, v129, v135
	v_pk_mul_f32 v[132:133], v[132:133], v[218:219]
	v_mov_b32_e32 v129, v253
	v_mov_b32_e32 v128, v254
	global_store_dwordx2 v[208:209], v[128:129], off offset:2048
	ds_read_b128 v[128:131], v205
	v_cvt_pk_bf16_f32 v232, v132, v178
	v_cvt_pk_bf16_f32 v255, v133, v179
	ds_read_b128 v[132:135], v205 offset:16
	s_waitcnt lgkmcnt(1)
	v_mov_b32_e32 v180, v129
	v_mov_b32_e32 v181, v130
	v_mov_b32_e32 v129, v131
	v_pk_add_f32 v[128:129], v[180:181], v[128:129]
	s_waitcnt lgkmcnt(0)
	v_mov_b32_e32 v130, v134
	v_mov_b32_e32 v131, v132
	v_mov_b32_e32 v132, v135
	v_pk_add_f32 v[130:131], v[130:131], v[132:133]
	v_add_f32_e32 v128, v128, v129
	v_add_f32_e32 v128, v128, v131
	v_add_f32_e32 v128, v130, v128
	v_fmamk_f32 v128, v128, 0x3b800000, v202
	v_mul_f32_e32 v129, 0x4f800000, v128
	v_cmp_gt_f32_e32 vcc, s26, v128
	s_nop 1
	v_cndmask_b32_e32 v128, v128, v129, vcc
	v_sqrt_f32_e32 v129, v128
	s_nop 0
	v_add_u32_e32 v132, -1, v129
	v_fma_f32 v133, -v132, v129, v128
	v_cmp_ge_f32_e64 s[8:9], 0, v133
	v_add_u32_e32 v133, 1, v129
	s_nop 0
	v_cndmask_b32_e64 v132, v129, v132, s[8:9]
	v_fma_f32 v129, -v133, v129, v128
	v_cmp_lt_f32_e64 s[8:9], 0, v129
	s_nop 1
	v_cndmask_b32_e64 v129, v132, v133, s[8:9]
	v_mul_f32_e32 v132, 0x37800000, v129
	v_cndmask_b32_e32 v129, v129, v132, vcc
	v_cmp_class_f32_e32 vcc, v128, v203
	s_nop 1
	v_cndmask_b32_e32 v132, v129, v128, vcc
	v_div_scale_f32 v133, s[8:9], v132, v132, 1.0
	v_rcp_f32_e32 v134, v133
	v_mov_b32_e32 v129, v255
	v_mov_b32_e32 v128, v232
	global_store_dwordx2 v[208:209], v[128:129], off offset:2080
	v_fma_f32 v128, -v133, v134, 1.0
	v_fmac_f32_e32 v134, v128, v134
	v_div_scale_f32 v128, vcc, 1.0, v132, 1.0
	v_mul_f32_e32 v129, v128, v134
	v_fma_f32 v130, -v133, v129, v128
	v_fmac_f32_e32 v129, v130, v134
	v_fma_f32 v128, -v133, v129, v128
	v_div_fmas_f32 v128, v128, v134, v129
	v_div_fixup_f32 v128, v128, v132, 1.0
	v_pk_mul_f32 v[126:127], v[126:127], v[128:129] op_sel_hi:[1,0]
	v_pk_mul_f32 v[124:125], v[124:125], v[128:129] op_sel_hi:[1,0]
	v_pk_mul_f32 v[126:127], v[142:143], v[126:127]
	v_pk_mul_f32 v[124:125], v[140:141], v[124:125]
	v_lshlrev_b32_e32 v133, 16, v177
	v_lshlrev_b32_e32 v132, 16, v176
	v_mov_b32_e32 v134, v124
	v_mov_b32_e32 v135, v126
	v_pk_mul_f32 v[132:133], v[134:135], v[132:133]
	v_and_b32_e32 v135, 0xffff0000, v177
	v_and_b32_e32 v134, 0xffff0000, v176
	v_mov_b32_e32 v126, v125
	v_pk_mul_f32 v[124:125], v[126:127], v[134:135]
	v_and_b32_sdwa v129, v125, v204 dst_sel:DWORD dst_unused:UNUSED_PAD src0_sel:WORD_1 src1_sel:DWORD
	v_cvt_pk_bf16_f32 v234, v132, v124
	v_add_u32_e32 v130, 16, v160
	v_mov_b32_e32 v131, v161
	v_cvt_pk_bf16_f32 v233, v133, v125
	v_lshlrev_b64 v[130:131], 12, v[130:131]
	v_pk_mul_f32 v[122:123], v[122:123], v[128:129] op_sel_hi:[1,0]
	v_pk_mul_f32 v[120:121], v[120:121], v[128:129] op_sel_hi:[1,0]
	v_mov_b32_e32 v125, v233
	v_mov_b32_e32 v124, v234
	v_lshl_add_u64 v[130:131], v[168:169], 0, v[130:131]
	v_pk_mul_f32 v[120:121], v[136:137], v[120:121]
	v_pk_mul_f32 v[122:123], v[138:139], v[122:123]
	global_store_dwordx2 v[130:131], v[124:125], off offset:2048
	v_lshlrev_b32_e32 v125, 16, v175
	v_lshlrev_b32_e32 v124, 16, v174
	v_mov_b32_e32 v126, v120
	v_mov_b32_e32 v127, v122
	v_pk_mul_f32 v[124:125], v[126:127], v[124:125]
	v_and_b32_e32 v127, 0xffff0000, v175
	v_and_b32_e32 v126, 0xffff0000, v174
	v_mov_b32_e32 v122, v121
	v_pk_mul_f32 v[128:129], v[122:123], v[126:127]
	ds_read_b128 v[120:123], v206
	v_cvt_pk_bf16_f32 v237, v124, v128
	v_cvt_pk_bf16_f32 v235, v125, v129
	ds_read_b128 v[124:127], v206 offset:16
	s_waitcnt lgkmcnt(1)
; #define LAS __attribute__((address_space(3)))
; __device__ __forceinline__ float bflo(unsigned w) { return __uint_as_float(w << 16); }
; __device__ __forceinline__ float bfhi(unsigned w) { return __uint_as_float(w & 0xffff0000u); }
; __device__ __forceinline__ unsigned pk2(float lo, float hi) { return f2bf(lo) | (f2bf(hi) << 16); }
; template <bool FULL>
; __device__ __forceinline__ void gla_pass(const Params& P, LAS unsigned char* lds, f32x4 (&S)[8][2], int bh, int c0, int L, bool dry) {
;     ...
;         if (FULL) {
;             f32x4 gn[2];
; #pragma unroll
;             for (int vt = 0; vt < 2; ++vt) gn[vt] = *(const f32x4*)(P.gla_norm_g + 32 * w + 4 * g + 16 * vt);
; #pragma unroll
;             for (int tt = 0; tt < 4; ++tt) {
;                 const int t = 16 * tt + fr;
;                 const f32x4 r0 = *(const LAS f32x4*)(red + t * 8), r1 = *(const LAS f32x4*)(red + t * 8 + 4);
;                 const float rstd = 1.0f / sqrtf(((r0[0] + r0[1]) + (r0[2] + r0[3]) + (r1[0] + r1[1]) + (r1[2] + r1[3])) * (1.0f / 256.0f) + RMS_EPS);
; #pragma unroll
;                 for (int vt = 0; vt < 2; ++vt) {
;                     bf16_t* op = (bf16_t*)P.out + (row0 + t) * 2048 + 1024 + h * 256 + 32 * w + 16 * vt + 4 * g;
;                     const u32x2 z = zb[vt][tt]; const f32x4 ov = o[vt][tt] * rstd * gn[vt];
;                     u32x2 r; r.x = pk2(ov[0] * bflo(z.x), ov[1] * bfhi(z.x)); r.y = pk2(ov[2] * bflo(z.y), ov[3] * bfhi(z.y));
;                     if (!dry) *(u32x2*)op = r;
;                 }
;             }
	v_mov_b32_e32 v132, v121
	v_mov_b32_e32 v133, v122
	v_mov_b32_e32 v121, v123
	v_pk_add_f32 v[120:121], v[132:133], v[120:121]
	s_waitcnt lgkmcnt(0)
	v_mov_b32_e32 v122, v126
	v_mov_b32_e32 v123, v124
	v_mov_b32_e32 v124, v127
	v_pk_add_f32 v[122:123], v[122:123], v[124:125]
	v_add_f32_e32 v120, v120, v121
	v_add_f32_e32 v120, v120, v123
	v_add_f32_e32 v120, v122, v120
	v_fmamk_f32 v120, v120, 0x3b800000, v202
	v_mul_f32_e32 v121, 0x4f800000, v120
	v_cmp_gt_f32_e32 vcc, s26, v120
	s_nop 1
	v_cndmask_b32_e32 v120, v120, v121, vcc
	v_sqrt_f32_e32 v121, v120
	s_nop 0
	v_add_u32_e32 v124, -1, v121
	v_fma_f32 v125, -v124, v121, v120
	v_cmp_ge_f32_e64 s[8:9], 0, v125
	v_add_u32_e32 v125, 1, v121
	s_nop 0
	v_cndmask_b32_e64 v124, v121, v124, s[8:9]
	v_fma_f32 v121, -v125, v121, v120
	v_cmp_lt_f32_e64 s[8:9], 0, v121
	s_nop 1
	v_cndmask_b32_e64 v121, v124, v125, s[8:9]
	v_mul_f32_e32 v124, 0x37800000, v121
	v_cndmask_b32_e32 v121, v121, v124, vcc
	v_cmp_class_f32_e32 vcc, v120, v203
	s_nop 1
	v_cndmask_b32_e32 v124, v121, v120, vcc
	v_div_scale_f32 v125, s[8:9], v124, v124, 1.0
	v_rcp_f32_e32 v126, v125
	v_mov_b32_e32 v121, v235
	v_mov_b32_e32 v120, v237
	global_store_dwordx2 v[130:131], v[120:121], off offset:2080
	v_fma_f32 v120, -v125, v126, 1.0
	v_fmac_f32_e32 v126, v120, v126
	v_div_scale_f32 v120, vcc, 1.0, v124, 1.0
	v_mul_f32_e32 v121, v120, v126
	v_fma_f32 v122, -v125, v121, v120
	v_fmac_f32_e32 v121, v122, v126
	v_fma_f32 v120, -v125, v121, v120
	v_div_fmas_f32 v120, v120, v126, v121
	v_div_fixup_f32 v120, v120, v124, 1.0
	v_pk_mul_f32 v[110:111], v[110:111], v[120:121] op_sel_hi:[1,0]
	v_pk_mul_f32 v[108:109], v[108:109], v[120:121] op_sel_hi:[1,0]
	v_pk_mul_f32 v[110:111], v[142:143], v[110:111]
	v_pk_mul_f32 v[108:109], v[140:141], v[108:109]
	v_lshlrev_b32_e32 v125, 16, v151
	v_lshlrev_b32_e32 v124, 16, v150
	v_mov_b32_e32 v126, v108
	v_mov_b32_e32 v127, v110
	v_pk_mul_f32 v[124:125], v[126:127], v[124:125]
	v_and_b32_e32 v127, 0xffff0000, v151
	v_and_b32_e32 v126, 0xffff0000, v150
	v_mov_b32_e32 v110, v109
	v_pk_mul_f32 v[108:109], v[110:111], v[126:127]
	v_and_b32_sdwa v121, v109, v204 dst_sel:DWORD dst_unused:UNUSED_PAD src0_sel:WORD_1 src1_sel:DWORD
	v_cvt_pk_bf16_f32 v253, v124, v108
	v_add_u32_e32 v122, 32, v160
	v_mov_b32_e32 v123, v161
	v_cvt_pk_bf16_f32 v252, v125, v109
	v_lshlrev_b64 v[122:123], 12, v[122:123]
	v_pk_mul_f32 v[106:107], v[106:107], v[120:121] op_sel_hi:[1,0]
	v_pk_mul_f32 v[104:105], v[104:105], v[120:121] op_sel_hi:[1,0]
	v_mov_b32_e32 v109, v252
	v_mov_b32_e32 v108, v253
	v_lshl_add_u64 v[122:123], v[168:169], 0, v[122:123]
	v_pk_mul_f32 v[104:105], v[136:137], v[104:105]
	v_pk_mul_f32 v[106:107], v[138:139], v[106:107]
	global_store_dwordx2 v[122:123], v[108:109], off offset:2048
	v_lshlrev_b32_e32 v109, 16, v149
	v_lshlrev_b32_e32 v108, 16, v148
	v_mov_b32_e32 v110, v104
	v_mov_b32_e32 v111, v106
	v_pk_mul_f32 v[108:109], v[110:111], v[108:109]
	v_and_b32_e32 v111, 0xffff0000, v149
	v_and_b32_e32 v110, 0xffff0000, v148
	v_mov_b32_e32 v106, v105
	v_pk_mul_f32 v[120:121], v[106:107], v[110:111]
	ds_read_b128 v[104:107], v207
	v_cvt_pk_bf16_f32 v255, v108, v120
	v_cvt_pk_bf16_f32 v254, v109, v121
	ds_read_b128 v[108:111], v207 offset:16
	s_waitcnt lgkmcnt(1)
	v_mov_b32_e32 v124, v105
	v_mov_b32_e32 v125, v106
	v_mov_b32_e32 v105, v107
	v_pk_add_f32 v[104:105], v[124:125], v[104:105]
	s_waitcnt lgkmcnt(0)
	v_mov_b32_e32 v106, v110
	v_mov_b32_e32 v107, v108
	v_mov_b32_e32 v108, v111
	v_pk_add_f32 v[106:107], v[106:107], v[108:109]
	v_add_f32_e32 v104, v104, v105
	v_add_f32_e32 v104, v104, v107
	v_add_f32_e32 v104, v106, v104
	v_fmamk_f32 v104, v104, 0x3b800000, v202
	v_mul_f32_e32 v105, 0x4f800000, v104
	v_cmp_gt_f32_e32 vcc, s26, v104
	s_nop 1
	v_cndmask_b32_e32 v104, v104, v105, vcc
	v_sqrt_f32_e32 v105, v104
	v_add_u32_e32 v160, 48, v160
	v_add_u32_e32 v108, -1, v105
	v_fma_f32 v109, -v108, v105, v104
	v_cmp_ge_f32_e64 s[8:9], 0, v109
	v_add_u32_e32 v109, 1, v105
	s_nop 0
	v_cndmask_b32_e64 v108, v105, v108, s[8:9]
	v_fma_f32 v105, -v109, v105, v104
	v_cmp_lt_f32_e64 s[8:9], 0, v105
	s_nop 1
	v_cndmask_b32_e64 v105, v108, v109, s[8:9]
	v_mul_f32_e32 v108, 0x37800000, v105
	v_cndmask_b32_e32 v105, v105, v108, vcc
	v_cmp_class_f32_e32 vcc, v104, v203
	s_nop 1
	v_cndmask_b32_e32 v108, v105, v104, vcc
	v_div_scale_f32 v109, s[8:9], v108, v108, 1.0
	v_rcp_f32_e32 v110, v109
	v_mov_b32_e32 v105, v254
	v_mov_b32_e32 v104, v255
	global_store_dwordx2 v[122:123], v[104:105], off offset:2080
	v_fma_f32 v104, -v109, v110, 1.0
	v_fmac_f32_e32 v110, v104, v110
	v_div_scale_f32 v104, vcc, 1.0, v108, 1.0
	v_mul_f32_e32 v105, v104, v110
	v_fma_f32 v106, -v109, v105, v104
	v_fmac_f32_e32 v105, v106, v110
	v_fma_f32 v104, -v109, v105, v104
	v_div_fmas_f32 v104, v104, v110, v105
	v_div_fixup_f32 v104, v104, v108, 1.0
	v_pk_mul_f32 v[108:109], v[118:119], v[104:105] op_sel_hi:[1,0]
	v_pk_mul_f32 v[110:111], v[116:117], v[104:105] op_sel_hi:[1,0]
	v_pk_mul_f32 v[108:109], v[142:143], v[108:109]
	v_pk_mul_f32 v[110:111], v[140:141], v[110:111]
	v_lshlrev_b32_e32 v117, 16, v147
	v_lshlrev_b32_e32 v116, 16, v146
	v_mov_b32_e32 v118, v110
	v_mov_b32_e32 v119, v108
	v_pk_mul_f32 v[116:117], v[118:119], v[116:117]
	v_and_b32_e32 v119, 0xffff0000, v147
	v_and_b32_e32 v118, 0xffff0000, v146
	v_mov_b32_e32 v108, v111
	v_pk_mul_f32 v[108:109], v[108:109], v[118:119]
	v_cvt_pk_bf16_f32 v233, v116, v108
	v_and_b32_sdwa v105, v117, v204 dst_sel:DWORD dst_unused:UNUSED_PAD src0_sel:WORD_1 src1_sel:DWORD
	v_cvt_pk_bf16_f32 v232, v117, v109
	v_lshlrev_b64 v[106:107], 12, v[160:161]
	v_add3_u32 v105, v117, v105, s1
	v_mov_b32_e32 v109, v232
	v_mov_b32_e32 v108, v233
	v_lshl_add_u64 v[106:107], v[168:169], 0, v[106:107]
	global_store_dwordx2 v[106:107], v[108:109], off offset:2048
	v_pk_mul_f32 v[108:109], v[114:115], v[104:105] op_sel_hi:[1,0]
	v_pk_mul_f32 v[104:105], v[112:113], v[104:105] op_sel_hi:[1,0]
	v_pk_mul_f32 v[108:109], v[138:139], v[108:109]
	v_pk_mul_f32 v[104:105], v[136:137], v[104:105]
	v_lshlrev_b32_e32 v111, 16, v145
	v_lshlrev_b32_e32 v110, 16, v144
	v_mov_b32_e32 v112, v104
	v_mov_b32_e32 v113, v108
	v_pk_mul_f32 v[110:111], v[112:113], v[110:111]
	v_and_b32_e32 v113, 0xffff0000, v145
	v_and_b32_e32 v112, 0xffff0000, v144
	v_mov_b32_e32 v108, v105
	v_pk_mul_f32 v[104:105], v[108:109], v[112:113]
	v_cvt_pk_bf16_f32 v235, v110, v104
	v_cvt_pk_bf16_f32 v234, v111, v105
	v_mov_b32_e32 v105, v234
	v_mov_b32_e32 v104, v235
	global_store_dwordx2 v[106:107], v[104:105], off offset:2080
	s_barrier
	s_cbranch_scc1 .LBB0_714
